# stack of all validated edits on top of kdma2: v_mov_b64 zero-init, prepare loads merged+hoisted+counted wait (p8,p1), rope-row prefetch, M0-write hoist, no mid-block prio flips
# speedup vs baseline: 1.0180x; 1.0071x over previous
; #define PG8_STAGE(bufoff, gbase, voff) do { _Pragma("unroll") for (int _i = 0; _i < 2; ++_i) \
;         __builtin_amdgcn_global_load_lds((const unsigned*)((const char*)(gbase) + (voff)[_i]), (LAS unsigned*)(lds + (bufoff) + ldsw + _i * 8192), 16, 0, 0); } while (0)
; #define PG8_LDA(dst, b, h) do { _Pragma("unroll") for (int m = 0; m < 4; ++m) _Pragma("unroll") for (int k = 0; k < 2; ++k) dst[m][k] = *(const LAS bf16x8*)(lds + PG8_SA(b, h) + aoff + m * 2048 + k * 1024); } while (0)
; #define PG8_LDB(dst, b, h) do { _Pragma("unroll") for (int n = 0; n < 2; ++n) _Pragma("unroll") for (int k = 0; k < 2; ++k) dst[n][k] = *(const LAS bf16x8*)(lds + PG8_SB(b, h) + boff + n * 2048 + k * 1024); } while (0)
; template <class Epi>
; __device__ __forceinline__ void gemm_phase(LAS unsigned char* lds, const Gemm g, const StaticOrder& S, const Epi& E, const int tid) {
;     ...
;         for (int t = 0; t < ntt; t += 2) {
;             const bool last = (t == ntt - 2);
;             const bool s1 = Epi::TWO && (t >= nt), s2 = Epi::TWO && (t + 2 >= nt);
;             const char* a1 = (s1 ? cA2 + (size_t)(t - nt + 1) * kstep : cA + (size_t)(t + 1) * kstep);
;             const char* a2 = last ? nA : (s2 ? cA2 + (size_t)(t + 2 - nt) * kstep : cA + (size_t)(t + 2) * kstep);
;             const char* b2 = last ? nB : (s2 ? cB2 + (size_t)(t + 2 - nt) * kstep : cB + (size_t)(t + 2) * kstep);
;             const char* a3 = a2 + kstep; const char* b3 = b2 + kstep;
;             if constexpr (Epi::TWO) { if (t == nt) E.mid(acc, cur, wr, wc, fr, fq); }
;             if constexpr (SP2) {
;             PG8_LDB(B0, 0, 0); PG8_LDB(B1, 0, 1); PG8_SCHED; PG8_LDA(At, 0, 0); PG8_STAGE(PG8_SA(1, 1), a1 + hstep, voffA);
;             PG8_WAIT_V(8); PG8_WAIT_L(0); PG8_BAR; PG8_MMA(0, 0, At, B0); PG8_MMA(0, 1, At, B1); PG8_BAR; PG8_SCHED;
;             PG8_LDA(At, 0, 1); PG8_STAGE(PG8_SB(0, 0), b2, voffB); PG8_STAGE(PG8_SB(0, 1), b2 + bhs, voffB); PG8_STAGE(PG8_SA(0, 0), a2, voffA);
;             PG8_WAIT_V(8); PG8_WAIT_L(0); PG8_BAR; PG8_MMA(1, 0, At, B0); PG8_MMA(1, 1, At, B1); PG8_BAR; PG8_SCHED;
;     ...
; #pragma unroll
;         for (int a = 0; a < 2; ++a)
; #pragma unroll
;             for (int b = 0; b < 2; ++b)
; #pragma unroll
;                 for (int m = 0; m < 4; ++m)
; #pragma unroll
;                     for (int n = 0; n < 2; ++n) acc[a][b][m][n] = (f32x4){0.f, 0.f, 0.f, 0.f};
.LBB0_126:
	s_add_u32 s30, s28, 0xffe00080
	s_addc_u32 s31, s29, -1
	s_add_i32 s52, 0, 0x10000
	s_cmpk_eq_i32 s51, 0x7c
	s_cselect_b32 s35, s17, s31
	s_cselect_b32 s34, s27, s30
	s_cselect_b32 s31, s15, s50
	s_cselect_b32 s30, s33, s49
	s_add_i32 s54, 0, 0x14000
	v_add_u32_e32 v30, s52, v193
	v_add_u32_e32 v54, s54, v193
	ds_read_b128 v[18:21], v30
	ds_read_b128 v[22:25], v30 offset:1024
	ds_read_b128 v[26:29], v30 offset:2048
	ds_read_b128 v[30:33], v30 offset:3072
	ds_read_b128 v[42:45], v54
	ds_read_b128 v[46:49], v54 offset:1024
	ds_read_b128 v[50:53], v54 offset:2048
	ds_read_b128 v[54:57], v54 offset:3072
	v_lshl_add_u64 v[172:173], s[28:29], 0, v[180:181]
	s_add_i32 m0, s37, 0xc000
	ds_read_b128 v[182:185], v199
	global_load_lds_dwordx4 v[172:173], off
	ds_read_b128 v[186:189], v199 offset:1024
	ds_read_b128 v[212:215], v199 offset:2048
	s_add_i32 m0, s37, 0xe000
	v_lshl_add_u64 v[172:173], s[28:29], 0, v[178:179]
	global_load_lds_dwordx4 v[172:173], off
	ds_read_b128 v[216:219], v199 offset:3072
	ds_read_b128 v[220:223], v199 offset:4096
	ds_read_b128 v[224:227], v199 offset:5120
	ds_read_b128 v[228:231], v199 offset:6144
	ds_read_b128 v[232:235], v199 offset:7168
	s_waitcnt vmcnt(8)
	s_waitcnt lgkmcnt(0)
	s_barrier
	s_setprio 1
	v_mfma_f32_16x16x32_bf16 v[158:161], v[18:21], v[182:185], v[158:161]
	v_mfma_f32_16x16x32_bf16 v[154:157], v[26:29], v[182:185], v[154:157]
	v_mfma_f32_16x16x32_bf16 v[142:145], v[18:21], v[212:215], v[142:145]
	v_mfma_f32_16x16x32_bf16 v[138:141], v[26:29], v[212:215], v[138:141]
	v_mfma_f32_16x16x32_bf16 v[126:129], v[18:21], v[220:223], v[126:129]
	v_mfma_f32_16x16x32_bf16 v[122:125], v[26:29], v[220:223], v[122:125]
	v_mfma_f32_16x16x32_bf16 v[110:113], v[18:21], v[228:231], v[110:113]
	v_mfma_f32_16x16x32_bf16 v[106:109], v[26:29], v[228:231], v[106:109]
	v_mfma_f32_16x16x32_bf16 v[158:161], v[22:25], v[186:189], v[158:161]
	v_mfma_f32_16x16x32_bf16 v[154:157], v[30:33], v[186:189], v[154:157]
	v_mfma_f32_16x16x32_bf16 v[142:145], v[22:25], v[216:219], v[142:145]
	v_mfma_f32_16x16x32_bf16 v[138:141], v[30:33], v[216:219], v[138:141]
	v_mfma_f32_16x16x32_bf16 v[126:129], v[22:25], v[224:227], v[126:129]
	v_mfma_f32_16x16x32_bf16 v[122:125], v[30:33], v[224:227], v[122:125]
	v_mfma_f32_16x16x32_bf16 v[110:113], v[22:25], v[232:235], v[110:113]
	v_mfma_f32_16x16x32_bf16 v[106:109], v[30:33], v[232:235], v[106:109]
	v_mfma_f32_16x16x32_bf16 v[150:153], v[42:45], v[182:185], v[150:153]
	v_mfma_f32_16x16x32_bf16 v[146:149], v[50:53], v[182:185], v[146:149]
	v_mfma_f32_16x16x32_bf16 v[134:137], v[42:45], v[212:215], v[134:137]
	v_mfma_f32_16x16x32_bf16 v[130:133], v[50:53], v[212:215], v[130:133]
	v_mfma_f32_16x16x32_bf16 v[118:121], v[42:45], v[220:223], v[118:121]
	v_mfma_f32_16x16x32_bf16 v[114:117], v[50:53], v[220:223], v[114:117]
	v_mfma_f32_16x16x32_bf16 v[102:105], v[42:45], v[228:231], v[102:105]
	v_mfma_f32_16x16x32_bf16 v[98:101], v[50:53], v[228:231], v[98:101]
	v_mfma_f32_16x16x32_bf16 v[150:153], v[46:49], v[186:189], v[150:153]
	v_mfma_f32_16x16x32_bf16 v[146:149], v[54:57], v[186:189], v[146:149]
	v_mfma_f32_16x16x32_bf16 v[134:137], v[46:49], v[216:219], v[134:137]
	v_mfma_f32_16x16x32_bf16 v[130:133], v[54:57], v[216:219], v[130:133]
	v_mfma_f32_16x16x32_bf16 v[118:121], v[46:49], v[224:227], v[118:121]
	v_mfma_f32_16x16x32_bf16 v[114:117], v[54:57], v[224:227], v[114:117]
	v_mfma_f32_16x16x32_bf16 v[102:105], v[46:49], v[232:235], v[102:105]
	v_mfma_f32_16x16x32_bf16 v[98:101], v[54:57], v[232:235], v[98:101]
	s_setprio 0
	s_barrier
	s_add_i32 s52, s52, s36
	v_lshl_add_u64 v[172:173], s[30:31], 0, v[0:1]
	s_mov_b32 m0, s52
	ds_read_b128 v[182:185], v199 offset:16384
	global_load_lds_dwordx4 v[172:173], off
	ds_read_b128 v[186:189], v199 offset:17408
	ds_read_b128 v[212:215], v199 offset:18432
	s_add_i32 m0, s52, 0x2000
	s_add_u32 s52, s30, 0x20000
	v_lshl_add_u64 v[174:175], s[30:31], 0, v[166:167]
	s_addc_u32 s53, s31, 0
	s_add_i32 s54, s54, s36
	global_load_lds_dwordx4 v[174:175], off
	ds_read_b128 v[216:219], v199 offset:19456
	ds_read_b128 v[220:223], v199 offset:20480
	v_lshl_add_u64 v[176:177], s[52:53], 0, v[0:1]
	s_mov_b32 m0, s54
	v_lshl_add_u64 v[200:201], s[34:35], 0, v[164:165]
	global_load_lds_dwordx4 v[176:177], off
	ds_read_b128 v[224:227], v199 offset:21504
	ds_read_b128 v[228:231], v199 offset:22528
	s_add_i32 m0, s54, 0x2000
	v_lshl_add_u64 v[176:177], s[52:53], 0, v[166:167]
	global_load_lds_dwordx4 v[176:177], off
	ds_read_b128 v[232:235], v199 offset:23552
	s_mov_b32 m0, s37
	v_lshl_add_u64 v[176:177], s[34:35], 0, v[162:163]
	global_load_lds_dwordx4 v[176:177], off
	s_mov_b32 m0, s38
	s_nop 0
	global_load_lds_dwordx4 v[200:201], off
	s_waitcnt vmcnt(8)
	s_waitcnt lgkmcnt(0)
	s_barrier
; #define PG8_STAGE(bufoff, gbase, voff) do { _Pragma("unroll") for (int _i = 0; _i < 2; ++_i) \
;         __builtin_amdgcn_global_load_lds((const unsigned*)((const char*)(gbase) + (voff)[_i]), (LAS unsigned*)(lds + (bufoff) + ldsw + _i * 8192), 16, 0, 0); } while (0)
; #define PG8_LDA(dst, b, h) do { _Pragma("unroll") for (int m = 0; m < 4; ++m) _Pragma("unroll") for (int k = 0; k < 2; ++k) dst[m][k] = *(const LAS bf16x8*)(lds + PG8_SA(b, h) + aoff + m * 2048 + k * 1024); } while (0)
; #define PG8_LDB(dst, b, h) do { _Pragma("unroll") for (int n = 0; n < 2; ++n) _Pragma("unroll") for (int k = 0; k < 2; ++k) dst[n][k] = *(const LAS bf16x8*)(lds + PG8_SB(b, h) + boff + n * 2048 + k * 1024); } while (0)
; #define PG8_MMA(ai, bj, At, Bt) do { __builtin_amdgcn_s_setprio(1); _Pragma("unroll") for (int m = 0; m < 4; ++m) _Pragma("unroll") for (int n = 0; n < 2; ++n) _Pragma("unroll") for (int k = 0; k < 2; ++k) \
;         acc[ai][bj][m][n] = __builtin_amdgcn_mfma_f32_16x16x32_bf16(Bt[n][k], At[m][k], acc[ai][bj][m][n], 0, 0, 0); __builtin_amdgcn_s_setprio(0); } while (0)
; #define PG8_WAIT_V(n) asm volatile("s_waitcnt vmcnt(" #n ")" ::: "memory")
; #define PG8_WAIT_L(n) asm volatile("s_waitcnt lgkmcnt(" #n ")" ::: "memory")
; #define PG8_BAR __builtin_amdgcn_s_barrier()
; #define PG8_SCHED __builtin_amdgcn_sched_barrier(0)
; template <class Epi>
; __device__ __forceinline__ void gemm_phase(LAS unsigned char* lds, const Gemm g, const StaticOrder& S, const Epi& E, const int tid) {
;     ...
;             PG8_WAIT_V(8); PG8_WAIT_L(0); PG8_BAR; PG8_MMA(0, 0, At, B0); PG8_MMA(0, 1, At, B1); PG8_BAR; PG8_SCHED;
;             PG8_LDA(At, 0, 1); PG8_STAGE(PG8_SB(0, 0), b2, voffB); PG8_STAGE(PG8_SB(0, 1), b2 + bhs, voffB); PG8_STAGE(PG8_SA(0, 0), a2, voffA);
;             PG8_WAIT_V(8); PG8_WAIT_L(0); PG8_BAR; PG8_MMA(1, 0, At, B0); PG8_MMA(1, 1, At, B1); PG8_BAR; PG8_SCHED;
;             PG8_LDB(B0, 1, 0); PG8_LDB(B1, 1, 1); PG8_SCHED; PG8_LDA(At, 1, 0); PG8_STAGE(PG8_SA(0, 1), a2 + hstep, voffA);
;             PG8_WAIT_V(8); PG8_WAIT_L(0); PG8_BAR; PG8_MMA(0, 0, At, B0); PG8_MMA(0, 1, At, B1); PG8_BAR; PG8_SCHED;
	s_setprio 1
	v_mfma_f32_16x16x32_bf16 v[94:97], v[18:21], v[182:185], v[94:97]
	v_mfma_f32_16x16x32_bf16 v[90:93], v[26:29], v[182:185], v[90:93]
	v_mfma_f32_16x16x32_bf16 v[78:81], v[18:21], v[212:215], v[78:81]
	v_mfma_f32_16x16x32_bf16 v[74:77], v[26:29], v[212:215], v[74:77]
	v_mfma_f32_16x16x32_bf16 v[62:65], v[18:21], v[220:223], v[62:65]
	v_mfma_f32_16x16x32_bf16 v[58:61], v[26:29], v[220:223], v[58:61]
	v_mfma_f32_16x16x32_bf16 v[14:17], v[18:21], v[228:231], v[14:17]
	v_mfma_f32_16x16x32_bf16 v[10:13], v[26:29], v[228:231], v[10:13]
	v_mfma_f32_16x16x32_bf16 v[94:97], v[22:25], v[186:189], v[94:97]
	v_mfma_f32_16x16x32_bf16 v[90:93], v[30:33], v[186:189], v[90:93]
	v_mfma_f32_16x16x32_bf16 v[78:81], v[22:25], v[216:219], v[78:81]
	v_mfma_f32_16x16x32_bf16 v[74:77], v[30:33], v[216:219], v[74:77]
	v_mfma_f32_16x16x32_bf16 v[62:65], v[22:25], v[224:227], v[62:65]
	v_mfma_f32_16x16x32_bf16 v[58:61], v[30:33], v[224:227], v[58:61]
	v_mfma_f32_16x16x32_bf16 v[14:17], v[22:25], v[232:235], v[14:17]
	v_mfma_f32_16x16x32_bf16 v[10:13], v[30:33], v[232:235], v[10:13]
	v_mfma_f32_16x16x32_bf16 v[38:41], v[42:45], v[220:223], v[38:41]
	v_mfma_f32_16x16x32_bf16 v[34:37], v[50:53], v[220:223], v[34:37]
	v_mfma_f32_16x16x32_bf16 v[6:9], v[42:45], v[228:231], v[6:9]
	v_mfma_f32_16x16x32_bf16 v[2:5], v[50:53], v[228:231], v[2:5]
	v_mfma_f32_16x16x32_bf16 v[18:21], v[42:45], v[182:185], v[86:89]
	v_mfma_f32_16x16x32_bf16 v[22:25], v[50:53], v[182:185], v[82:85]
	v_mfma_f32_16x16x32_bf16 v[26:29], v[42:45], v[212:215], v[70:73]
	v_mfma_f32_16x16x32_bf16 v[30:33], v[50:53], v[212:215], v[66:69]
	v_mfma_f32_16x16x32_bf16 v[38:41], v[46:49], v[224:227], v[38:41]
	v_mfma_f32_16x16x32_bf16 v[34:37], v[54:57], v[224:227], v[34:37]
	v_mfma_f32_16x16x32_bf16 v[6:9], v[46:49], v[232:235], v[6:9]
	v_mfma_f32_16x16x32_bf16 v[2:5], v[54:57], v[232:235], v[2:5]
	v_mfma_f32_16x16x32_bf16 v[18:21], v[46:49], v[186:189], v[18:21]
	v_mfma_f32_16x16x32_bf16 v[22:25], v[54:57], v[186:189], v[22:25]
	v_mfma_f32_16x16x32_bf16 v[26:29], v[46:49], v[216:219], v[26:29]
	v_mfma_f32_16x16x32_bf16 v[30:33], v[54:57], v[216:219], v[30:33]
	s_setprio 0
	s_barrier
	s_add_i32 s52, 0, 0x18000
	s_add_i32 s53, 0, 0x1c000
	v_add_u32_e32 v54, s52, v193
	v_add_u32_e32 v66, s53, v193
	ds_read_b128 v[42:45], v54
	ds_read_b128 v[46:49], v54 offset:1024
	ds_read_b128 v[50:53], v54 offset:2048
	ds_read_b128 v[54:57], v54 offset:3072
	ds_read_b128 v[182:185], v66
	ds_read_b128 v[186:189], v66 offset:1024
	ds_read_b128 v[212:215], v66 offset:2048
	ds_read_b128 v[216:219], v66 offset:3072
	s_add_u32 s34, s34, 0x200000
	s_addc_u32 s35, s35, 0
	s_mov_b32 m0, s39
	v_lshl_add_u64 v[236:237], s[34:35], 0, v[162:163]
	ds_read_b128 v[66:69], v199 offset:32768
	global_load_lds_dwordx4 v[236:237], off
	ds_read_b128 v[70:73], v199 offset:33792
	ds_read_b128 v[82:85], v199 offset:34816
	s_mov_b32 m0, s44
	v_lshl_add_u64 v[236:237], s[34:35], 0, v[164:165]
	global_load_lds_dwordx4 v[236:237], off
	ds_read_b128 v[86:89], v199 offset:35840
	ds_read_b128 v[220:223], v199 offset:36864
	ds_read_b128 v[224:227], v199 offset:37888
	ds_read_b128 v[228:231], v199 offset:38912
	ds_read_b128 v[232:235], v199 offset:39936
	s_waitcnt vmcnt(8)
	s_waitcnt lgkmcnt(0)
	s_barrier
	s_setprio 1
	v_mfma_f32_16x16x32_bf16 v[158:161], v[42:45], v[66:69], v[158:161]
	v_mfma_f32_16x16x32_bf16 v[154:157], v[50:53], v[66:69], v[154:157]
	v_mfma_f32_16x16x32_bf16 v[142:145], v[42:45], v[82:85], v[142:145]
	v_mfma_f32_16x16x32_bf16 v[138:141], v[50:53], v[82:85], v[138:141]
	v_mfma_f32_16x16x32_bf16 v[126:129], v[42:45], v[220:223], v[126:129]
	v_mfma_f32_16x16x32_bf16 v[122:125], v[50:53], v[220:223], v[122:125]
	v_mfma_f32_16x16x32_bf16 v[110:113], v[42:45], v[228:231], v[110:113]
	v_mfma_f32_16x16x32_bf16 v[106:109], v[50:53], v[228:231], v[106:109]
	v_mfma_f32_16x16x32_bf16 v[158:161], v[46:49], v[70:73], v[158:161]
	v_mfma_f32_16x16x32_bf16 v[154:157], v[54:57], v[70:73], v[154:157]
	v_mfma_f32_16x16x32_bf16 v[142:145], v[46:49], v[86:89], v[142:145]
	v_mfma_f32_16x16x32_bf16 v[138:141], v[54:57], v[86:89], v[138:141]
	v_mfma_f32_16x16x32_bf16 v[126:129], v[46:49], v[224:227], v[126:129]
	v_mfma_f32_16x16x32_bf16 v[122:125], v[54:57], v[224:227], v[122:125]
	v_mfma_f32_16x16x32_bf16 v[110:113], v[46:49], v[232:235], v[110:113]
	v_mfma_f32_16x16x32_bf16 v[106:109], v[54:57], v[232:235], v[106:109]
	v_mfma_f32_16x16x32_bf16 v[150:153], v[182:185], v[66:69], v[150:153]
	v_mfma_f32_16x16x32_bf16 v[66:69], v[212:215], v[66:69], v[146:149]
	v_mfma_f32_16x16x32_bf16 v[146:149], v[216:219], v[70:73], v[66:69]
	v_mfma_f32_16x16x32_bf16 v[66:69], v[182:185], v[82:85], v[134:137]
	v_mfma_f32_16x16x32_bf16 v[134:137], v[186:189], v[86:89], v[66:69]
	v_mfma_f32_16x16x32_bf16 v[66:69], v[212:215], v[82:85], v[130:133]
	v_mfma_f32_16x16x32_bf16 v[130:133], v[216:219], v[86:89], v[66:69]
	v_mfma_f32_16x16x32_bf16 v[66:69], v[182:185], v[220:223], v[118:121]
	v_mfma_f32_16x16x32_bf16 v[118:121], v[186:189], v[224:227], v[66:69]
	v_mfma_f32_16x16x32_bf16 v[66:69], v[212:215], v[220:223], v[114:117]
	v_mfma_f32_16x16x32_bf16 v[114:117], v[216:219], v[224:227], v[66:69]
	v_mfma_f32_16x16x32_bf16 v[66:69], v[182:185], v[228:231], v[102:105]
	v_mfma_f32_16x16x32_bf16 v[102:105], v[186:189], v[232:235], v[66:69]
	v_mfma_f32_16x16x32_bf16 v[66:69], v[212:215], v[228:231], v[98:101]
	v_mfma_f32_16x16x32_bf16 v[150:153], v[186:189], v[70:73], v[150:153]
	v_mfma_f32_16x16x32_bf16 v[98:101], v[216:219], v[232:235], v[66:69]
	s_setprio 0
	s_barrier
; #define PG8_STAGE(bufoff, gbase, voff) do { _Pragma("unroll") for (int _i = 0; _i < 2; ++_i) \
;         __builtin_amdgcn_global_load_lds((const unsigned*)((const char*)(gbase) + (voff)[_i]), (LAS unsigned*)(lds + (bufoff) + ldsw + _i * 8192), 16, 0, 0); } while (0)
; #define PG8_LDA(dst, b, h) do { _Pragma("unroll") for (int m = 0; m < 4; ++m) _Pragma("unroll") for (int k = 0; k < 2; ++k) dst[m][k] = *(const LAS bf16x8*)(lds + PG8_SA(b, h) + aoff + m * 2048 + k * 1024); } while (0)
; #define PG8_MMA(ai, bj, At, Bt) do { __builtin_amdgcn_s_setprio(1); _Pragma("unroll") for (int m = 0; m < 4; ++m) _Pragma("unroll") for (int n = 0; n < 2; ++n) _Pragma("unroll") for (int k = 0; k < 2; ++k) \
;         acc[ai][bj][m][n] = __builtin_amdgcn_mfma_f32_16x16x32_bf16(Bt[n][k], At[m][k], acc[ai][bj][m][n], 0, 0, 0); __builtin_amdgcn_s_setprio(0); } while (0)
; #define PG8_WAIT_V(n) asm volatile("s_waitcnt vmcnt(" #n ")" ::: "memory")
; #define PG8_WAIT_L(n) asm volatile("s_waitcnt lgkmcnt(" #n ")" ::: "memory")
; #define PG8_BAR __builtin_amdgcn_s_barrier()
; #define PG8_SCHED __builtin_amdgcn_sched_barrier(0)
; template <class Epi>
; __device__ __forceinline__ void gemm_phase(LAS unsigned char* lds, const Gemm g, const StaticOrder& S, const Epi& E, const int tid) {
;     ...
;         for (int t = 0; t < ntt; t += 2) {
;             const bool last = (t == ntt - 2);
;             const bool s1 = Epi::TWO && (t >= nt), s2 = Epi::TWO && (t + 2 >= nt);
;     ...
;             PG8_LDA(At, 1, 1); PG8_STAGE(PG8_SB(1, 0), b3, voffB); PG8_STAGE(PG8_SB(1, 1), b3 + bhs, voffB); PG8_STAGE(PG8_SA(1, 0), a3, voffA);
;             PG8_WAIT_V(8); PG8_WAIT_L(0); PG8_BAR; PG8_MMA(1, 0, At, B0); PG8_MMA(1, 1, At, B1); PG8_BAR; PG8_SCHED;
	s_add_i32 s34, s52, s36
	v_lshl_add_u64 v[82:83], v[172:173], 0, s[70:71]
	s_mov_b32 m0, s34
	s_nop 0
	ds_read_b128 v[66:69], v199 offset:49152
	global_load_lds_dwordx4 v[82:83], off
	ds_read_b128 v[70:73], v199 offset:50176
	ds_read_b128 v[220:223], v199 offset:51200
	s_add_i32 m0, s34, 0x2000
	s_add_u32 s30, s30, 0x20080
	v_lshl_add_u64 v[82:83], v[174:175], 0, s[70:71]
	s_addc_u32 s31, s31, 0
	s_add_i32 s34, s53, s36
	global_load_lds_dwordx4 v[82:83], off
	ds_read_b128 v[224:227], v199 offset:52224
	ds_read_b128 v[228:231], v199 offset:53248
	s_mov_b32 m0, s34
	v_lshl_add_u64 v[82:83], s[30:31], 0, v[0:1]
	global_load_lds_dwordx4 v[82:83], off
	ds_read_b128 v[232:235], v199 offset:54272
	ds_read_b128 v[236:239], v199 offset:55296
	s_add_i32 m0, s34, 0x2000
	v_lshl_add_u64 v[82:83], s[30:31], 0, v[166:167]
	global_load_lds_dwordx4 v[82:83], off
	ds_read_b128 v[240:243], v199 offset:56320
	s_mov_b32 m0, s45
	v_lshl_add_u64 v[82:83], v[176:177], 0, s[70:71]
	global_load_lds_dwordx4 v[82:83], off
	s_mov_b32 m0, s46
	v_lshl_add_u64 v[82:83], v[200:201], 0, s[70:71]
	global_load_lds_dwordx4 v[82:83], off
	s_waitcnt vmcnt(8)
	s_waitcnt lgkmcnt(0)
	s_barrier
	s_setprio 1
	v_mfma_f32_16x16x32_bf16 v[82:85], v[42:45], v[66:69], v[94:97]
	v_mfma_f32_16x16x32_bf16 v[94:97], v[46:49], v[70:73], v[82:85]
	v_mfma_f32_16x16x32_bf16 v[82:85], v[50:53], v[66:69], v[90:93]
	v_mfma_f32_16x16x32_bf16 v[78:81], v[42:45], v[220:223], v[78:81]
	v_mfma_f32_16x16x32_bf16 v[74:77], v[50:53], v[220:223], v[74:77]
	v_mfma_f32_16x16x32_bf16 v[62:65], v[42:45], v[228:231], v[62:65]
	v_mfma_f32_16x16x32_bf16 v[58:61], v[50:53], v[228:231], v[58:61]
	v_mfma_f32_16x16x32_bf16 v[14:17], v[42:45], v[236:239], v[14:17]
	v_mfma_f32_16x16x32_bf16 v[10:13], v[50:53], v[236:239], v[10:13]
	v_mfma_f32_16x16x32_bf16 v[90:93], v[54:57], v[70:73], v[82:85]
	v_mfma_f32_16x16x32_bf16 v[78:81], v[46:49], v[224:227], v[78:81]
	v_mfma_f32_16x16x32_bf16 v[74:77], v[54:57], v[224:227], v[74:77]
	v_mfma_f32_16x16x32_bf16 v[62:65], v[46:49], v[232:235], v[62:65]
	v_mfma_f32_16x16x32_bf16 v[58:61], v[54:57], v[232:235], v[58:61]
	v_mfma_f32_16x16x32_bf16 v[14:17], v[46:49], v[240:243], v[14:17]
	v_mfma_f32_16x16x32_bf16 v[10:13], v[54:57], v[240:243], v[10:13]
	v_mfma_f32_16x16x32_bf16 v[18:21], v[182:185], v[66:69], v[18:21]
	v_mfma_f32_16x16x32_bf16 v[86:89], v[186:189], v[70:73], v[18:21]
	v_mfma_f32_16x16x32_bf16 v[18:21], v[212:215], v[66:69], v[22:25]
	v_mfma_f32_16x16x32_bf16 v[82:85], v[216:219], v[70:73], v[18:21]
	v_mfma_f32_16x16x32_bf16 v[18:21], v[182:185], v[220:223], v[26:29]
	v_mfma_f32_16x16x32_bf16 v[70:73], v[186:189], v[224:227], v[18:21]
	v_mfma_f32_16x16x32_bf16 v[18:21], v[212:215], v[220:223], v[30:33]
	v_mfma_f32_16x16x32_bf16 v[66:69], v[216:219], v[224:227], v[18:21]
	v_mfma_f32_16x16x32_bf16 v[18:21], v[182:185], v[228:231], v[38:41]
	v_mfma_f32_16x16x32_bf16 v[38:41], v[186:189], v[232:235], v[18:21]
	v_mfma_f32_16x16x32_bf16 v[18:21], v[212:215], v[228:231], v[34:37]
	v_mfma_f32_16x16x32_bf16 v[6:9], v[182:185], v[236:239], v[6:9]
	v_mfma_f32_16x16x32_bf16 v[2:5], v[212:215], v[236:239], v[2:5]
	v_mfma_f32_16x16x32_bf16 v[34:37], v[216:219], v[232:235], v[18:21]
	v_mfma_f32_16x16x32_bf16 v[6:9], v[186:189], v[240:243], v[6:9]
	v_mfma_f32_16x16x32_bf16 v[2:5], v[216:219], v[240:243], v[2:5]
	s_setprio 0
	s_barrier
	s_add_i32 s51, s51, 2
	s_add_u32 s49, s49, 0x100
	s_addc_u32 s50, s50, 0
	s_add_u32 s28, s28, 0x100
	s_addc_u32 s29, s29, 0
	s_cmpk_gt_u32 s51, 0x7d
	s_cbranch_scc0 .LBB0_126
	s_and_b64 vcc, exec, s[12:13]
	s_cbranch_vccz .LBB0_129
	s_barrier

; #define PG8_STAGE(bufoff, gbase, voff) do { _Pragma("unroll") for (int _i = 0; _i < 2; ++_i) \
;         __builtin_amdgcn_global_load_lds((const unsigned*)((const char*)(gbase) + (voff)[_i]), (LAS unsigned*)(lds + (bufoff) + ldsw + _i * 8192), 16, 0, 0); } while (0)
; #define PG8_LDA(dst, b, h) do { _Pragma("unroll") for (int m = 0; m < 4; ++m) _Pragma("unroll") for (int k = 0; k < 2; ++k) dst[m][k] = *(const LAS bf16x8*)(lds + PG8_SA(b, h) + aoff + m * 2048 + k * 1024); } while (0)
; #define PG8_LDB(dst, b, h) do { _Pragma("unroll") for (int n = 0; n < 2; ++n) _Pragma("unroll") for (int k = 0; k < 2; ++k) dst[n][k] = *(const LAS bf16x8*)(lds + PG8_SB(b, h) + boff + n * 2048 + k * 1024); } while (0)
; template <class Epi>
; __device__ __forceinline__ void gemm_phase(LAS unsigned char* lds, const Gemm g, const StaticOrder& S, const Epi& E, const int tid) {
;     ...
;         for (int t = 0; t < ntt; t += 2) {
;             const bool last = (t == ntt - 2);
;             const bool s1 = Epi::TWO && (t >= nt), s2 = Epi::TWO && (t + 2 >= nt);
;             const char* a1 = (s1 ? cA2 + (size_t)(t - nt + 1) * kstep : cA + (size_t)(t + 1) * kstep);
;             const char* a2 = last ? nA : (s2 ? cA2 + (size_t)(t + 2 - nt) * kstep : cA + (size_t)(t + 2) * kstep);
;             const char* b2 = last ? nB : (s2 ? cB2 + (size_t)(t + 2 - nt) * kstep : cB + (size_t)(t + 2) * kstep);
;             const char* a3 = a2 + kstep; const char* b3 = b2 + kstep;
;             if constexpr (Epi::TWO) { if (t == nt) E.mid(acc, cur, wr, wc, fr, fq); }
;             if constexpr (SP2) {
;             PG8_LDB(B0, 0, 0); PG8_LDB(B1, 0, 1); PG8_SCHED; PG8_LDA(At, 0, 0); PG8_STAGE(PG8_SA(1, 1), a1 + hstep, voffA);
;             PG8_WAIT_V(8); PG8_WAIT_L(0); PG8_BAR; PG8_MMA(0, 0, At, B0); PG8_MMA(0, 1, At, B1); PG8_BAR; PG8_SCHED;
;             PG8_LDA(At, 0, 1); PG8_STAGE(PG8_SB(0, 0), b2, voffB); PG8_STAGE(PG8_SB(0, 1), b2 + bhs, voffB); PG8_STAGE(PG8_SA(0, 0), a2, voffA);
;             PG8_WAIT_V(8); PG8_WAIT_L(0); PG8_BAR; PG8_MMA(1, 0, At, B0); PG8_MMA(1, 1, At, B1); PG8_BAR; PG8_SCHED;
;     ...
; #pragma unroll
;         for (int a = 0; a < 2; ++a)
; #pragma unroll
;             for (int b = 0; b < 2; ++b)
; #pragma unroll
;                 for (int m = 0; m < 4; ++m)
; #pragma unroll
;                     for (int n = 0; n < 2; ++n) acc[a][b][m][n] = (f32x4){0.f, 0.f, 0.f, 0.f};
.LBB0_173:
	s_add_u32 s28, s26, 0xfff80080
	s_addc_u32 s29, s27, -1
	s_add_i32 s47, 0, 0x10000
	s_cmp_eq_u32 s46, 28
	s_cselect_b32 s31, s17, s29
	s_cselect_b32 s30, s42, s28
	v_add_u32_e32 v142, s47, v149
	s_cselect_b32 s29, s15, s45
	s_cselect_b32 s28, s43, s44
	s_add_i32 s50, 0, 0x14000
	ds_read_b128 v[156:159], v142
	ds_read_b128 v[160:163], v142 offset:1024
	ds_read_b128 v[164:167], v142 offset:2048
	ds_read_b128 v[178:181], v142 offset:3072
	v_add_u32_e32 v142, s50, v149
	ds_read_b128 v[182:185], v142
	ds_read_b128 v[186:189], v142 offset:1024
	ds_read_b128 v[190:193], v142 offset:2048
	ds_read_b128 v[194:197], v142 offset:3072
	v_lshl_add_u64 v[142:143], s[26:27], 0, v[140:141]
	s_add_i32 m0, s2, 0xc000
	ds_read_b128 v[198:201], v154
	global_load_lds_dwordx4 v[142:143], off
	ds_read_b128 v[212:215], v154 offset:1024
	ds_read_b128 v[216:219], v154 offset:2048
	s_add_i32 m0, s2, 0xe000
	v_lshl_add_u64 v[142:143], s[26:27], 0, v[138:139]
	global_load_lds_dwordx4 v[142:143], off
	ds_read_b128 v[220:223], v154 offset:3072
	ds_read_b128 v[224:227], v154 offset:4096
	ds_read_b128 v[228:231], v154 offset:5120
	ds_read_b128 v[232:235], v154 offset:6144
	ds_read_b128 v[236:239], v154 offset:7168
	s_waitcnt vmcnt(8)
	s_waitcnt lgkmcnt(0)
	s_barrier
	s_setprio 1
	v_mfma_f32_16x16x32_bf16 v[126:129], v[156:159], v[198:201], v[126:129]
	v_mfma_f32_16x16x32_bf16 v[122:125], v[164:167], v[198:201], v[122:125]
	v_mfma_f32_16x16x32_bf16 v[110:113], v[156:159], v[216:219], v[110:113]
	v_mfma_f32_16x16x32_bf16 v[106:109], v[164:167], v[216:219], v[106:109]
	v_mfma_f32_16x16x32_bf16 v[94:97], v[156:159], v[224:227], v[94:97]
	v_mfma_f32_16x16x32_bf16 v[90:93], v[164:167], v[224:227], v[90:93]
	v_mfma_f32_16x16x32_bf16 v[78:81], v[156:159], v[232:235], v[78:81]
	v_mfma_f32_16x16x32_bf16 v[74:77], v[164:167], v[232:235], v[74:77]
	v_mfma_f32_16x16x32_bf16 v[126:129], v[160:163], v[212:215], v[126:129]
	v_mfma_f32_16x16x32_bf16 v[122:125], v[178:181], v[212:215], v[122:125]
	v_mfma_f32_16x16x32_bf16 v[110:113], v[160:163], v[220:223], v[110:113]
	v_mfma_f32_16x16x32_bf16 v[106:109], v[178:181], v[220:223], v[106:109]
	v_mfma_f32_16x16x32_bf16 v[94:97], v[160:163], v[228:231], v[94:97]
	v_mfma_f32_16x16x32_bf16 v[90:93], v[178:181], v[228:231], v[90:93]
	v_mfma_f32_16x16x32_bf16 v[78:81], v[160:163], v[236:239], v[78:81]
	v_mfma_f32_16x16x32_bf16 v[74:77], v[178:181], v[236:239], v[74:77]
	v_mfma_f32_16x16x32_bf16 v[118:121], v[182:185], v[198:201], v[118:121]
	v_mfma_f32_16x16x32_bf16 v[114:117], v[190:193], v[198:201], v[114:117]
	v_mfma_f32_16x16x32_bf16 v[102:105], v[182:185], v[216:219], v[102:105]
	v_mfma_f32_16x16x32_bf16 v[98:101], v[190:193], v[216:219], v[98:101]
	v_mfma_f32_16x16x32_bf16 v[86:89], v[182:185], v[224:227], v[86:89]
	v_mfma_f32_16x16x32_bf16 v[82:85], v[190:193], v[224:227], v[82:85]
	v_mfma_f32_16x16x32_bf16 v[70:73], v[182:185], v[232:235], v[70:73]
	v_mfma_f32_16x16x32_bf16 v[66:69], v[190:193], v[232:235], v[66:69]
	v_mfma_f32_16x16x32_bf16 v[118:121], v[186:189], v[212:215], v[118:121]
	v_mfma_f32_16x16x32_bf16 v[114:117], v[194:197], v[212:215], v[114:117]
	v_mfma_f32_16x16x32_bf16 v[102:105], v[186:189], v[220:223], v[102:105]
	v_mfma_f32_16x16x32_bf16 v[98:101], v[194:197], v[220:223], v[98:101]
	v_mfma_f32_16x16x32_bf16 v[86:89], v[186:189], v[228:231], v[86:89]
	v_mfma_f32_16x16x32_bf16 v[82:85], v[194:197], v[228:231], v[82:85]
	v_mfma_f32_16x16x32_bf16 v[70:73], v[186:189], v[236:239], v[70:73]
	v_mfma_f32_16x16x32_bf16 v[66:69], v[194:197], v[236:239], v[66:69]
	s_setprio 0
	s_barrier
	s_add_i32 s47, s47, s34
	v_lshl_add_u64 v[142:143], s[28:29], 0, v[0:1]
	s_mov_b32 m0, s47
	ds_read_b128 v[198:201], v154 offset:16384
	global_load_lds_dwordx4 v[142:143], off
	ds_read_b128 v[212:215], v154 offset:17408
	ds_read_b128 v[216:219], v154 offset:18432
	s_add_i32 m0, s47, 0x2000
	s_add_u32 s48, s28, 0x8000
	v_lshl_add_u64 v[168:169], s[28:29], 0, v[134:135]
	s_addc_u32 s49, s29, 0
	s_add_i32 s47, s50, s34
	global_load_lds_dwordx4 v[168:169], off
	ds_read_b128 v[220:223], v154 offset:19456
	ds_read_b128 v[224:227], v154 offset:20480
	v_lshl_add_u64 v[172:173], s[48:49], 0, v[0:1]
	s_mov_b32 m0, s47
	v_lshl_add_u64 v[174:175], s[30:31], 0, v[132:133]
	global_load_lds_dwordx4 v[172:173], off
	ds_read_b128 v[228:231], v154 offset:21504
	ds_read_b128 v[232:235], v154 offset:22528
	s_add_i32 m0, s47, 0x2000
	v_lshl_add_u64 v[172:173], s[48:49], 0, v[134:135]
	global_load_lds_dwordx4 v[172:173], off
	ds_read_b128 v[236:239], v154 offset:23552
	s_mov_b32 m0, s2
	v_lshl_add_u64 v[172:173], s[30:31], 0, v[130:131]
	global_load_lds_dwordx4 v[172:173], off
	s_mov_b32 m0, s25
	s_nop 0
	global_load_lds_dwordx4 v[174:175], off
	s_waitcnt vmcnt(8)
	s_waitcnt lgkmcnt(0)
	s_barrier
; #define PG8_STAGE(bufoff, gbase, voff) do { _Pragma("unroll") for (int _i = 0; _i < 2; ++_i) \
;         __builtin_amdgcn_global_load_lds((const unsigned*)((const char*)(gbase) + (voff)[_i]), (LAS unsigned*)(lds + (bufoff) + ldsw + _i * 8192), 16, 0, 0); } while (0)
; #define PG8_LDA(dst, b, h) do { _Pragma("unroll") for (int m = 0; m < 4; ++m) _Pragma("unroll") for (int k = 0; k < 2; ++k) dst[m][k] = *(const LAS bf16x8*)(lds + PG8_SA(b, h) + aoff + m * 2048 + k * 1024); } while (0)
; #define PG8_LDB(dst, b, h) do { _Pragma("unroll") for (int n = 0; n < 2; ++n) _Pragma("unroll") for (int k = 0; k < 2; ++k) dst[n][k] = *(const LAS bf16x8*)(lds + PG8_SB(b, h) + boff + n * 2048 + k * 1024); } while (0)
; #define PG8_MMA(ai, bj, At, Bt) do { __builtin_amdgcn_s_setprio(1); _Pragma("unroll") for (int m = 0; m < 4; ++m) _Pragma("unroll") for (int n = 0; n < 2; ++n) _Pragma("unroll") for (int k = 0; k < 2; ++k) \
;         acc[ai][bj][m][n] = __builtin_amdgcn_mfma_f32_16x16x32_bf16(Bt[n][k], At[m][k], acc[ai][bj][m][n], 0, 0, 0); __builtin_amdgcn_s_setprio(0); } while (0)
; #define PG8_WAIT_V(n) asm volatile("s_waitcnt vmcnt(" #n ")" ::: "memory")
; #define PG8_WAIT_L(n) asm volatile("s_waitcnt lgkmcnt(" #n ")" ::: "memory")
; #define PG8_BAR __builtin_amdgcn_s_barrier()
; #define PG8_SCHED __builtin_amdgcn_sched_barrier(0)
; template <class Epi>
; __device__ __forceinline__ void gemm_phase(LAS unsigned char* lds, const Gemm g, const StaticOrder& S, const Epi& E, const int tid) {
;     ...
;             PG8_WAIT_V(8); PG8_WAIT_L(0); PG8_BAR; PG8_MMA(0, 0, At, B0); PG8_MMA(0, 1, At, B1); PG8_BAR; PG8_SCHED;
;             PG8_LDA(At, 0, 1); PG8_STAGE(PG8_SB(0, 0), b2, voffB); PG8_STAGE(PG8_SB(0, 1), b2 + bhs, voffB); PG8_STAGE(PG8_SA(0, 0), a2, voffA);
;             PG8_WAIT_V(8); PG8_WAIT_L(0); PG8_BAR; PG8_MMA(1, 0, At, B0); PG8_MMA(1, 1, At, B1); PG8_BAR; PG8_SCHED;
;             PG8_LDB(B0, 1, 0); PG8_LDB(B1, 1, 1); PG8_SCHED; PG8_LDA(At, 1, 0); PG8_STAGE(PG8_SA(0, 1), a2 + hstep, voffA);
;             PG8_WAIT_V(8); PG8_WAIT_L(0); PG8_BAR; PG8_MMA(0, 0, At, B0); PG8_MMA(0, 1, At, B1); PG8_BAR; PG8_SCHED;
	s_setprio 1
	v_mfma_f32_16x16x32_bf16 v[62:65], v[156:159], v[198:201], v[62:65]
	v_mfma_f32_16x16x32_bf16 v[58:61], v[164:167], v[198:201], v[58:61]
	v_mfma_f32_16x16x32_bf16 v[46:49], v[156:159], v[216:219], v[46:49]
	v_mfma_f32_16x16x32_bf16 v[42:45], v[164:167], v[216:219], v[42:45]
	v_mfma_f32_16x16x32_bf16 v[30:33], v[156:159], v[224:227], v[30:33]
	v_mfma_f32_16x16x32_bf16 v[26:29], v[164:167], v[224:227], v[26:29]
	v_mfma_f32_16x16x32_bf16 v[14:17], v[156:159], v[232:235], v[14:17]
	v_mfma_f32_16x16x32_bf16 v[10:13], v[164:167], v[232:235], v[10:13]
	v_mfma_f32_16x16x32_bf16 v[62:65], v[160:163], v[212:215], v[62:65]
	v_mfma_f32_16x16x32_bf16 v[58:61], v[178:181], v[212:215], v[58:61]
	v_mfma_f32_16x16x32_bf16 v[46:49], v[160:163], v[220:223], v[46:49]
	v_mfma_f32_16x16x32_bf16 v[42:45], v[178:181], v[220:223], v[42:45]
	v_mfma_f32_16x16x32_bf16 v[30:33], v[160:163], v[228:231], v[30:33]
	v_mfma_f32_16x16x32_bf16 v[26:29], v[178:181], v[228:231], v[26:29]
	v_mfma_f32_16x16x32_bf16 v[14:17], v[160:163], v[236:239], v[14:17]
	v_mfma_f32_16x16x32_bf16 v[10:13], v[178:181], v[236:239], v[10:13]
	v_mfma_f32_16x16x32_bf16 v[54:57], v[182:185], v[198:201], v[54:57]
	v_mfma_f32_16x16x32_bf16 v[50:53], v[190:193], v[198:201], v[50:53]
	v_mfma_f32_16x16x32_bf16 v[38:41], v[182:185], v[216:219], v[38:41]
	v_mfma_f32_16x16x32_bf16 v[34:37], v[190:193], v[216:219], v[34:37]
	v_mfma_f32_16x16x32_bf16 v[22:25], v[182:185], v[224:227], v[22:25]
	v_mfma_f32_16x16x32_bf16 v[18:21], v[190:193], v[224:227], v[18:21]
	v_mfma_f32_16x16x32_bf16 v[6:9], v[182:185], v[232:235], v[6:9]
	v_mfma_f32_16x16x32_bf16 v[2:5], v[190:193], v[232:235], v[2:5]
	v_mfma_f32_16x16x32_bf16 v[54:57], v[186:189], v[212:215], v[54:57]
	v_mfma_f32_16x16x32_bf16 v[50:53], v[194:197], v[212:215], v[50:53]
	v_mfma_f32_16x16x32_bf16 v[38:41], v[186:189], v[220:223], v[38:41]
	v_mfma_f32_16x16x32_bf16 v[34:37], v[194:197], v[220:223], v[34:37]
	v_mfma_f32_16x16x32_bf16 v[22:25], v[186:189], v[228:231], v[22:25]
	v_mfma_f32_16x16x32_bf16 v[18:21], v[194:197], v[228:231], v[18:21]
	v_mfma_f32_16x16x32_bf16 v[6:9], v[186:189], v[236:239], v[6:9]
	v_mfma_f32_16x16x32_bf16 v[2:5], v[194:197], v[236:239], v[2:5]
	s_setprio 0
	s_barrier
	s_add_i32 s47, 0, 0x18000
	v_add_u32_e32 v155, s47, v149
	s_add_i32 s48, 0, 0x1c000
	ds_read_b128 v[156:159], v155
	ds_read_b128 v[160:163], v155 offset:1024
	ds_read_b128 v[164:167], v155 offset:2048
	ds_read_b128 v[178:181], v155 offset:3072
	v_add_u32_e32 v155, s48, v149
	ds_read_b128 v[182:185], v155
	ds_read_b128 v[186:189], v155 offset:1024
	ds_read_b128 v[190:193], v155 offset:2048
	ds_read_b128 v[194:197], v155 offset:3072
	s_add_u32 s30, s30, 0x80000
	s_addc_u32 s31, s31, 0
	s_mov_b32 m0, s35
	v_lshl_add_u64 v[176:177], s[30:31], 0, v[130:131]
	ds_read_b128 v[198:201], v154 offset:32768
	global_load_lds_dwordx4 v[176:177], off
	ds_read_b128 v[212:215], v154 offset:33792
	ds_read_b128 v[216:219], v154 offset:34816
	s_mov_b32 m0, s36
	v_lshl_add_u64 v[176:177], s[30:31], 0, v[132:133]
	global_load_lds_dwordx4 v[176:177], off
	ds_read_b128 v[220:223], v154 offset:35840
	ds_read_b128 v[224:227], v154 offset:36864
	ds_read_b128 v[228:231], v154 offset:37888
	ds_read_b128 v[232:235], v154 offset:38912
	ds_read_b128 v[236:239], v154 offset:39936
	s_waitcnt vmcnt(8)
	s_waitcnt lgkmcnt(0)
	s_barrier
	s_setprio 1
	v_mfma_f32_16x16x32_bf16 v[126:129], v[156:159], v[198:201], v[126:129]
	v_mfma_f32_16x16x32_bf16 v[122:125], v[164:167], v[198:201], v[122:125]
	v_mfma_f32_16x16x32_bf16 v[110:113], v[156:159], v[216:219], v[110:113]
	v_mfma_f32_16x16x32_bf16 v[106:109], v[164:167], v[216:219], v[106:109]
	v_mfma_f32_16x16x32_bf16 v[94:97], v[156:159], v[224:227], v[94:97]
	v_mfma_f32_16x16x32_bf16 v[90:93], v[164:167], v[224:227], v[90:93]
	v_mfma_f32_16x16x32_bf16 v[78:81], v[156:159], v[232:235], v[78:81]
	v_mfma_f32_16x16x32_bf16 v[74:77], v[164:167], v[232:235], v[74:77]
	v_mfma_f32_16x16x32_bf16 v[126:129], v[160:163], v[212:215], v[126:129]
	v_mfma_f32_16x16x32_bf16 v[122:125], v[178:181], v[212:215], v[122:125]
	v_mfma_f32_16x16x32_bf16 v[110:113], v[160:163], v[220:223], v[110:113]
	v_mfma_f32_16x16x32_bf16 v[106:109], v[178:181], v[220:223], v[106:109]
	v_mfma_f32_16x16x32_bf16 v[94:97], v[160:163], v[228:231], v[94:97]
	v_mfma_f32_16x16x32_bf16 v[90:93], v[178:181], v[228:231], v[90:93]
	v_mfma_f32_16x16x32_bf16 v[78:81], v[160:163], v[236:239], v[78:81]
	v_mfma_f32_16x16x32_bf16 v[74:77], v[178:181], v[236:239], v[74:77]
	v_mfma_f32_16x16x32_bf16 v[118:121], v[182:185], v[198:201], v[118:121]
	v_mfma_f32_16x16x32_bf16 v[114:117], v[190:193], v[198:201], v[114:117]
	v_mfma_f32_16x16x32_bf16 v[102:105], v[182:185], v[216:219], v[102:105]
	v_mfma_f32_16x16x32_bf16 v[98:101], v[190:193], v[216:219], v[98:101]
	v_mfma_f32_16x16x32_bf16 v[86:89], v[182:185], v[224:227], v[86:89]
	v_mfma_f32_16x16x32_bf16 v[82:85], v[190:193], v[224:227], v[82:85]
	v_mfma_f32_16x16x32_bf16 v[70:73], v[182:185], v[232:235], v[70:73]
	v_mfma_f32_16x16x32_bf16 v[66:69], v[190:193], v[232:235], v[66:69]
	v_mfma_f32_16x16x32_bf16 v[118:121], v[186:189], v[212:215], v[118:121]
	v_mfma_f32_16x16x32_bf16 v[114:117], v[194:197], v[212:215], v[114:117]
	v_mfma_f32_16x16x32_bf16 v[102:105], v[186:189], v[220:223], v[102:105]
	v_mfma_f32_16x16x32_bf16 v[98:101], v[194:197], v[220:223], v[98:101]
	v_mfma_f32_16x16x32_bf16 v[86:89], v[186:189], v[228:231], v[86:89]
	v_mfma_f32_16x16x32_bf16 v[82:85], v[194:197], v[228:231], v[82:85]
	v_mfma_f32_16x16x32_bf16 v[70:73], v[186:189], v[236:239], v[70:73]
	v_mfma_f32_16x16x32_bf16 v[66:69], v[194:197], v[236:239], v[66:69]
	s_setprio 0
	s_barrier
; #define PG8_STAGE(bufoff, gbase, voff) do { _Pragma("unroll") for (int _i = 0; _i < 2; ++_i) \
;         __builtin_amdgcn_global_load_lds((const unsigned*)((const char*)(gbase) + (voff)[_i]), (LAS unsigned*)(lds + (bufoff) + ldsw + _i * 8192), 16, 0, 0); } while (0)
; #define PG8_LDA(dst, b, h) do { _Pragma("unroll") for (int m = 0; m < 4; ++m) _Pragma("unroll") for (int k = 0; k < 2; ++k) dst[m][k] = *(const LAS bf16x8*)(lds + PG8_SA(b, h) + aoff + m * 2048 + k * 1024); } while (0)
; #define PG8_MMA(ai, bj, At, Bt) do { __builtin_amdgcn_s_setprio(1); _Pragma("unroll") for (int m = 0; m < 4; ++m) _Pragma("unroll") for (int n = 0; n < 2; ++n) _Pragma("unroll") for (int k = 0; k < 2; ++k) \
;         acc[ai][bj][m][n] = __builtin_amdgcn_mfma_f32_16x16x32_bf16(Bt[n][k], At[m][k], acc[ai][bj][m][n], 0, 0, 0); __builtin_amdgcn_s_setprio(0); } while (0)
; #define PG8_WAIT_V(n) asm volatile("s_waitcnt vmcnt(" #n ")" ::: "memory")
; #define PG8_WAIT_L(n) asm volatile("s_waitcnt lgkmcnt(" #n ")" ::: "memory")
; #define PG8_BAR __builtin_amdgcn_s_barrier()
; #define PG8_SCHED __builtin_amdgcn_sched_barrier(0)
; template <class Epi>
; __device__ __forceinline__ void gemm_phase(LAS unsigned char* lds, const Gemm g, const StaticOrder& S, const Epi& E, const int tid) {
;     ...
;         for (int t = 0; t < ntt; t += 2) {
;             const bool last = (t == ntt - 2);
;             const bool s1 = Epi::TWO && (t >= nt), s2 = Epi::TWO && (t + 2 >= nt);
;     ...
;             PG8_LDA(At, 1, 1); PG8_STAGE(PG8_SB(1, 0), b3, voffB); PG8_STAGE(PG8_SB(1, 1), b3 + bhs, voffB); PG8_STAGE(PG8_SA(1, 0), a3, voffA);
;             PG8_WAIT_V(8); PG8_WAIT_L(0); PG8_BAR; PG8_MMA(1, 0, At, B0); PG8_MMA(1, 1, At, B1); PG8_BAR; PG8_SCHED;
	s_add_i32 s30, s47, s34
	v_lshl_add_u64 v[142:143], v[142:143], 0, s[70:71]
	s_mov_b32 m0, s30
	ds_read_b128 v[198:201], v154 offset:49152
	global_load_lds_dwordx4 v[142:143], off
	ds_read_b128 v[212:215], v154 offset:50176
	ds_read_b128 v[216:219], v154 offset:51200
	s_add_i32 m0, s30, 0x2000
	s_add_u32 s28, s28, 0x8080
	v_lshl_add_u64 v[142:143], v[168:169], 0, s[70:71]
	s_addc_u32 s29, s29, 0
	s_add_i32 s30, s48, s34
	global_load_lds_dwordx4 v[142:143], off
	ds_read_b128 v[220:223], v154 offset:52224
	ds_read_b128 v[224:227], v154 offset:53248
	s_mov_b32 m0, s30
	v_lshl_add_u64 v[142:143], s[28:29], 0, v[0:1]
	global_load_lds_dwordx4 v[142:143], off
	ds_read_b128 v[228:231], v154 offset:54272
	ds_read_b128 v[232:235], v154 offset:55296
	s_add_i32 m0, s30, 0x2000
	v_lshl_add_u64 v[142:143], s[28:29], 0, v[134:135]
	global_load_lds_dwordx4 v[142:143], off
	ds_read_b128 v[236:239], v154 offset:56320
	s_mov_b32 m0, s37
	v_lshl_add_u64 v[142:143], v[172:173], 0, s[70:71]
	global_load_lds_dwordx4 v[142:143], off
	s_mov_b32 m0, s38
	v_lshl_add_u64 v[142:143], v[174:175], 0, s[70:71]
	global_load_lds_dwordx4 v[142:143], off
	s_waitcnt vmcnt(8)
	s_waitcnt lgkmcnt(0)
	s_barrier
	s_setprio 1
	v_mfma_f32_16x16x32_bf16 v[62:65], v[156:159], v[198:201], v[62:65]
	v_mfma_f32_16x16x32_bf16 v[58:61], v[164:167], v[198:201], v[58:61]
	v_mfma_f32_16x16x32_bf16 v[46:49], v[156:159], v[216:219], v[46:49]
	v_mfma_f32_16x16x32_bf16 v[42:45], v[164:167], v[216:219], v[42:45]
	v_mfma_f32_16x16x32_bf16 v[30:33], v[156:159], v[224:227], v[30:33]
	v_mfma_f32_16x16x32_bf16 v[26:29], v[164:167], v[224:227], v[26:29]
	v_mfma_f32_16x16x32_bf16 v[14:17], v[156:159], v[232:235], v[14:17]
	v_mfma_f32_16x16x32_bf16 v[10:13], v[164:167], v[232:235], v[10:13]
	v_mfma_f32_16x16x32_bf16 v[62:65], v[160:163], v[212:215], v[62:65]
	v_mfma_f32_16x16x32_bf16 v[58:61], v[178:181], v[212:215], v[58:61]
	v_mfma_f32_16x16x32_bf16 v[46:49], v[160:163], v[220:223], v[46:49]
	v_mfma_f32_16x16x32_bf16 v[42:45], v[178:181], v[220:223], v[42:45]
	v_mfma_f32_16x16x32_bf16 v[30:33], v[160:163], v[228:231], v[30:33]
	v_mfma_f32_16x16x32_bf16 v[26:29], v[178:181], v[228:231], v[26:29]
	v_mfma_f32_16x16x32_bf16 v[14:17], v[160:163], v[236:239], v[14:17]
	v_mfma_f32_16x16x32_bf16 v[10:13], v[178:181], v[236:239], v[10:13]
	v_mfma_f32_16x16x32_bf16 v[54:57], v[182:185], v[198:201], v[54:57]
	v_mfma_f32_16x16x32_bf16 v[50:53], v[190:193], v[198:201], v[50:53]
	v_mfma_f32_16x16x32_bf16 v[38:41], v[182:185], v[216:219], v[38:41]
	v_mfma_f32_16x16x32_bf16 v[34:37], v[190:193], v[216:219], v[34:37]
	v_mfma_f32_16x16x32_bf16 v[22:25], v[182:185], v[224:227], v[22:25]
	v_mfma_f32_16x16x32_bf16 v[18:21], v[190:193], v[224:227], v[18:21]
	v_mfma_f32_16x16x32_bf16 v[6:9], v[182:185], v[232:235], v[6:9]
	v_mfma_f32_16x16x32_bf16 v[2:5], v[190:193], v[232:235], v[2:5]
	v_mfma_f32_16x16x32_bf16 v[54:57], v[186:189], v[212:215], v[54:57]
	v_mfma_f32_16x16x32_bf16 v[50:53], v[194:197], v[212:215], v[50:53]
	v_mfma_f32_16x16x32_bf16 v[38:41], v[186:189], v[220:223], v[38:41]
	v_mfma_f32_16x16x32_bf16 v[34:37], v[194:197], v[220:223], v[34:37]
	v_mfma_f32_16x16x32_bf16 v[22:25], v[186:189], v[228:231], v[22:25]
	v_mfma_f32_16x16x32_bf16 v[18:21], v[194:197], v[228:231], v[18:21]
	v_mfma_f32_16x16x32_bf16 v[6:9], v[186:189], v[236:239], v[6:9]
	v_mfma_f32_16x16x32_bf16 v[2:5], v[194:197], v[236:239], v[2:5]
	s_setprio 0
	s_barrier
	s_add_i32 s46, s46, 2
	s_add_u32 s44, s44, 0x100
	s_addc_u32 s45, s45, 0
	s_add_u32 s26, s26, 0x100
	s_addc_u32 s27, s27, 0
	s_cmp_gt_u32 s46, 29
	s_cbranch_scc0 .LBB0_173
	v_readlane_b32 s42, v251, 53
	s_and_b64 vcc, exec, s[12:13]
	v_readlane_b32 s43, v251, 54
	s_cbranch_vccz .LBB0_176
	s_barrier

; #define PG8_STAGE(bufoff, gbase, voff) do { _Pragma("unroll") for (int _i = 0; _i < 2; ++_i) \
;         __builtin_amdgcn_global_load_lds((const unsigned*)((const char*)(gbase) + (voff)[_i]), (LAS unsigned*)(lds + (bufoff) + ldsw + _i * 8192), 16, 0, 0); } while (0)
; #define PG8_LDA(dst, b, h) do { _Pragma("unroll") for (int m = 0; m < 4; ++m) _Pragma("unroll") for (int k = 0; k < 2; ++k) dst[m][k] = *(const LAS bf16x8*)(lds + PG8_SA(b, h) + aoff + m * 2048 + k * 1024); } while (0)
; #define PG8_LDB(dst, b, h) do { _Pragma("unroll") for (int n = 0; n < 2; ++n) _Pragma("unroll") for (int k = 0; k < 2; ++k) dst[n][k] = *(const LAS bf16x8*)(lds + PG8_SB(b, h) + boff + n * 2048 + k * 1024); } while (0)
; template <class Epi>
; __device__ __forceinline__ void gemm_phase(LAS unsigned char* lds, const Gemm g, const StaticOrder& S, const Epi& E, const int tid) {
;     ...
;         for (int t = 0; t < ntt; t += 2) {
;             const bool last = (t == ntt - 2);
;             const bool s1 = Epi::TWO && (t >= nt), s2 = Epi::TWO && (t + 2 >= nt);
;             const char* a1 = (s1 ? cA2 + (size_t)(t - nt + 1) * kstep : cA + (size_t)(t + 1) * kstep);
;             const char* a2 = last ? nA : (s2 ? cA2 + (size_t)(t + 2 - nt) * kstep : cA + (size_t)(t + 2) * kstep);
;             const char* b2 = last ? nB : (s2 ? cB2 + (size_t)(t + 2 - nt) * kstep : cB + (size_t)(t + 2) * kstep);
;             const char* a3 = a2 + kstep; const char* b3 = b2 + kstep;
;             if constexpr (Epi::TWO) { if (t == nt) E.mid(acc, cur, wr, wc, fr, fq); }
;             if constexpr (SP2) {
;             PG8_LDB(B0, 0, 0); PG8_LDB(B1, 0, 1); PG8_SCHED; PG8_LDA(At, 0, 0); PG8_STAGE(PG8_SA(1, 1), a1 + hstep, voffA);
;             PG8_WAIT_V(8); PG8_WAIT_L(0); PG8_BAR; PG8_MMA(0, 0, At, B0); PG8_MMA(0, 1, At, B1); PG8_BAR; PG8_SCHED;
;             PG8_LDA(At, 0, 1); PG8_STAGE(PG8_SB(0, 0), b2, voffB); PG8_STAGE(PG8_SB(0, 1), b2 + bhs, voffB); PG8_STAGE(PG8_SA(0, 0), a2, voffA);
;             PG8_WAIT_V(8); PG8_WAIT_L(0); PG8_BAR; PG8_MMA(1, 0, At, B0); PG8_MMA(1, 1, At, B1); PG8_BAR; PG8_SCHED;
;     ...
; #pragma unroll
;         for (int a = 0; a < 2; ++a)
; #pragma unroll
;             for (int b = 0; b < 2; ++b)
; #pragma unroll
;                 for (int m = 0; m < 4; ++m)
; #pragma unroll
;                     for (int n = 0; n < 2; ++n) acc[a][b][m][n] = (f32x4){0.f, 0.f, 0.f, 0.f};
.LBB0_206:
	s_add_u32 s30, s28, 0xfffe0080
	s_addc_u32 s31, s29, -1
	s_add_i32 s52, 0, 0x10000
	s_cmp_eq_u32 s51, 4
	s_cselect_b32 s35, s17, s31
	s_cselect_b32 s34, s27, s30
	s_cselect_b32 s31, s15, s50
	s_cselect_b32 s30, s33, s49
	s_add_i32 s54, 0, 0x14000
	v_add_u32_e32 v30, s52, v193
	v_add_u32_e32 v54, s54, v193
	ds_read_b128 v[18:21], v30
	ds_read_b128 v[22:25], v30 offset:1024
	ds_read_b128 v[26:29], v30 offset:2048
	ds_read_b128 v[30:33], v30 offset:3072
	ds_read_b128 v[42:45], v54
	ds_read_b128 v[46:49], v54 offset:1024
	ds_read_b128 v[50:53], v54 offset:2048
	ds_read_b128 v[54:57], v54 offset:3072
	v_lshl_add_u64 v[172:173], s[28:29], 0, v[180:181]
	s_add_i32 m0, s37, 0xc000
	ds_read_b128 v[182:185], v199
	global_load_lds_dwordx4 v[172:173], off
	ds_read_b128 v[186:189], v199 offset:1024
	ds_read_b128 v[212:215], v199 offset:2048
	s_add_i32 m0, s37, 0xe000
	v_lshl_add_u64 v[172:173], s[28:29], 0, v[178:179]
	global_load_lds_dwordx4 v[172:173], off
	ds_read_b128 v[216:219], v199 offset:3072
	ds_read_b128 v[220:223], v199 offset:4096
	ds_read_b128 v[224:227], v199 offset:5120
	ds_read_b128 v[228:231], v199 offset:6144
	ds_read_b128 v[232:235], v199 offset:7168
	s_waitcnt vmcnt(8)
	s_waitcnt lgkmcnt(0)
	s_barrier
	s_setprio 1
	v_mfma_f32_16x16x32_bf16 v[158:161], v[18:21], v[182:185], v[158:161]
	v_mfma_f32_16x16x32_bf16 v[154:157], v[26:29], v[182:185], v[154:157]
	v_mfma_f32_16x16x32_bf16 v[142:145], v[18:21], v[212:215], v[142:145]
	v_mfma_f32_16x16x32_bf16 v[138:141], v[26:29], v[212:215], v[138:141]
	v_mfma_f32_16x16x32_bf16 v[126:129], v[18:21], v[220:223], v[126:129]
	v_mfma_f32_16x16x32_bf16 v[122:125], v[26:29], v[220:223], v[122:125]
	v_mfma_f32_16x16x32_bf16 v[110:113], v[18:21], v[228:231], v[110:113]
	v_mfma_f32_16x16x32_bf16 v[106:109], v[26:29], v[228:231], v[106:109]
	v_mfma_f32_16x16x32_bf16 v[158:161], v[22:25], v[186:189], v[158:161]
	v_mfma_f32_16x16x32_bf16 v[154:157], v[30:33], v[186:189], v[154:157]
	v_mfma_f32_16x16x32_bf16 v[142:145], v[22:25], v[216:219], v[142:145]
	v_mfma_f32_16x16x32_bf16 v[138:141], v[30:33], v[216:219], v[138:141]
	v_mfma_f32_16x16x32_bf16 v[126:129], v[22:25], v[224:227], v[126:129]
	v_mfma_f32_16x16x32_bf16 v[122:125], v[30:33], v[224:227], v[122:125]
	v_mfma_f32_16x16x32_bf16 v[110:113], v[22:25], v[232:235], v[110:113]
	v_mfma_f32_16x16x32_bf16 v[106:109], v[30:33], v[232:235], v[106:109]
	v_mfma_f32_16x16x32_bf16 v[150:153], v[42:45], v[182:185], v[150:153]
	v_mfma_f32_16x16x32_bf16 v[146:149], v[50:53], v[182:185], v[146:149]
	v_mfma_f32_16x16x32_bf16 v[134:137], v[42:45], v[212:215], v[134:137]
	v_mfma_f32_16x16x32_bf16 v[130:133], v[50:53], v[212:215], v[130:133]
	v_mfma_f32_16x16x32_bf16 v[118:121], v[42:45], v[220:223], v[118:121]
	v_mfma_f32_16x16x32_bf16 v[114:117], v[50:53], v[220:223], v[114:117]
	v_mfma_f32_16x16x32_bf16 v[102:105], v[42:45], v[228:231], v[102:105]
	v_mfma_f32_16x16x32_bf16 v[98:101], v[50:53], v[228:231], v[98:101]
	v_mfma_f32_16x16x32_bf16 v[150:153], v[46:49], v[186:189], v[150:153]
	v_mfma_f32_16x16x32_bf16 v[146:149], v[54:57], v[186:189], v[146:149]
	v_mfma_f32_16x16x32_bf16 v[134:137], v[46:49], v[216:219], v[134:137]
	v_mfma_f32_16x16x32_bf16 v[130:133], v[54:57], v[216:219], v[130:133]
	v_mfma_f32_16x16x32_bf16 v[118:121], v[46:49], v[224:227], v[118:121]
	v_mfma_f32_16x16x32_bf16 v[114:117], v[54:57], v[224:227], v[114:117]
	v_mfma_f32_16x16x32_bf16 v[102:105], v[46:49], v[232:235], v[102:105]
	v_mfma_f32_16x16x32_bf16 v[98:101], v[54:57], v[232:235], v[98:101]
	s_setprio 0
	s_barrier
	s_add_i32 s52, s52, s36
	v_lshl_add_u64 v[172:173], s[30:31], 0, v[0:1]
	s_mov_b32 m0, s52
	ds_read_b128 v[182:185], v199 offset:16384
	global_load_lds_dwordx4 v[172:173], off
	ds_read_b128 v[186:189], v199 offset:17408
	ds_read_b128 v[212:215], v199 offset:18432
	s_add_i32 m0, s52, 0x2000
	s_add_u32 s52, s30, 0x2000
	v_lshl_add_u64 v[174:175], s[30:31], 0, v[166:167]
	s_addc_u32 s53, s31, 0
	s_add_i32 s54, s54, s36
	global_load_lds_dwordx4 v[174:175], off
	ds_read_b128 v[216:219], v199 offset:19456
	ds_read_b128 v[220:223], v199 offset:20480
	v_lshl_add_u64 v[176:177], s[52:53], 0, v[0:1]
	s_mov_b32 m0, s54
	v_lshl_add_u64 v[200:201], s[34:35], 0, v[164:165]
	global_load_lds_dwordx4 v[176:177], off
	ds_read_b128 v[224:227], v199 offset:21504
	ds_read_b128 v[228:231], v199 offset:22528
	s_add_i32 m0, s54, 0x2000
	v_lshl_add_u64 v[176:177], s[52:53], 0, v[166:167]
	global_load_lds_dwordx4 v[176:177], off
	ds_read_b128 v[232:235], v199 offset:23552
	s_mov_b32 m0, s37
	v_lshl_add_u64 v[176:177], s[34:35], 0, v[162:163]
	global_load_lds_dwordx4 v[176:177], off
	s_mov_b32 m0, s38
	s_nop 0
	global_load_lds_dwordx4 v[200:201], off
	s_waitcnt vmcnt(8)
	s_waitcnt lgkmcnt(0)
	s_barrier
; #define PG8_STAGE(bufoff, gbase, voff) do { _Pragma("unroll") for (int _i = 0; _i < 2; ++_i) \
;         __builtin_amdgcn_global_load_lds((const unsigned*)((const char*)(gbase) + (voff)[_i]), (LAS unsigned*)(lds + (bufoff) + ldsw + _i * 8192), 16, 0, 0); } while (0)
; #define PG8_LDA(dst, b, h) do { _Pragma("unroll") for (int m = 0; m < 4; ++m) _Pragma("unroll") for (int k = 0; k < 2; ++k) dst[m][k] = *(const LAS bf16x8*)(lds + PG8_SA(b, h) + aoff + m * 2048 + k * 1024); } while (0)
; #define PG8_LDB(dst, b, h) do { _Pragma("unroll") for (int n = 0; n < 2; ++n) _Pragma("unroll") for (int k = 0; k < 2; ++k) dst[n][k] = *(const LAS bf16x8*)(lds + PG8_SB(b, h) + boff + n * 2048 + k * 1024); } while (0)
; #define PG8_MMA(ai, bj, At, Bt) do { __builtin_amdgcn_s_setprio(1); _Pragma("unroll") for (int m = 0; m < 4; ++m) _Pragma("unroll") for (int n = 0; n < 2; ++n) _Pragma("unroll") for (int k = 0; k < 2; ++k) \
;         acc[ai][bj][m][n] = __builtin_amdgcn_mfma_f32_16x16x32_bf16(Bt[n][k], At[m][k], acc[ai][bj][m][n], 0, 0, 0); __builtin_amdgcn_s_setprio(0); } while (0)
; #define PG8_WAIT_V(n) asm volatile("s_waitcnt vmcnt(" #n ")" ::: "memory")
; #define PG8_WAIT_L(n) asm volatile("s_waitcnt lgkmcnt(" #n ")" ::: "memory")
; #define PG8_BAR __builtin_amdgcn_s_barrier()
; #define PG8_SCHED __builtin_amdgcn_sched_barrier(0)
; template <class Epi>
; __device__ __forceinline__ void gemm_phase(LAS unsigned char* lds, const Gemm g, const StaticOrder& S, const Epi& E, const int tid) {
;     ...
;             PG8_WAIT_V(8); PG8_WAIT_L(0); PG8_BAR; PG8_MMA(0, 0, At, B0); PG8_MMA(0, 1, At, B1); PG8_BAR; PG8_SCHED;
;             PG8_LDA(At, 0, 1); PG8_STAGE(PG8_SB(0, 0), b2, voffB); PG8_STAGE(PG8_SB(0, 1), b2 + bhs, voffB); PG8_STAGE(PG8_SA(0, 0), a2, voffA);
;             PG8_WAIT_V(8); PG8_WAIT_L(0); PG8_BAR; PG8_MMA(1, 0, At, B0); PG8_MMA(1, 1, At, B1); PG8_BAR; PG8_SCHED;
;             PG8_LDB(B0, 1, 0); PG8_LDB(B1, 1, 1); PG8_SCHED; PG8_LDA(At, 1, 0); PG8_STAGE(PG8_SA(0, 1), a2 + hstep, voffA);
;             PG8_WAIT_V(8); PG8_WAIT_L(0); PG8_BAR; PG8_MMA(0, 0, At, B0); PG8_MMA(0, 1, At, B1); PG8_BAR; PG8_SCHED;
	s_setprio 1
	v_mfma_f32_16x16x32_bf16 v[94:97], v[18:21], v[182:185], v[94:97]
	v_mfma_f32_16x16x32_bf16 v[90:93], v[26:29], v[182:185], v[90:93]
	v_mfma_f32_16x16x32_bf16 v[78:81], v[18:21], v[212:215], v[78:81]
	v_mfma_f32_16x16x32_bf16 v[74:77], v[26:29], v[212:215], v[74:77]
	v_mfma_f32_16x16x32_bf16 v[62:65], v[18:21], v[220:223], v[62:65]
	v_mfma_f32_16x16x32_bf16 v[58:61], v[26:29], v[220:223], v[58:61]
	v_mfma_f32_16x16x32_bf16 v[14:17], v[18:21], v[228:231], v[14:17]
	v_mfma_f32_16x16x32_bf16 v[10:13], v[26:29], v[228:231], v[10:13]
	v_mfma_f32_16x16x32_bf16 v[94:97], v[22:25], v[186:189], v[94:97]
	v_mfma_f32_16x16x32_bf16 v[90:93], v[30:33], v[186:189], v[90:93]
	v_mfma_f32_16x16x32_bf16 v[78:81], v[22:25], v[216:219], v[78:81]
	v_mfma_f32_16x16x32_bf16 v[74:77], v[30:33], v[216:219], v[74:77]
	v_mfma_f32_16x16x32_bf16 v[62:65], v[22:25], v[224:227], v[62:65]
	v_mfma_f32_16x16x32_bf16 v[58:61], v[30:33], v[224:227], v[58:61]
	v_mfma_f32_16x16x32_bf16 v[14:17], v[22:25], v[232:235], v[14:17]
	v_mfma_f32_16x16x32_bf16 v[10:13], v[30:33], v[232:235], v[10:13]
	v_mfma_f32_16x16x32_bf16 v[38:41], v[42:45], v[220:223], v[38:41]
	v_mfma_f32_16x16x32_bf16 v[34:37], v[50:53], v[220:223], v[34:37]
	v_mfma_f32_16x16x32_bf16 v[6:9], v[42:45], v[228:231], v[6:9]
	v_mfma_f32_16x16x32_bf16 v[2:5], v[50:53], v[228:231], v[2:5]
	v_mfma_f32_16x16x32_bf16 v[18:21], v[42:45], v[182:185], v[86:89]
	v_mfma_f32_16x16x32_bf16 v[22:25], v[50:53], v[182:185], v[82:85]
	v_mfma_f32_16x16x32_bf16 v[26:29], v[42:45], v[212:215], v[70:73]
	v_mfma_f32_16x16x32_bf16 v[30:33], v[50:53], v[212:215], v[66:69]
	v_mfma_f32_16x16x32_bf16 v[38:41], v[46:49], v[224:227], v[38:41]
	v_mfma_f32_16x16x32_bf16 v[34:37], v[54:57], v[224:227], v[34:37]
	v_mfma_f32_16x16x32_bf16 v[6:9], v[46:49], v[232:235], v[6:9]
	v_mfma_f32_16x16x32_bf16 v[2:5], v[54:57], v[232:235], v[2:5]
	v_mfma_f32_16x16x32_bf16 v[18:21], v[46:49], v[186:189], v[18:21]
	v_mfma_f32_16x16x32_bf16 v[22:25], v[54:57], v[186:189], v[22:25]
	v_mfma_f32_16x16x32_bf16 v[26:29], v[46:49], v[216:219], v[26:29]
	v_mfma_f32_16x16x32_bf16 v[30:33], v[54:57], v[216:219], v[30:33]
	s_setprio 0
	s_barrier
	s_add_i32 s52, 0, 0x18000
	s_add_i32 s53, 0, 0x1c000
	v_add_u32_e32 v54, s52, v193
	v_add_u32_e32 v66, s53, v193
	ds_read_b128 v[42:45], v54
	ds_read_b128 v[46:49], v54 offset:1024
	ds_read_b128 v[50:53], v54 offset:2048
	ds_read_b128 v[54:57], v54 offset:3072
	ds_read_b128 v[182:185], v66
	ds_read_b128 v[186:189], v66 offset:1024
	ds_read_b128 v[212:215], v66 offset:2048
	ds_read_b128 v[216:219], v66 offset:3072
	s_add_u32 s34, s34, 0x20000
	s_addc_u32 s35, s35, 0
	s_mov_b32 m0, s39
	v_lshl_add_u64 v[236:237], s[34:35], 0, v[162:163]
	ds_read_b128 v[66:69], v199 offset:32768
	global_load_lds_dwordx4 v[236:237], off
	ds_read_b128 v[70:73], v199 offset:33792
	ds_read_b128 v[82:85], v199 offset:34816
	s_mov_b32 m0, s44
	v_lshl_add_u64 v[236:237], s[34:35], 0, v[164:165]
	global_load_lds_dwordx4 v[236:237], off
	ds_read_b128 v[86:89], v199 offset:35840
	ds_read_b128 v[220:223], v199 offset:36864
	ds_read_b128 v[224:227], v199 offset:37888
	ds_read_b128 v[228:231], v199 offset:38912
	ds_read_b128 v[232:235], v199 offset:39936
	s_waitcnt vmcnt(8)
	s_waitcnt lgkmcnt(0)
	s_barrier
	s_setprio 1
	v_mfma_f32_16x16x32_bf16 v[158:161], v[42:45], v[66:69], v[158:161]
	v_mfma_f32_16x16x32_bf16 v[154:157], v[50:53], v[66:69], v[154:157]
	v_mfma_f32_16x16x32_bf16 v[142:145], v[42:45], v[82:85], v[142:145]
	v_mfma_f32_16x16x32_bf16 v[138:141], v[50:53], v[82:85], v[138:141]
	v_mfma_f32_16x16x32_bf16 v[126:129], v[42:45], v[220:223], v[126:129]
	v_mfma_f32_16x16x32_bf16 v[122:125], v[50:53], v[220:223], v[122:125]
	v_mfma_f32_16x16x32_bf16 v[110:113], v[42:45], v[228:231], v[110:113]
	v_mfma_f32_16x16x32_bf16 v[106:109], v[50:53], v[228:231], v[106:109]
	v_mfma_f32_16x16x32_bf16 v[158:161], v[46:49], v[70:73], v[158:161]
	v_mfma_f32_16x16x32_bf16 v[154:157], v[54:57], v[70:73], v[154:157]
	v_mfma_f32_16x16x32_bf16 v[142:145], v[46:49], v[86:89], v[142:145]
	v_mfma_f32_16x16x32_bf16 v[138:141], v[54:57], v[86:89], v[138:141]
	v_mfma_f32_16x16x32_bf16 v[126:129], v[46:49], v[224:227], v[126:129]
	v_mfma_f32_16x16x32_bf16 v[122:125], v[54:57], v[224:227], v[122:125]
	v_mfma_f32_16x16x32_bf16 v[110:113], v[46:49], v[232:235], v[110:113]
	v_mfma_f32_16x16x32_bf16 v[106:109], v[54:57], v[232:235], v[106:109]
	v_mfma_f32_16x16x32_bf16 v[150:153], v[182:185], v[66:69], v[150:153]
	v_mfma_f32_16x16x32_bf16 v[66:69], v[212:215], v[66:69], v[146:149]
	v_mfma_f32_16x16x32_bf16 v[146:149], v[216:219], v[70:73], v[66:69]
	v_mfma_f32_16x16x32_bf16 v[66:69], v[182:185], v[82:85], v[134:137]
	v_mfma_f32_16x16x32_bf16 v[134:137], v[186:189], v[86:89], v[66:69]
	v_mfma_f32_16x16x32_bf16 v[66:69], v[212:215], v[82:85], v[130:133]
	v_mfma_f32_16x16x32_bf16 v[130:133], v[216:219], v[86:89], v[66:69]
	v_mfma_f32_16x16x32_bf16 v[66:69], v[182:185], v[220:223], v[118:121]
	v_mfma_f32_16x16x32_bf16 v[118:121], v[186:189], v[224:227], v[66:69]
	v_mfma_f32_16x16x32_bf16 v[66:69], v[212:215], v[220:223], v[114:117]
	v_mfma_f32_16x16x32_bf16 v[114:117], v[216:219], v[224:227], v[66:69]
	v_mfma_f32_16x16x32_bf16 v[66:69], v[182:185], v[228:231], v[102:105]
	v_mfma_f32_16x16x32_bf16 v[102:105], v[186:189], v[232:235], v[66:69]
	v_mfma_f32_16x16x32_bf16 v[66:69], v[212:215], v[228:231], v[98:101]
	v_mfma_f32_16x16x32_bf16 v[150:153], v[186:189], v[70:73], v[150:153]
	v_mfma_f32_16x16x32_bf16 v[98:101], v[216:219], v[232:235], v[66:69]
	s_setprio 0
	s_barrier
; #define PG8_STAGE(bufoff, gbase, voff) do { _Pragma("unroll") for (int _i = 0; _i < 2; ++_i) \
;         __builtin_amdgcn_global_load_lds((const unsigned*)((const char*)(gbase) + (voff)[_i]), (LAS unsigned*)(lds + (bufoff) + ldsw + _i * 8192), 16, 0, 0); } while (0)
; #define PG8_LDA(dst, b, h) do { _Pragma("unroll") for (int m = 0; m < 4; ++m) _Pragma("unroll") for (int k = 0; k < 2; ++k) dst[m][k] = *(const LAS bf16x8*)(lds + PG8_SA(b, h) + aoff + m * 2048 + k * 1024); } while (0)
; #define PG8_MMA(ai, bj, At, Bt) do { __builtin_amdgcn_s_setprio(1); _Pragma("unroll") for (int m = 0; m < 4; ++m) _Pragma("unroll") for (int n = 0; n < 2; ++n) _Pragma("unroll") for (int k = 0; k < 2; ++k) \
;         acc[ai][bj][m][n] = __builtin_amdgcn_mfma_f32_16x16x32_bf16(Bt[n][k], At[m][k], acc[ai][bj][m][n], 0, 0, 0); __builtin_amdgcn_s_setprio(0); } while (0)
; #define PG8_WAIT_V(n) asm volatile("s_waitcnt vmcnt(" #n ")" ::: "memory")
; #define PG8_WAIT_L(n) asm volatile("s_waitcnt lgkmcnt(" #n ")" ::: "memory")
; #define PG8_BAR __builtin_amdgcn_s_barrier()
; #define PG8_SCHED __builtin_amdgcn_sched_barrier(0)
; template <class Epi>
; __device__ __forceinline__ void gemm_phase(LAS unsigned char* lds, const Gemm g, const StaticOrder& S, const Epi& E, const int tid) {
;     ...
;         for (int t = 0; t < ntt; t += 2) {
;             const bool last = (t == ntt - 2);
;             const bool s1 = Epi::TWO && (t >= nt), s2 = Epi::TWO && (t + 2 >= nt);
;     ...
;             PG8_LDA(At, 1, 1); PG8_STAGE(PG8_SB(1, 0), b3, voffB); PG8_STAGE(PG8_SB(1, 1), b3 + bhs, voffB); PG8_STAGE(PG8_SA(1, 0), a3, voffA);
;             PG8_WAIT_V(8); PG8_WAIT_L(0); PG8_BAR; PG8_MMA(1, 0, At, B0); PG8_MMA(1, 1, At, B1); PG8_BAR; PG8_SCHED;
	s_add_i32 s34, s52, s36
	v_lshl_add_u64 v[82:83], v[172:173], 0, s[70:71]
	s_mov_b32 m0, s34
	s_nop 0
	ds_read_b128 v[66:69], v199 offset:49152
	global_load_lds_dwordx4 v[82:83], off
	ds_read_b128 v[70:73], v199 offset:50176
	ds_read_b128 v[220:223], v199 offset:51200
	s_add_i32 m0, s34, 0x2000
	s_add_u32 s30, s30, 0x2080
	v_lshl_add_u64 v[82:83], v[174:175], 0, s[70:71]
	s_addc_u32 s31, s31, 0
	s_add_i32 s34, s53, s36
	global_load_lds_dwordx4 v[82:83], off
	ds_read_b128 v[224:227], v199 offset:52224
	ds_read_b128 v[228:231], v199 offset:53248
	s_mov_b32 m0, s34
	v_lshl_add_u64 v[82:83], s[30:31], 0, v[0:1]
	global_load_lds_dwordx4 v[82:83], off
	ds_read_b128 v[232:235], v199 offset:54272
	ds_read_b128 v[236:239], v199 offset:55296
	s_add_i32 m0, s34, 0x2000
	v_lshl_add_u64 v[82:83], s[30:31], 0, v[166:167]
	global_load_lds_dwordx4 v[82:83], off
	ds_read_b128 v[240:243], v199 offset:56320
	s_mov_b32 m0, s45
	v_lshl_add_u64 v[82:83], v[176:177], 0, s[70:71]
	global_load_lds_dwordx4 v[82:83], off
	s_mov_b32 m0, s46
	v_lshl_add_u64 v[82:83], v[200:201], 0, s[70:71]
	global_load_lds_dwordx4 v[82:83], off
	s_waitcnt vmcnt(8)
	s_waitcnt lgkmcnt(0)
	s_barrier
	s_setprio 1
	v_mfma_f32_16x16x32_bf16 v[82:85], v[42:45], v[66:69], v[94:97]
	v_mfma_f32_16x16x32_bf16 v[94:97], v[46:49], v[70:73], v[82:85]
	v_mfma_f32_16x16x32_bf16 v[82:85], v[50:53], v[66:69], v[90:93]
	v_mfma_f32_16x16x32_bf16 v[78:81], v[42:45], v[220:223], v[78:81]
	v_mfma_f32_16x16x32_bf16 v[74:77], v[50:53], v[220:223], v[74:77]
	v_mfma_f32_16x16x32_bf16 v[62:65], v[42:45], v[228:231], v[62:65]
	v_mfma_f32_16x16x32_bf16 v[58:61], v[50:53], v[228:231], v[58:61]
	v_mfma_f32_16x16x32_bf16 v[14:17], v[42:45], v[236:239], v[14:17]
	v_mfma_f32_16x16x32_bf16 v[10:13], v[50:53], v[236:239], v[10:13]
	v_mfma_f32_16x16x32_bf16 v[90:93], v[54:57], v[70:73], v[82:85]
	v_mfma_f32_16x16x32_bf16 v[78:81], v[46:49], v[224:227], v[78:81]
	v_mfma_f32_16x16x32_bf16 v[74:77], v[54:57], v[224:227], v[74:77]
	v_mfma_f32_16x16x32_bf16 v[62:65], v[46:49], v[232:235], v[62:65]
	v_mfma_f32_16x16x32_bf16 v[58:61], v[54:57], v[232:235], v[58:61]
	v_mfma_f32_16x16x32_bf16 v[14:17], v[46:49], v[240:243], v[14:17]
	v_mfma_f32_16x16x32_bf16 v[10:13], v[54:57], v[240:243], v[10:13]
	v_mfma_f32_16x16x32_bf16 v[18:21], v[182:185], v[66:69], v[18:21]
	v_mfma_f32_16x16x32_bf16 v[86:89], v[186:189], v[70:73], v[18:21]
	v_mfma_f32_16x16x32_bf16 v[18:21], v[212:215], v[66:69], v[22:25]
	v_mfma_f32_16x16x32_bf16 v[82:85], v[216:219], v[70:73], v[18:21]
	v_mfma_f32_16x16x32_bf16 v[18:21], v[182:185], v[220:223], v[26:29]
	v_mfma_f32_16x16x32_bf16 v[70:73], v[186:189], v[224:227], v[18:21]
	v_mfma_f32_16x16x32_bf16 v[18:21], v[212:215], v[220:223], v[30:33]
	v_mfma_f32_16x16x32_bf16 v[66:69], v[216:219], v[224:227], v[18:21]
	v_mfma_f32_16x16x32_bf16 v[18:21], v[182:185], v[228:231], v[38:41]
	v_mfma_f32_16x16x32_bf16 v[38:41], v[186:189], v[232:235], v[18:21]
	v_mfma_f32_16x16x32_bf16 v[18:21], v[212:215], v[228:231], v[34:37]
	v_mfma_f32_16x16x32_bf16 v[6:9], v[182:185], v[236:239], v[6:9]
	v_mfma_f32_16x16x32_bf16 v[2:5], v[212:215], v[236:239], v[2:5]
	v_mfma_f32_16x16x32_bf16 v[34:37], v[216:219], v[232:235], v[18:21]
	v_mfma_f32_16x16x32_bf16 v[6:9], v[186:189], v[240:243], v[6:9]
	v_mfma_f32_16x16x32_bf16 v[2:5], v[216:219], v[240:243], v[2:5]
	s_setprio 0
	s_barrier
	s_add_i32 s51, s51, 2
	s_add_u32 s49, s49, 0x100
	s_addc_u32 s50, s50, 0
	s_add_u32 s28, s28, 0x100
	s_addc_u32 s29, s29, 0
	s_cmp_gt_u32 s51, 5
	s_cbranch_scc0 .LBB0_206
	s_and_b64 vcc, exec, s[12:13]
	s_cbranch_vccz .LBB0_209
	s_barrier

; #define PG8_STAGE(bufoff, gbase, voff) do { _Pragma("unroll") for (int _i = 0; _i < 2; ++_i) \
;         __builtin_amdgcn_global_load_lds((const unsigned*)((const char*)(gbase) + (voff)[_i]), (LAS unsigned*)(lds + (bufoff) + ldsw + _i * 8192), 16, 0, 0); } while (0)
; #define PG8_LDA(dst, b, h) do { _Pragma("unroll") for (int m = 0; m < 4; ++m) _Pragma("unroll") for (int k = 0; k < 2; ++k) dst[m][k] = *(const LAS bf16x8*)(lds + PG8_SA(b, h) + aoff + m * 2048 + k * 1024); } while (0)
; #define PG8_LDB(dst, b, h) do { _Pragma("unroll") for (int n = 0; n < 2; ++n) _Pragma("unroll") for (int k = 0; k < 2; ++k) dst[n][k] = *(const LAS bf16x8*)(lds + PG8_SB(b, h) + boff + n * 2048 + k * 1024); } while (0)
; template <class Epi>
; __device__ __forceinline__ void gemm_phase(LAS unsigned char* lds, const Gemm g, const StaticOrder& S, const Epi& E, const int tid) {
;     ...
;         for (int t = 0; t < ntt; t += 2) {
;             const bool last = (t == ntt - 2);
;             const bool s1 = Epi::TWO && (t >= nt), s2 = Epi::TWO && (t + 2 >= nt);
;             const char* a1 = (s1 ? cA2 + (size_t)(t - nt + 1) * kstep : cA + (size_t)(t + 1) * kstep);
;             const char* a2 = last ? nA : (s2 ? cA2 + (size_t)(t + 2 - nt) * kstep : cA + (size_t)(t + 2) * kstep);
;             const char* b2 = last ? nB : (s2 ? cB2 + (size_t)(t + 2 - nt) * kstep : cB + (size_t)(t + 2) * kstep);
;             const char* a3 = a2 + kstep; const char* b3 = b2 + kstep;
;             if constexpr (Epi::TWO) { if (t == nt) E.mid(acc, cur, wr, wc, fr, fq); }
;             if constexpr (SP2) {
;             PG8_LDB(B0, 0, 0); PG8_LDB(B1, 0, 1); PG8_SCHED; PG8_LDA(At, 0, 0); PG8_STAGE(PG8_SA(1, 1), a1 + hstep, voffA);
;             PG8_WAIT_V(8); PG8_WAIT_L(0); PG8_BAR; PG8_MMA(0, 0, At, B0); PG8_MMA(0, 1, At, B1); PG8_BAR; PG8_SCHED;
;             PG8_LDA(At, 0, 1); PG8_STAGE(PG8_SB(0, 0), b2, voffB); PG8_STAGE(PG8_SB(0, 1), b2 + bhs, voffB); PG8_STAGE(PG8_SA(0, 0), a2, voffA);
;             PG8_WAIT_V(8); PG8_WAIT_L(0); PG8_BAR; PG8_MMA(1, 0, At, B0); PG8_MMA(1, 1, At, B1); PG8_BAR; PG8_SCHED;
;     ...
; #pragma unroll
;         for (int a = 0; a < 2; ++a)
; #pragma unroll
;             for (int b = 0; b < 2; ++b)
; #pragma unroll
;                 for (int m = 0; m < 4; ++m)
; #pragma unroll
;                     for (int n = 0; n < 2; ++n) acc[a][b][m][n] = (f32x4){0.f, 0.f, 0.f, 0.f};
.LBB0_261:
	s_add_u32 s30, s28, 0xfff80080
	s_addc_u32 s31, s29, -1
	s_add_i32 s49, 0, 0x10000
	s_cmp_eq_u32 s48, 28
	s_cselect_b32 s35, s19, s31
	s_cselect_b32 s34, s44, s30
	v_add_u32_e32 v142, s49, v149
	s_cselect_b32 s31, s17, s47
	s_cselect_b32 s30, s45, s46
	s_add_i32 s52, 0, 0x14000
	ds_read_b128 v[156:159], v142
	ds_read_b128 v[160:163], v142 offset:1024
	ds_read_b128 v[164:167], v142 offset:2048
	ds_read_b128 v[178:181], v142 offset:3072
	v_add_u32_e32 v142, s52, v149
	ds_read_b128 v[182:185], v142
	ds_read_b128 v[186:189], v142 offset:1024
	ds_read_b128 v[190:193], v142 offset:2048
	ds_read_b128 v[194:197], v142 offset:3072
	v_lshl_add_u64 v[142:143], s[28:29], 0, v[140:141]
	s_add_i32 m0, s2, 0xc000
	ds_read_b128 v[198:201], v154
	global_load_lds_dwordx4 v[142:143], off
	ds_read_b128 v[212:215], v154 offset:1024
	ds_read_b128 v[216:219], v154 offset:2048
	s_add_i32 m0, s2, 0xe000
	v_lshl_add_u64 v[142:143], s[28:29], 0, v[138:139]
	global_load_lds_dwordx4 v[142:143], off
	ds_read_b128 v[220:223], v154 offset:3072
	ds_read_b128 v[224:227], v154 offset:4096
	ds_read_b128 v[228:231], v154 offset:5120
	ds_read_b128 v[232:235], v154 offset:6144
	ds_read_b128 v[236:239], v154 offset:7168
	s_waitcnt vmcnt(8)
	s_waitcnt lgkmcnt(0)
	s_barrier
	s_setprio 1
	v_mfma_f32_16x16x32_bf16 v[126:129], v[156:159], v[198:201], v[126:129]
	v_mfma_f32_16x16x32_bf16 v[122:125], v[164:167], v[198:201], v[122:125]
	v_mfma_f32_16x16x32_bf16 v[110:113], v[156:159], v[216:219], v[110:113]
	v_mfma_f32_16x16x32_bf16 v[106:109], v[164:167], v[216:219], v[106:109]
	v_mfma_f32_16x16x32_bf16 v[94:97], v[156:159], v[224:227], v[94:97]
	v_mfma_f32_16x16x32_bf16 v[90:93], v[164:167], v[224:227], v[90:93]
	v_mfma_f32_16x16x32_bf16 v[78:81], v[156:159], v[232:235], v[78:81]
	v_mfma_f32_16x16x32_bf16 v[74:77], v[164:167], v[232:235], v[74:77]
	v_mfma_f32_16x16x32_bf16 v[126:129], v[160:163], v[212:215], v[126:129]
	v_mfma_f32_16x16x32_bf16 v[122:125], v[178:181], v[212:215], v[122:125]
	v_mfma_f32_16x16x32_bf16 v[110:113], v[160:163], v[220:223], v[110:113]
	v_mfma_f32_16x16x32_bf16 v[106:109], v[178:181], v[220:223], v[106:109]
	v_mfma_f32_16x16x32_bf16 v[94:97], v[160:163], v[228:231], v[94:97]
	v_mfma_f32_16x16x32_bf16 v[90:93], v[178:181], v[228:231], v[90:93]
	v_mfma_f32_16x16x32_bf16 v[78:81], v[160:163], v[236:239], v[78:81]
	v_mfma_f32_16x16x32_bf16 v[74:77], v[178:181], v[236:239], v[74:77]
	v_mfma_f32_16x16x32_bf16 v[118:121], v[182:185], v[198:201], v[118:121]
	v_mfma_f32_16x16x32_bf16 v[114:117], v[190:193], v[198:201], v[114:117]
	v_mfma_f32_16x16x32_bf16 v[102:105], v[182:185], v[216:219], v[102:105]
	v_mfma_f32_16x16x32_bf16 v[98:101], v[190:193], v[216:219], v[98:101]
	v_mfma_f32_16x16x32_bf16 v[86:89], v[182:185], v[224:227], v[86:89]
	v_mfma_f32_16x16x32_bf16 v[82:85], v[190:193], v[224:227], v[82:85]
	v_mfma_f32_16x16x32_bf16 v[70:73], v[182:185], v[232:235], v[70:73]
	v_mfma_f32_16x16x32_bf16 v[66:69], v[190:193], v[232:235], v[66:69]
	v_mfma_f32_16x16x32_bf16 v[118:121], v[186:189], v[212:215], v[118:121]
	v_mfma_f32_16x16x32_bf16 v[114:117], v[194:197], v[212:215], v[114:117]
	v_mfma_f32_16x16x32_bf16 v[102:105], v[186:189], v[220:223], v[102:105]
	v_mfma_f32_16x16x32_bf16 v[98:101], v[194:197], v[220:223], v[98:101]
	v_mfma_f32_16x16x32_bf16 v[86:89], v[186:189], v[228:231], v[86:89]
	v_mfma_f32_16x16x32_bf16 v[82:85], v[194:197], v[228:231], v[82:85]
	v_mfma_f32_16x16x32_bf16 v[70:73], v[186:189], v[236:239], v[70:73]
	v_mfma_f32_16x16x32_bf16 v[66:69], v[194:197], v[236:239], v[66:69]
	s_setprio 0
	s_barrier
	s_add_i32 s49, s49, s36
	v_lshl_add_u64 v[142:143], s[30:31], 0, v[0:1]
	s_mov_b32 m0, s49
	ds_read_b128 v[198:201], v154 offset:16384
	global_load_lds_dwordx4 v[142:143], off
	ds_read_b128 v[212:215], v154 offset:17408
	ds_read_b128 v[216:219], v154 offset:18432
	s_add_i32 m0, s49, 0x2000
	s_add_u32 s50, s30, 0x8000
	v_lshl_add_u64 v[168:169], s[30:31], 0, v[134:135]
	s_addc_u32 s51, s31, 0
	s_add_i32 s49, s52, s36
	global_load_lds_dwordx4 v[168:169], off
	ds_read_b128 v[220:223], v154 offset:19456
	ds_read_b128 v[224:227], v154 offset:20480
	v_lshl_add_u64 v[172:173], s[50:51], 0, v[0:1]
	s_mov_b32 m0, s49
	v_lshl_add_u64 v[174:175], s[34:35], 0, v[132:133]
	global_load_lds_dwordx4 v[172:173], off
	ds_read_b128 v[228:231], v154 offset:21504
	ds_read_b128 v[232:235], v154 offset:22528
	s_add_i32 m0, s49, 0x2000
	v_lshl_add_u64 v[172:173], s[50:51], 0, v[134:135]
	global_load_lds_dwordx4 v[172:173], off
	ds_read_b128 v[236:239], v154 offset:23552
	s_mov_b32 m0, s2
	v_lshl_add_u64 v[172:173], s[34:35], 0, v[130:131]
	global_load_lds_dwordx4 v[172:173], off
	s_mov_b32 m0, s27
	s_nop 0
	global_load_lds_dwordx4 v[174:175], off
	s_waitcnt vmcnt(8)
	s_waitcnt lgkmcnt(0)
	s_barrier
; #define PG8_STAGE(bufoff, gbase, voff) do { _Pragma("unroll") for (int _i = 0; _i < 2; ++_i) \
;         __builtin_amdgcn_global_load_lds((const unsigned*)((const char*)(gbase) + (voff)[_i]), (LAS unsigned*)(lds + (bufoff) + ldsw + _i * 8192), 16, 0, 0); } while (0)
; #define PG8_LDA(dst, b, h) do { _Pragma("unroll") for (int m = 0; m < 4; ++m) _Pragma("unroll") for (int k = 0; k < 2; ++k) dst[m][k] = *(const LAS bf16x8*)(lds + PG8_SA(b, h) + aoff + m * 2048 + k * 1024); } while (0)
; #define PG8_LDB(dst, b, h) do { _Pragma("unroll") for (int n = 0; n < 2; ++n) _Pragma("unroll") for (int k = 0; k < 2; ++k) dst[n][k] = *(const LAS bf16x8*)(lds + PG8_SB(b, h) + boff + n * 2048 + k * 1024); } while (0)
; #define PG8_MMA(ai, bj, At, Bt) do { __builtin_amdgcn_s_setprio(1); _Pragma("unroll") for (int m = 0; m < 4; ++m) _Pragma("unroll") for (int n = 0; n < 2; ++n) _Pragma("unroll") for (int k = 0; k < 2; ++k) \
;         acc[ai][bj][m][n] = __builtin_amdgcn_mfma_f32_16x16x32_bf16(Bt[n][k], At[m][k], acc[ai][bj][m][n], 0, 0, 0); __builtin_amdgcn_s_setprio(0); } while (0)
; #define PG8_WAIT_V(n) asm volatile("s_waitcnt vmcnt(" #n ")" ::: "memory")
; #define PG8_WAIT_L(n) asm volatile("s_waitcnt lgkmcnt(" #n ")" ::: "memory")
; #define PG8_BAR __builtin_amdgcn_s_barrier()
; #define PG8_SCHED __builtin_amdgcn_sched_barrier(0)
; template <class Epi>
; __device__ __forceinline__ void gemm_phase(LAS unsigned char* lds, const Gemm g, const StaticOrder& S, const Epi& E, const int tid) {
;     ...
;             PG8_WAIT_V(8); PG8_WAIT_L(0); PG8_BAR; PG8_MMA(0, 0, At, B0); PG8_MMA(0, 1, At, B1); PG8_BAR; PG8_SCHED;
;             PG8_LDA(At, 0, 1); PG8_STAGE(PG8_SB(0, 0), b2, voffB); PG8_STAGE(PG8_SB(0, 1), b2 + bhs, voffB); PG8_STAGE(PG8_SA(0, 0), a2, voffA);
;             PG8_WAIT_V(8); PG8_WAIT_L(0); PG8_BAR; PG8_MMA(1, 0, At, B0); PG8_MMA(1, 1, At, B1); PG8_BAR; PG8_SCHED;
;             PG8_LDB(B0, 1, 0); PG8_LDB(B1, 1, 1); PG8_SCHED; PG8_LDA(At, 1, 0); PG8_STAGE(PG8_SA(0, 1), a2 + hstep, voffA);
;             PG8_WAIT_V(8); PG8_WAIT_L(0); PG8_BAR; PG8_MMA(0, 0, At, B0); PG8_MMA(0, 1, At, B1); PG8_BAR; PG8_SCHED;
	s_setprio 1
	v_mfma_f32_16x16x32_bf16 v[62:65], v[156:159], v[198:201], v[62:65]
	v_mfma_f32_16x16x32_bf16 v[58:61], v[164:167], v[198:201], v[58:61]
	v_mfma_f32_16x16x32_bf16 v[46:49], v[156:159], v[216:219], v[46:49]
	v_mfma_f32_16x16x32_bf16 v[42:45], v[164:167], v[216:219], v[42:45]
	v_mfma_f32_16x16x32_bf16 v[30:33], v[156:159], v[224:227], v[30:33]
	v_mfma_f32_16x16x32_bf16 v[26:29], v[164:167], v[224:227], v[26:29]
	v_mfma_f32_16x16x32_bf16 v[14:17], v[156:159], v[232:235], v[14:17]
	v_mfma_f32_16x16x32_bf16 v[10:13], v[164:167], v[232:235], v[10:13]
	v_mfma_f32_16x16x32_bf16 v[62:65], v[160:163], v[212:215], v[62:65]
	v_mfma_f32_16x16x32_bf16 v[58:61], v[178:181], v[212:215], v[58:61]
	v_mfma_f32_16x16x32_bf16 v[46:49], v[160:163], v[220:223], v[46:49]
	v_mfma_f32_16x16x32_bf16 v[42:45], v[178:181], v[220:223], v[42:45]
	v_mfma_f32_16x16x32_bf16 v[30:33], v[160:163], v[228:231], v[30:33]
	v_mfma_f32_16x16x32_bf16 v[26:29], v[178:181], v[228:231], v[26:29]
	v_mfma_f32_16x16x32_bf16 v[14:17], v[160:163], v[236:239], v[14:17]
	v_mfma_f32_16x16x32_bf16 v[10:13], v[178:181], v[236:239], v[10:13]
	v_mfma_f32_16x16x32_bf16 v[54:57], v[182:185], v[198:201], v[54:57]
	v_mfma_f32_16x16x32_bf16 v[50:53], v[190:193], v[198:201], v[50:53]
	v_mfma_f32_16x16x32_bf16 v[38:41], v[182:185], v[216:219], v[38:41]
	v_mfma_f32_16x16x32_bf16 v[34:37], v[190:193], v[216:219], v[34:37]
	v_mfma_f32_16x16x32_bf16 v[22:25], v[182:185], v[224:227], v[22:25]
	v_mfma_f32_16x16x32_bf16 v[18:21], v[190:193], v[224:227], v[18:21]
	v_mfma_f32_16x16x32_bf16 v[6:9], v[182:185], v[232:235], v[6:9]
	v_mfma_f32_16x16x32_bf16 v[2:5], v[190:193], v[232:235], v[2:5]
	v_mfma_f32_16x16x32_bf16 v[54:57], v[186:189], v[212:215], v[54:57]
	v_mfma_f32_16x16x32_bf16 v[50:53], v[194:197], v[212:215], v[50:53]
	v_mfma_f32_16x16x32_bf16 v[38:41], v[186:189], v[220:223], v[38:41]
	v_mfma_f32_16x16x32_bf16 v[34:37], v[194:197], v[220:223], v[34:37]
	v_mfma_f32_16x16x32_bf16 v[22:25], v[186:189], v[228:231], v[22:25]
	v_mfma_f32_16x16x32_bf16 v[18:21], v[194:197], v[228:231], v[18:21]
	v_mfma_f32_16x16x32_bf16 v[6:9], v[186:189], v[236:239], v[6:9]
	v_mfma_f32_16x16x32_bf16 v[2:5], v[194:197], v[236:239], v[2:5]
	s_setprio 0
	s_barrier
	s_add_i32 s49, 0, 0x18000
	v_add_u32_e32 v155, s49, v149
	s_add_i32 s50, 0, 0x1c000
	ds_read_b128 v[156:159], v155
	ds_read_b128 v[160:163], v155 offset:1024
	ds_read_b128 v[164:167], v155 offset:2048
	ds_read_b128 v[178:181], v155 offset:3072
	v_add_u32_e32 v155, s50, v149
	ds_read_b128 v[182:185], v155
	ds_read_b128 v[186:189], v155 offset:1024
	ds_read_b128 v[190:193], v155 offset:2048
	ds_read_b128 v[194:197], v155 offset:3072
	s_add_u32 s34, s34, 0x80000
	s_addc_u32 s35, s35, 0
	s_mov_b32 m0, s37
	v_lshl_add_u64 v[176:177], s[34:35], 0, v[130:131]
	ds_read_b128 v[198:201], v154 offset:32768
	global_load_lds_dwordx4 v[176:177], off
	ds_read_b128 v[212:215], v154 offset:33792
	ds_read_b128 v[216:219], v154 offset:34816
	s_mov_b32 m0, s38
	v_lshl_add_u64 v[176:177], s[34:35], 0, v[132:133]
	global_load_lds_dwordx4 v[176:177], off
	ds_read_b128 v[220:223], v154 offset:35840
	ds_read_b128 v[224:227], v154 offset:36864
	ds_read_b128 v[228:231], v154 offset:37888
	ds_read_b128 v[232:235], v154 offset:38912
	ds_read_b128 v[236:239], v154 offset:39936
	s_waitcnt vmcnt(8)
	s_waitcnt lgkmcnt(0)
	s_barrier
	s_setprio 1
	v_mfma_f32_16x16x32_bf16 v[126:129], v[156:159], v[198:201], v[126:129]
	v_mfma_f32_16x16x32_bf16 v[122:125], v[164:167], v[198:201], v[122:125]
	v_mfma_f32_16x16x32_bf16 v[110:113], v[156:159], v[216:219], v[110:113]
	v_mfma_f32_16x16x32_bf16 v[106:109], v[164:167], v[216:219], v[106:109]
	v_mfma_f32_16x16x32_bf16 v[94:97], v[156:159], v[224:227], v[94:97]
	v_mfma_f32_16x16x32_bf16 v[90:93], v[164:167], v[224:227], v[90:93]
	v_mfma_f32_16x16x32_bf16 v[78:81], v[156:159], v[232:235], v[78:81]
	v_mfma_f32_16x16x32_bf16 v[74:77], v[164:167], v[232:235], v[74:77]
	v_mfma_f32_16x16x32_bf16 v[126:129], v[160:163], v[212:215], v[126:129]
	v_mfma_f32_16x16x32_bf16 v[122:125], v[178:181], v[212:215], v[122:125]
	v_mfma_f32_16x16x32_bf16 v[110:113], v[160:163], v[220:223], v[110:113]
	v_mfma_f32_16x16x32_bf16 v[106:109], v[178:181], v[220:223], v[106:109]
	v_mfma_f32_16x16x32_bf16 v[94:97], v[160:163], v[228:231], v[94:97]
	v_mfma_f32_16x16x32_bf16 v[90:93], v[178:181], v[228:231], v[90:93]
	v_mfma_f32_16x16x32_bf16 v[78:81], v[160:163], v[236:239], v[78:81]
	v_mfma_f32_16x16x32_bf16 v[74:77], v[178:181], v[236:239], v[74:77]
	v_mfma_f32_16x16x32_bf16 v[118:121], v[182:185], v[198:201], v[118:121]
	v_mfma_f32_16x16x32_bf16 v[114:117], v[190:193], v[198:201], v[114:117]
	v_mfma_f32_16x16x32_bf16 v[102:105], v[182:185], v[216:219], v[102:105]
	v_mfma_f32_16x16x32_bf16 v[98:101], v[190:193], v[216:219], v[98:101]
	v_mfma_f32_16x16x32_bf16 v[86:89], v[182:185], v[224:227], v[86:89]
	v_mfma_f32_16x16x32_bf16 v[82:85], v[190:193], v[224:227], v[82:85]
	v_mfma_f32_16x16x32_bf16 v[70:73], v[182:185], v[232:235], v[70:73]
	v_mfma_f32_16x16x32_bf16 v[66:69], v[190:193], v[232:235], v[66:69]
	v_mfma_f32_16x16x32_bf16 v[118:121], v[186:189], v[212:215], v[118:121]
	v_mfma_f32_16x16x32_bf16 v[114:117], v[194:197], v[212:215], v[114:117]
	v_mfma_f32_16x16x32_bf16 v[102:105], v[186:189], v[220:223], v[102:105]
	v_mfma_f32_16x16x32_bf16 v[98:101], v[194:197], v[220:223], v[98:101]
	v_mfma_f32_16x16x32_bf16 v[86:89], v[186:189], v[228:231], v[86:89]
	v_mfma_f32_16x16x32_bf16 v[82:85], v[194:197], v[228:231], v[82:85]
	v_mfma_f32_16x16x32_bf16 v[70:73], v[186:189], v[236:239], v[70:73]
	v_mfma_f32_16x16x32_bf16 v[66:69], v[194:197], v[236:239], v[66:69]
	s_setprio 0
	s_barrier
; #define PG8_STAGE(bufoff, gbase, voff) do { _Pragma("unroll") for (int _i = 0; _i < 2; ++_i) \
;         __builtin_amdgcn_global_load_lds((const unsigned*)((const char*)(gbase) + (voff)[_i]), (LAS unsigned*)(lds + (bufoff) + ldsw + _i * 8192), 16, 0, 0); } while (0)
; #define PG8_LDA(dst, b, h) do { _Pragma("unroll") for (int m = 0; m < 4; ++m) _Pragma("unroll") for (int k = 0; k < 2; ++k) dst[m][k] = *(const LAS bf16x8*)(lds + PG8_SA(b, h) + aoff + m * 2048 + k * 1024); } while (0)
; #define PG8_MMA(ai, bj, At, Bt) do { __builtin_amdgcn_s_setprio(1); _Pragma("unroll") for (int m = 0; m < 4; ++m) _Pragma("unroll") for (int n = 0; n < 2; ++n) _Pragma("unroll") for (int k = 0; k < 2; ++k) \
;         acc[ai][bj][m][n] = __builtin_amdgcn_mfma_f32_16x16x32_bf16(Bt[n][k], At[m][k], acc[ai][bj][m][n], 0, 0, 0); __builtin_amdgcn_s_setprio(0); } while (0)
; #define PG8_WAIT_V(n) asm volatile("s_waitcnt vmcnt(" #n ")" ::: "memory")
; #define PG8_WAIT_L(n) asm volatile("s_waitcnt lgkmcnt(" #n ")" ::: "memory")
; #define PG8_BAR __builtin_amdgcn_s_barrier()
; #define PG8_SCHED __builtin_amdgcn_sched_barrier(0)
; template <class Epi>
; __device__ __forceinline__ void gemm_phase(LAS unsigned char* lds, const Gemm g, const StaticOrder& S, const Epi& E, const int tid) {
;     ...
;         for (int t = 0; t < ntt; t += 2) {
;             const bool last = (t == ntt - 2);
;             const bool s1 = Epi::TWO && (t >= nt), s2 = Epi::TWO && (t + 2 >= nt);
;     ...
;             PG8_LDA(At, 1, 1); PG8_STAGE(PG8_SB(1, 0), b3, voffB); PG8_STAGE(PG8_SB(1, 1), b3 + bhs, voffB); PG8_STAGE(PG8_SA(1, 0), a3, voffA);
;             PG8_WAIT_V(8); PG8_WAIT_L(0); PG8_BAR; PG8_MMA(1, 0, At, B0); PG8_MMA(1, 1, At, B1); PG8_BAR; PG8_SCHED;
	s_add_i32 s34, s49, s36
	v_lshl_add_u64 v[142:143], v[142:143], 0, s[70:71]
	s_mov_b32 m0, s34
	ds_read_b128 v[198:201], v154 offset:49152
	global_load_lds_dwordx4 v[142:143], off
	ds_read_b128 v[212:215], v154 offset:50176
	ds_read_b128 v[216:219], v154 offset:51200
	s_add_i32 m0, s34, 0x2000
	s_add_u32 s30, s30, 0x8080
	v_lshl_add_u64 v[142:143], v[168:169], 0, s[70:71]
	s_addc_u32 s31, s31, 0
	s_add_i32 s34, s50, s36
	global_load_lds_dwordx4 v[142:143], off
	ds_read_b128 v[220:223], v154 offset:52224
	ds_read_b128 v[224:227], v154 offset:53248
	s_mov_b32 m0, s34
	v_lshl_add_u64 v[142:143], s[30:31], 0, v[0:1]
	global_load_lds_dwordx4 v[142:143], off
	ds_read_b128 v[228:231], v154 offset:54272
	ds_read_b128 v[232:235], v154 offset:55296
	s_add_i32 m0, s34, 0x2000
	v_lshl_add_u64 v[142:143], s[30:31], 0, v[134:135]
	global_load_lds_dwordx4 v[142:143], off
	ds_read_b128 v[236:239], v154 offset:56320
	s_mov_b32 m0, s39
	v_lshl_add_u64 v[142:143], v[172:173], 0, s[70:71]
	global_load_lds_dwordx4 v[142:143], off
	s_mov_b32 m0, s40
	v_lshl_add_u64 v[142:143], v[174:175], 0, s[70:71]
	global_load_lds_dwordx4 v[142:143], off
	s_waitcnt vmcnt(8)
	s_waitcnt lgkmcnt(0)
	s_barrier
	s_setprio 1
	v_mfma_f32_16x16x32_bf16 v[62:65], v[156:159], v[198:201], v[62:65]
	v_mfma_f32_16x16x32_bf16 v[58:61], v[164:167], v[198:201], v[58:61]
	v_mfma_f32_16x16x32_bf16 v[46:49], v[156:159], v[216:219], v[46:49]
	v_mfma_f32_16x16x32_bf16 v[42:45], v[164:167], v[216:219], v[42:45]
	v_mfma_f32_16x16x32_bf16 v[30:33], v[156:159], v[224:227], v[30:33]
	v_mfma_f32_16x16x32_bf16 v[26:29], v[164:167], v[224:227], v[26:29]
	v_mfma_f32_16x16x32_bf16 v[14:17], v[156:159], v[232:235], v[14:17]
	v_mfma_f32_16x16x32_bf16 v[10:13], v[164:167], v[232:235], v[10:13]
	v_mfma_f32_16x16x32_bf16 v[62:65], v[160:163], v[212:215], v[62:65]
	v_mfma_f32_16x16x32_bf16 v[58:61], v[178:181], v[212:215], v[58:61]
	v_mfma_f32_16x16x32_bf16 v[46:49], v[160:163], v[220:223], v[46:49]
	v_mfma_f32_16x16x32_bf16 v[42:45], v[178:181], v[220:223], v[42:45]
	v_mfma_f32_16x16x32_bf16 v[30:33], v[160:163], v[228:231], v[30:33]
	v_mfma_f32_16x16x32_bf16 v[26:29], v[178:181], v[228:231], v[26:29]
	v_mfma_f32_16x16x32_bf16 v[14:17], v[160:163], v[236:239], v[14:17]
	v_mfma_f32_16x16x32_bf16 v[10:13], v[178:181], v[236:239], v[10:13]
	v_mfma_f32_16x16x32_bf16 v[54:57], v[182:185], v[198:201], v[54:57]
	v_mfma_f32_16x16x32_bf16 v[50:53], v[190:193], v[198:201], v[50:53]
	v_mfma_f32_16x16x32_bf16 v[38:41], v[182:185], v[216:219], v[38:41]
	v_mfma_f32_16x16x32_bf16 v[34:37], v[190:193], v[216:219], v[34:37]
	v_mfma_f32_16x16x32_bf16 v[22:25], v[182:185], v[224:227], v[22:25]
	v_mfma_f32_16x16x32_bf16 v[18:21], v[190:193], v[224:227], v[18:21]
	v_mfma_f32_16x16x32_bf16 v[6:9], v[182:185], v[232:235], v[6:9]
	v_mfma_f32_16x16x32_bf16 v[2:5], v[190:193], v[232:235], v[2:5]
	v_mfma_f32_16x16x32_bf16 v[54:57], v[186:189], v[212:215], v[54:57]
	v_mfma_f32_16x16x32_bf16 v[50:53], v[194:197], v[212:215], v[50:53]
	v_mfma_f32_16x16x32_bf16 v[38:41], v[186:189], v[220:223], v[38:41]
	v_mfma_f32_16x16x32_bf16 v[34:37], v[194:197], v[220:223], v[34:37]
	v_mfma_f32_16x16x32_bf16 v[22:25], v[186:189], v[228:231], v[22:25]
	v_mfma_f32_16x16x32_bf16 v[18:21], v[194:197], v[228:231], v[18:21]
	v_mfma_f32_16x16x32_bf16 v[6:9], v[186:189], v[236:239], v[6:9]
	v_mfma_f32_16x16x32_bf16 v[2:5], v[194:197], v[236:239], v[2:5]
	s_setprio 0
	s_barrier
	s_add_i32 s48, s48, 2
	s_add_u32 s46, s46, 0x100
	s_addc_u32 s47, s47, 0
	s_add_u32 s28, s28, 0x100
	s_addc_u32 s29, s29, 0
	s_cmp_gt_u32 s48, 29
	s_cbranch_scc0 .LBB0_261
	s_and_b64 vcc, exec, s[14:15]
	s_cbranch_vccz .LBB0_264
	s_barrier

; #define PG8_STAGE(bufoff, gbase, voff) do { _Pragma("unroll") for (int _i = 0; _i < 2; ++_i) \
;         __builtin_amdgcn_global_load_lds((const unsigned*)((const char*)(gbase) + (voff)[_i]), (LAS unsigned*)(lds + (bufoff) + ldsw + _i * 8192), 16, 0, 0); } while (0)
; #define PG8_LDA(dst, b, h) do { _Pragma("unroll") for (int m = 0; m < 4; ++m) _Pragma("unroll") for (int k = 0; k < 2; ++k) dst[m][k] = *(const LAS bf16x8*)(lds + PG8_SA(b, h) + aoff + m * 2048 + k * 1024); } while (0)
; #define PG8_LDB(dst, b, h) do { _Pragma("unroll") for (int n = 0; n < 2; ++n) _Pragma("unroll") for (int k = 0; k < 2; ++k) dst[n][k] = *(const LAS bf16x8*)(lds + PG8_SB(b, h) + boff + n * 2048 + k * 1024); } while (0)
; template <class Epi>
; __device__ __forceinline__ void gemm_phase(LAS unsigned char* lds, const Gemm g, const StaticOrder& S, const Epi& E, const int tid) {
;     ...
;         for (int t = 0; t < ntt; t += 2) {
;             const bool last = (t == ntt - 2);
;             const bool s1 = Epi::TWO && (t >= nt), s2 = Epi::TWO && (t + 2 >= nt);
;             const char* a1 = (s1 ? cA2 + (size_t)(t - nt + 1) * kstep : cA + (size_t)(t + 1) * kstep);
;             const char* a2 = last ? nA : (s2 ? cA2 + (size_t)(t + 2 - nt) * kstep : cA + (size_t)(t + 2) * kstep);
;             const char* b2 = last ? nB : (s2 ? cB2 + (size_t)(t + 2 - nt) * kstep : cB + (size_t)(t + 2) * kstep);
;             const char* a3 = a2 + kstep; const char* b3 = b2 + kstep;
;             if constexpr (Epi::TWO) { if (t == nt) E.mid(acc, cur, wr, wc, fr, fq); }
;             if constexpr (SP2) {
;             PG8_LDB(B0, 0, 0); PG8_LDB(B1, 0, 1); PG8_SCHED; PG8_LDA(At, 0, 0); PG8_STAGE(PG8_SA(1, 1), a1 + hstep, voffA);
;             PG8_WAIT_V(8); PG8_WAIT_L(0); PG8_BAR; PG8_MMA(0, 0, At, B0); PG8_MMA(0, 1, At, B1); PG8_BAR; PG8_SCHED;
;             PG8_LDA(At, 0, 1); PG8_STAGE(PG8_SB(0, 0), b2, voffB); PG8_STAGE(PG8_SB(0, 1), b2 + bhs, voffB); PG8_STAGE(PG8_SA(0, 0), a2, voffA);
;             PG8_WAIT_V(8); PG8_WAIT_L(0); PG8_BAR; PG8_MMA(1, 0, At, B0); PG8_MMA(1, 1, At, B1); PG8_BAR; PG8_SCHED;
;     ...
; #pragma unroll
;         for (int a = 0; a < 2; ++a)
; #pragma unroll
;             for (int b = 0; b < 2; ++b)
; #pragma unroll
;                 for (int m = 0; m < 4; ++m)
; #pragma unroll
;                     for (int n = 0; n < 2; ++n) acc[a][b][m][n] = (f32x4){0.f, 0.f, 0.f, 0.f};
.LBB0_314:
	s_add_u32 s40, s6, 0xfff80080
	s_addc_u32 s41, s7, -1
	s_add_i32 s56, 0, 0x10000
	s_cmp_eq_u32 s55, 28
	s_cselect_b32 s43, s27, s41
	s_cselect_b32 s42, s39, s40
	s_cselect_b32 s41, s25, s54
	s_cselect_b32 s40, s52, s53
	s_add_i32 s58, 0, 0x14000
	v_add_u32_e32 v46, s56, v212
	v_add_u32_e32 v70, s58, v212
	ds_read_b128 v[34:37], v46
	ds_read_b128 v[38:41], v46 offset:1024
	ds_read_b128 v[42:45], v46 offset:2048
	ds_read_b128 v[46:49], v46 offset:3072
	ds_read_b128 v[58:61], v70
	ds_read_b128 v[62:65], v70 offset:1024
	ds_read_b128 v[66:69], v70 offset:2048
	ds_read_b128 v[70:73], v70 offset:3072
	v_lshl_add_u64 v[172:173], s[6:7], 0, v[188:189]
	s_add_i32 m0, s44, 0xc000
	ds_read_b128 v[162:165], v220
	global_load_lds_dwordx4 v[172:173], off
	ds_read_b128 v[166:169], v220 offset:1024
	ds_read_b128 v[190:193], v220 offset:2048
	s_add_i32 m0, s44, 0xe000
	v_lshl_add_u64 v[172:173], s[6:7], 0, v[186:187]
	global_load_lds_dwordx4 v[172:173], off
	ds_read_b128 v[194:197], v220 offset:3072
	ds_read_b128 v[198:201], v220 offset:4096
	ds_read_b128 v[222:225], v220 offset:5120
	ds_read_b128 v[226:229], v220 offset:6144
	ds_read_b128 v[230:233], v220 offset:7168
	s_waitcnt vmcnt(8)
	s_waitcnt lgkmcnt(0)
	s_barrier
	s_setprio 1
	v_mfma_f32_16x16x32_bf16 v[158:161], v[34:37], v[162:165], v[158:161]
	v_mfma_f32_16x16x32_bf16 v[154:157], v[42:45], v[162:165], v[154:157]
	v_mfma_f32_16x16x32_bf16 v[142:145], v[34:37], v[190:193], v[142:145]
	v_mfma_f32_16x16x32_bf16 v[138:141], v[42:45], v[190:193], v[138:141]
	v_mfma_f32_16x16x32_bf16 v[126:129], v[34:37], v[198:201], v[126:129]
	v_mfma_f32_16x16x32_bf16 v[122:125], v[42:45], v[198:201], v[122:125]
	v_mfma_f32_16x16x32_bf16 v[110:113], v[34:37], v[226:229], v[110:113]
	v_mfma_f32_16x16x32_bf16 v[106:109], v[42:45], v[226:229], v[106:109]
	v_mfma_f32_16x16x32_bf16 v[158:161], v[38:41], v[166:169], v[158:161]
	v_mfma_f32_16x16x32_bf16 v[154:157], v[46:49], v[166:169], v[154:157]
	v_mfma_f32_16x16x32_bf16 v[142:145], v[38:41], v[194:197], v[142:145]
	v_mfma_f32_16x16x32_bf16 v[138:141], v[46:49], v[194:197], v[138:141]
	v_mfma_f32_16x16x32_bf16 v[126:129], v[38:41], v[222:225], v[126:129]
	v_mfma_f32_16x16x32_bf16 v[122:125], v[46:49], v[222:225], v[122:125]
	v_mfma_f32_16x16x32_bf16 v[110:113], v[38:41], v[230:233], v[110:113]
	v_mfma_f32_16x16x32_bf16 v[106:109], v[46:49], v[230:233], v[106:109]
	v_mfma_f32_16x16x32_bf16 v[150:153], v[58:61], v[162:165], v[150:153]
	v_mfma_f32_16x16x32_bf16 v[146:149], v[66:69], v[162:165], v[146:149]
	v_mfma_f32_16x16x32_bf16 v[134:137], v[58:61], v[190:193], v[134:137]
	v_mfma_f32_16x16x32_bf16 v[130:133], v[66:69], v[190:193], v[130:133]
	v_mfma_f32_16x16x32_bf16 v[118:121], v[58:61], v[198:201], v[118:121]
	v_mfma_f32_16x16x32_bf16 v[114:117], v[66:69], v[198:201], v[114:117]
	v_mfma_f32_16x16x32_bf16 v[102:105], v[58:61], v[226:229], v[102:105]
	v_mfma_f32_16x16x32_bf16 v[98:101], v[66:69], v[226:229], v[98:101]
	v_mfma_f32_16x16x32_bf16 v[150:153], v[62:65], v[166:169], v[150:153]
	v_mfma_f32_16x16x32_bf16 v[146:149], v[70:73], v[166:169], v[146:149]
	v_mfma_f32_16x16x32_bf16 v[134:137], v[62:65], v[194:197], v[134:137]
	v_mfma_f32_16x16x32_bf16 v[130:133], v[70:73], v[194:197], v[130:133]
	v_mfma_f32_16x16x32_bf16 v[118:121], v[62:65], v[222:225], v[118:121]
	v_mfma_f32_16x16x32_bf16 v[114:117], v[70:73], v[222:225], v[114:117]
	v_mfma_f32_16x16x32_bf16 v[102:105], v[62:65], v[230:233], v[102:105]
	v_mfma_f32_16x16x32_bf16 v[98:101], v[70:73], v[230:233], v[98:101]
	s_setprio 0
	s_barrier
	s_add_i32 s56, s56, s33
	v_lshl_add_u64 v[172:173], s[40:41], 0, v[0:1]
	s_mov_b32 m0, s56
	ds_read_b128 v[162:165], v220 offset:16384
	global_load_lds_dwordx4 v[172:173], off
	ds_read_b128 v[166:169], v220 offset:17408
	ds_read_b128 v[190:193], v220 offset:18432
	s_add_i32 m0, s56, 0x2000
	s_add_u32 s56, s40, 0x8000
	v_lshl_add_u64 v[174:175], s[40:41], 0, v[182:183]
	s_addc_u32 s57, s41, 0
	s_add_i32 s58, s58, s33
	global_load_lds_dwordx4 v[174:175], off
	ds_read_b128 v[194:197], v220 offset:19456
	ds_read_b128 v[198:201], v220 offset:20480
	v_lshl_add_u64 v[176:177], s[56:57], 0, v[0:1]
	s_mov_b32 m0, s58
	v_lshl_add_u64 v[238:239], s[42:43], 0, v[180:181]
	global_load_lds_dwordx4 v[176:177], off
	ds_read_b128 v[222:225], v220 offset:21504
	ds_read_b128 v[226:229], v220 offset:22528
	s_add_i32 m0, s58, 0x2000
	v_lshl_add_u64 v[176:177], s[56:57], 0, v[182:183]
	global_load_lds_dwordx4 v[176:177], off
	ds_read_b128 v[230:233], v220 offset:23552
	s_mov_b32 m0, s44
	v_lshl_add_u64 v[176:177], s[42:43], 0, v[178:179]
	global_load_lds_dwordx4 v[176:177], off
	s_mov_b32 m0, s45
	s_nop 0
	global_load_lds_dwordx4 v[238:239], off
	s_waitcnt vmcnt(8)
	s_waitcnt lgkmcnt(0)
	s_barrier
; #define PG8_STAGE(bufoff, gbase, voff) do { _Pragma("unroll") for (int _i = 0; _i < 2; ++_i) \
;         __builtin_amdgcn_global_load_lds((const unsigned*)((const char*)(gbase) + (voff)[_i]), (LAS unsigned*)(lds + (bufoff) + ldsw + _i * 8192), 16, 0, 0); } while (0)
; #define PG8_LDA(dst, b, h) do { _Pragma("unroll") for (int m = 0; m < 4; ++m) _Pragma("unroll") for (int k = 0; k < 2; ++k) dst[m][k] = *(const LAS bf16x8*)(lds + PG8_SA(b, h) + aoff + m * 2048 + k * 1024); } while (0)
; #define PG8_LDB(dst, b, h) do { _Pragma("unroll") for (int n = 0; n < 2; ++n) _Pragma("unroll") for (int k = 0; k < 2; ++k) dst[n][k] = *(const LAS bf16x8*)(lds + PG8_SB(b, h) + boff + n * 2048 + k * 1024); } while (0)
; #define PG8_MMA(ai, bj, At, Bt) do { __builtin_amdgcn_s_setprio(1); _Pragma("unroll") for (int m = 0; m < 4; ++m) _Pragma("unroll") for (int n = 0; n < 2; ++n) _Pragma("unroll") for (int k = 0; k < 2; ++k) \
;         acc[ai][bj][m][n] = __builtin_amdgcn_mfma_f32_16x16x32_bf16(Bt[n][k], At[m][k], acc[ai][bj][m][n], 0, 0, 0); __builtin_amdgcn_s_setprio(0); } while (0)
; #define PG8_WAIT_V(n) asm volatile("s_waitcnt vmcnt(" #n ")" ::: "memory")
; #define PG8_WAIT_L(n) asm volatile("s_waitcnt lgkmcnt(" #n ")" ::: "memory")
; #define PG8_BAR __builtin_amdgcn_s_barrier()
; #define PG8_SCHED __builtin_amdgcn_sched_barrier(0)
; template <class Epi>
; __device__ __forceinline__ void gemm_phase(LAS unsigned char* lds, const Gemm g, const StaticOrder& S, const Epi& E, const int tid) {
;     ...
;             PG8_WAIT_V(8); PG8_WAIT_L(0); PG8_BAR; PG8_MMA(0, 0, At, B0); PG8_MMA(0, 1, At, B1); PG8_BAR; PG8_SCHED;
;             PG8_LDA(At, 0, 1); PG8_STAGE(PG8_SB(0, 0), b2, voffB); PG8_STAGE(PG8_SB(0, 1), b2 + bhs, voffB); PG8_STAGE(PG8_SA(0, 0), a2, voffA);
;             PG8_WAIT_V(8); PG8_WAIT_L(0); PG8_BAR; PG8_MMA(1, 0, At, B0); PG8_MMA(1, 1, At, B1); PG8_BAR; PG8_SCHED;
;             PG8_LDB(B0, 1, 0); PG8_LDB(B1, 1, 1); PG8_SCHED; PG8_LDA(At, 1, 0); PG8_STAGE(PG8_SA(0, 1), a2 + hstep, voffA);
;             PG8_WAIT_V(8); PG8_WAIT_L(0); PG8_BAR; PG8_MMA(0, 0, At, B0); PG8_MMA(0, 1, At, B1); PG8_BAR; PG8_SCHED;
	s_setprio 1
	v_mfma_f32_16x16x32_bf16 v[94:97], v[34:37], v[162:165], v[94:97]
	v_mfma_f32_16x16x32_bf16 v[90:93], v[42:45], v[162:165], v[90:93]
	v_mfma_f32_16x16x32_bf16 v[78:81], v[34:37], v[190:193], v[78:81]
	v_mfma_f32_16x16x32_bf16 v[74:77], v[42:45], v[190:193], v[74:77]
	v_mfma_f32_16x16x32_bf16 v[30:33], v[34:37], v[198:201], v[30:33]
	v_mfma_f32_16x16x32_bf16 v[26:29], v[42:45], v[198:201], v[26:29]
	v_mfma_f32_16x16x32_bf16 v[14:17], v[34:37], v[226:229], v[14:17]
	v_mfma_f32_16x16x32_bf16 v[10:13], v[42:45], v[226:229], v[10:13]
	v_mfma_f32_16x16x32_bf16 v[94:97], v[38:41], v[166:169], v[94:97]
	v_mfma_f32_16x16x32_bf16 v[90:93], v[46:49], v[166:169], v[90:93]
	v_mfma_f32_16x16x32_bf16 v[78:81], v[38:41], v[194:197], v[78:81]
	v_mfma_f32_16x16x32_bf16 v[74:77], v[46:49], v[194:197], v[74:77]
	v_mfma_f32_16x16x32_bf16 v[30:33], v[38:41], v[222:225], v[30:33]
	v_mfma_f32_16x16x32_bf16 v[26:29], v[46:49], v[222:225], v[26:29]
	v_mfma_f32_16x16x32_bf16 v[14:17], v[38:41], v[230:233], v[14:17]
	v_mfma_f32_16x16x32_bf16 v[10:13], v[46:49], v[230:233], v[10:13]
	v_mfma_f32_16x16x32_bf16 v[22:25], v[58:61], v[198:201], v[22:25]
	v_mfma_f32_16x16x32_bf16 v[18:21], v[66:69], v[198:201], v[18:21]
	v_mfma_f32_16x16x32_bf16 v[6:9], v[58:61], v[226:229], v[6:9]
	v_mfma_f32_16x16x32_bf16 v[2:5], v[66:69], v[226:229], v[2:5]
	v_mfma_f32_16x16x32_bf16 v[34:37], v[58:61], v[162:165], v[86:89]
	v_mfma_f32_16x16x32_bf16 v[38:41], v[66:69], v[162:165], v[82:85]
	v_mfma_f32_16x16x32_bf16 v[42:45], v[58:61], v[190:193], v[54:57]
	v_mfma_f32_16x16x32_bf16 v[46:49], v[66:69], v[190:193], v[50:53]
	v_mfma_f32_16x16x32_bf16 v[22:25], v[62:65], v[222:225], v[22:25]
	v_mfma_f32_16x16x32_bf16 v[18:21], v[70:73], v[222:225], v[18:21]
	v_mfma_f32_16x16x32_bf16 v[6:9], v[62:65], v[230:233], v[6:9]
	v_mfma_f32_16x16x32_bf16 v[2:5], v[70:73], v[230:233], v[2:5]
	v_mfma_f32_16x16x32_bf16 v[34:37], v[62:65], v[166:169], v[34:37]
	v_mfma_f32_16x16x32_bf16 v[38:41], v[70:73], v[166:169], v[38:41]
	v_mfma_f32_16x16x32_bf16 v[42:45], v[62:65], v[194:197], v[42:45]
	v_mfma_f32_16x16x32_bf16 v[46:49], v[70:73], v[194:197], v[46:49]
	s_setprio 0
	s_barrier
	s_add_i32 s56, 0, 0x18000
	s_add_i32 s57, 0, 0x1c000
	v_add_u32_e32 v62, s56, v212
	v_add_u32_e32 v82, s57, v212
	ds_read_b128 v[50:53], v62
	ds_read_b128 v[54:57], v62 offset:1024
	ds_read_b128 v[58:61], v62 offset:2048
	ds_read_b128 v[62:65], v62 offset:3072
	ds_read_b128 v[66:69], v82
	ds_read_b128 v[70:73], v82 offset:1024
	ds_read_b128 v[162:165], v82 offset:2048
	ds_read_b128 v[166:169], v82 offset:3072
	s_add_u32 s42, s42, 0x80000
	s_addc_u32 s43, s43, 0
	s_mov_b32 m0, s46
	v_lshl_add_u64 v[234:235], s[42:43], 0, v[178:179]
	ds_read_b128 v[82:85], v220 offset:32768
	global_load_lds_dwordx4 v[234:235], off
	ds_read_b128 v[86:89], v220 offset:33792
	ds_read_b128 v[190:193], v220 offset:34816
	s_mov_b32 m0, s47
	v_lshl_add_u64 v[234:235], s[42:43], 0, v[180:181]
	global_load_lds_dwordx4 v[234:235], off
	ds_read_b128 v[194:197], v220 offset:35840
	ds_read_b128 v[198:201], v220 offset:36864
	ds_read_b128 v[222:225], v220 offset:37888
	ds_read_b128 v[226:229], v220 offset:38912
	ds_read_b128 v[230:233], v220 offset:39936
	s_waitcnt vmcnt(8)
	s_waitcnt lgkmcnt(0)
	s_barrier
	s_setprio 1
	v_mfma_f32_16x16x32_bf16 v[158:161], v[50:53], v[82:85], v[158:161]
	v_mfma_f32_16x16x32_bf16 v[154:157], v[58:61], v[82:85], v[154:157]
	v_mfma_f32_16x16x32_bf16 v[142:145], v[50:53], v[190:193], v[142:145]
	v_mfma_f32_16x16x32_bf16 v[138:141], v[58:61], v[190:193], v[138:141]
	v_mfma_f32_16x16x32_bf16 v[126:129], v[50:53], v[198:201], v[126:129]
	v_mfma_f32_16x16x32_bf16 v[122:125], v[58:61], v[198:201], v[122:125]
	v_mfma_f32_16x16x32_bf16 v[110:113], v[50:53], v[226:229], v[110:113]
	v_mfma_f32_16x16x32_bf16 v[106:109], v[58:61], v[226:229], v[106:109]
	v_mfma_f32_16x16x32_bf16 v[158:161], v[54:57], v[86:89], v[158:161]
	v_mfma_f32_16x16x32_bf16 v[154:157], v[62:65], v[86:89], v[154:157]
	v_mfma_f32_16x16x32_bf16 v[142:145], v[54:57], v[194:197], v[142:145]
	v_mfma_f32_16x16x32_bf16 v[138:141], v[62:65], v[194:197], v[138:141]
	v_mfma_f32_16x16x32_bf16 v[126:129], v[54:57], v[222:225], v[126:129]
	v_mfma_f32_16x16x32_bf16 v[122:125], v[62:65], v[222:225], v[122:125]
	v_mfma_f32_16x16x32_bf16 v[110:113], v[54:57], v[230:233], v[110:113]
	v_mfma_f32_16x16x32_bf16 v[106:109], v[62:65], v[230:233], v[106:109]
	v_mfma_f32_16x16x32_bf16 v[150:153], v[66:69], v[82:85], v[150:153]
	v_mfma_f32_16x16x32_bf16 v[82:85], v[162:165], v[82:85], v[146:149]
	v_mfma_f32_16x16x32_bf16 v[146:149], v[166:169], v[86:89], v[82:85]
	v_mfma_f32_16x16x32_bf16 v[82:85], v[66:69], v[190:193], v[134:137]
	v_mfma_f32_16x16x32_bf16 v[134:137], v[70:73], v[194:197], v[82:85]
	v_mfma_f32_16x16x32_bf16 v[82:85], v[162:165], v[190:193], v[130:133]
	v_mfma_f32_16x16x32_bf16 v[130:133], v[166:169], v[194:197], v[82:85]
	v_mfma_f32_16x16x32_bf16 v[82:85], v[66:69], v[198:201], v[118:121]
	v_mfma_f32_16x16x32_bf16 v[118:121], v[70:73], v[222:225], v[82:85]
	v_mfma_f32_16x16x32_bf16 v[82:85], v[162:165], v[198:201], v[114:117]
	v_mfma_f32_16x16x32_bf16 v[114:117], v[166:169], v[222:225], v[82:85]
	v_mfma_f32_16x16x32_bf16 v[82:85], v[66:69], v[226:229], v[102:105]
	v_mfma_f32_16x16x32_bf16 v[102:105], v[70:73], v[230:233], v[82:85]
	v_mfma_f32_16x16x32_bf16 v[82:85], v[162:165], v[226:229], v[98:101]
	v_mfma_f32_16x16x32_bf16 v[150:153], v[70:73], v[86:89], v[150:153]
	v_mfma_f32_16x16x32_bf16 v[98:101], v[166:169], v[230:233], v[82:85]
	s_setprio 0
	s_barrier
; #define PG8_STAGE(bufoff, gbase, voff) do { _Pragma("unroll") for (int _i = 0; _i < 2; ++_i) \
;         __builtin_amdgcn_global_load_lds((const unsigned*)((const char*)(gbase) + (voff)[_i]), (LAS unsigned*)(lds + (bufoff) + ldsw + _i * 8192), 16, 0, 0); } while (0)
; #define PG8_LDA(dst, b, h) do { _Pragma("unroll") for (int m = 0; m < 4; ++m) _Pragma("unroll") for (int k = 0; k < 2; ++k) dst[m][k] = *(const LAS bf16x8*)(lds + PG8_SA(b, h) + aoff + m * 2048 + k * 1024); } while (0)
; #define PG8_MMA(ai, bj, At, Bt) do { __builtin_amdgcn_s_setprio(1); _Pragma("unroll") for (int m = 0; m < 4; ++m) _Pragma("unroll") for (int n = 0; n < 2; ++n) _Pragma("unroll") for (int k = 0; k < 2; ++k) \
;         acc[ai][bj][m][n] = __builtin_amdgcn_mfma_f32_16x16x32_bf16(Bt[n][k], At[m][k], acc[ai][bj][m][n], 0, 0, 0); __builtin_amdgcn_s_setprio(0); } while (0)
; #define PG8_WAIT_V(n) asm volatile("s_waitcnt vmcnt(" #n ")" ::: "memory")
; #define PG8_WAIT_L(n) asm volatile("s_waitcnt lgkmcnt(" #n ")" ::: "memory")
; #define PG8_BAR __builtin_amdgcn_s_barrier()
; #define PG8_SCHED __builtin_amdgcn_sched_barrier(0)
; template <class Epi>
; __device__ __forceinline__ void gemm_phase(LAS unsigned char* lds, const Gemm g, const StaticOrder& S, const Epi& E, const int tid) {
;     ...
;             PG8_LDA(At, 1, 1); PG8_STAGE(PG8_SB(1, 0), b3, voffB); PG8_STAGE(PG8_SB(1, 1), b3 + bhs, voffB); PG8_STAGE(PG8_SA(1, 0), a3, voffA);
;             PG8_WAIT_V(8); PG8_WAIT_L(0); PG8_BAR; PG8_MMA(1, 0, At, B0); PG8_MMA(1, 1, At, B1); PG8_BAR; PG8_SCHED;
;     ...
;         if (ALIGN_EPI) { if (wr == 0) PG8_BAR; }
	s_add_i32 s42, s56, s33
	v_lshl_add_u64 v[86:87], v[172:173], 0, s[70:71]
	s_mov_b32 m0, s42
	s_nop 0
	ds_read_b128 v[82:85], v220 offset:49152
	global_load_lds_dwordx4 v[86:87], off
	ds_read_b128 v[190:193], v220 offset:50176
	ds_read_b128 v[194:197], v220 offset:51200
	s_add_i32 m0, s42, 0x2000
	s_add_u32 s40, s40, 0x8080
	v_lshl_add_u64 v[86:87], v[174:175], 0, s[70:71]
	s_addc_u32 s41, s41, 0
	s_add_i32 s42, s57, s33
	global_load_lds_dwordx4 v[86:87], off
	ds_read_b128 v[198:201], v220 offset:52224
	ds_read_b128 v[222:225], v220 offset:53248
	s_mov_b32 m0, s42
	v_lshl_add_u64 v[86:87], s[40:41], 0, v[0:1]
	global_load_lds_dwordx4 v[86:87], off
	ds_read_b128 v[226:229], v220 offset:54272
	ds_read_b128 v[230:233], v220 offset:55296
	s_add_i32 m0, s42, 0x2000
	v_lshl_add_u64 v[86:87], s[40:41], 0, v[182:183]
	global_load_lds_dwordx4 v[86:87], off
	ds_read_b128 v[234:237], v220 offset:56320
	s_mov_b32 m0, s48
	v_lshl_add_u64 v[86:87], v[176:177], 0, s[70:71]
	global_load_lds_dwordx4 v[86:87], off
	s_mov_b32 m0, s49
	v_lshl_add_u64 v[86:87], v[238:239], 0, s[70:71]
	global_load_lds_dwordx4 v[86:87], off
	s_waitcnt vmcnt(8)
	s_waitcnt lgkmcnt(0)
	s_barrier
	s_setprio 1
	v_mfma_f32_16x16x32_bf16 v[86:89], v[50:53], v[82:85], v[94:97]
	v_mfma_f32_16x16x32_bf16 v[94:97], v[54:57], v[190:193], v[86:89]
	v_mfma_f32_16x16x32_bf16 v[86:89], v[58:61], v[82:85], v[90:93]
	v_mfma_f32_16x16x32_bf16 v[78:81], v[50:53], v[194:197], v[78:81]
	v_mfma_f32_16x16x32_bf16 v[74:77], v[58:61], v[194:197], v[74:77]
	v_mfma_f32_16x16x32_bf16 v[30:33], v[50:53], v[222:225], v[30:33]
	v_mfma_f32_16x16x32_bf16 v[26:29], v[58:61], v[222:225], v[26:29]
	v_mfma_f32_16x16x32_bf16 v[14:17], v[50:53], v[230:233], v[14:17]
	v_mfma_f32_16x16x32_bf16 v[10:13], v[58:61], v[230:233], v[10:13]
	v_mfma_f32_16x16x32_bf16 v[90:93], v[62:65], v[190:193], v[86:89]
	v_mfma_f32_16x16x32_bf16 v[78:81], v[54:57], v[198:201], v[78:81]
	v_mfma_f32_16x16x32_bf16 v[74:77], v[62:65], v[198:201], v[74:77]
	v_mfma_f32_16x16x32_bf16 v[30:33], v[54:57], v[226:229], v[30:33]
	v_mfma_f32_16x16x32_bf16 v[26:29], v[62:65], v[226:229], v[26:29]
	v_mfma_f32_16x16x32_bf16 v[14:17], v[54:57], v[234:237], v[14:17]
	v_mfma_f32_16x16x32_bf16 v[10:13], v[62:65], v[234:237], v[10:13]
	v_mfma_f32_16x16x32_bf16 v[34:37], v[66:69], v[82:85], v[34:37]
	v_mfma_f32_16x16x32_bf16 v[86:89], v[70:73], v[190:193], v[34:37]
	v_mfma_f32_16x16x32_bf16 v[34:37], v[162:165], v[82:85], v[38:41]
	v_mfma_f32_16x16x32_bf16 v[82:85], v[166:169], v[190:193], v[34:37]
	v_mfma_f32_16x16x32_bf16 v[34:37], v[66:69], v[194:197], v[42:45]
	v_mfma_f32_16x16x32_bf16 v[54:57], v[70:73], v[198:201], v[34:37]
	v_mfma_f32_16x16x32_bf16 v[34:37], v[162:165], v[194:197], v[46:49]
	v_mfma_f32_16x16x32_bf16 v[22:25], v[66:69], v[222:225], v[22:25]
	v_mfma_f32_16x16x32_bf16 v[18:21], v[162:165], v[222:225], v[18:21]
	v_mfma_f32_16x16x32_bf16 v[6:9], v[66:69], v[230:233], v[6:9]
	v_mfma_f32_16x16x32_bf16 v[2:5], v[162:165], v[230:233], v[2:5]
	v_mfma_f32_16x16x32_bf16 v[50:53], v[166:169], v[198:201], v[34:37]
	v_mfma_f32_16x16x32_bf16 v[22:25], v[70:73], v[226:229], v[22:25]
	v_mfma_f32_16x16x32_bf16 v[18:21], v[166:169], v[226:229], v[18:21]
	v_mfma_f32_16x16x32_bf16 v[6:9], v[70:73], v[234:237], v[6:9]
	v_mfma_f32_16x16x32_bf16 v[2:5], v[166:169], v[234:237], v[2:5]
	s_setprio 0
	s_barrier
	s_add_i32 s55, s55, 2
	s_add_u32 s53, s53, 0x100
	s_addc_u32 s54, s54, 0
	s_add_u32 s6, s6, 0x100
	s_addc_u32 s7, s7, 0
	s_cmp_gt_u32 s55, 29
	s_cbranch_scc0 .LBB0_314
	s_and_b64 vcc, exec, s[22:23]
	s_cbranch_vccz .LBB0_317
	s_barrier

; #define PG8_STAGE(bufoff, gbase, voff) do { _Pragma("unroll") for (int _i = 0; _i < 2; ++_i) \
;         __builtin_amdgcn_global_load_lds((const unsigned*)((const char*)(gbase) + (voff)[_i]), (LAS unsigned*)(lds + (bufoff) + ldsw + _i * 8192), 16, 0, 0); } while (0)
; #define PG8_LDA(dst, b, h) do { _Pragma("unroll") for (int m = 0; m < 4; ++m) _Pragma("unroll") for (int k = 0; k < 2; ++k) dst[m][k] = *(const LAS bf16x8*)(lds + PG8_SA(b, h) + aoff + m * 2048 + k * 1024); } while (0)
; #define PG8_LDB(dst, b, h) do { _Pragma("unroll") for (int n = 0; n < 2; ++n) _Pragma("unroll") for (int k = 0; k < 2; ++k) dst[n][k] = *(const LAS bf16x8*)(lds + PG8_SB(b, h) + boff + n * 2048 + k * 1024); } while (0)
; #define PG8_MMA(ai, bj, At, Bt) do { __builtin_amdgcn_s_setprio(1); _Pragma("unroll") for (int m = 0; m < 4; ++m) _Pragma("unroll") for (int n = 0; n < 2; ++n) _Pragma("unroll") for (int k = 0; k < 2; ++k) \
;         acc[ai][bj][m][n] = __builtin_amdgcn_mfma_f32_16x16x32_bf16(Bt[n][k], At[m][k], acc[ai][bj][m][n], 0, 0, 0); __builtin_amdgcn_s_setprio(0); } while (0)
; #define PG8_WAIT_V(n) asm volatile("s_waitcnt vmcnt(" #n ")" ::: "memory")
; #define PG8_WAIT_L(n) asm volatile("s_waitcnt lgkmcnt(" #n ")" ::: "memory")
; #define PG8_BAR __builtin_amdgcn_s_barrier()
; #define PG8_SCHED __builtin_amdgcn_sched_barrier(0)
; template <class Epi>
; __device__ __forceinline__ void gemm_phase(LAS unsigned char* lds, const Gemm g, const StaticOrder& S, const Epi& E, const int tid) {
;     ...
;             PG8_LDB(B0, 0, 0); PG8_LDB(B1, 0, 1); PG8_SCHED; PG8_LDA(At, 0, 0); PG8_STAGE(PG8_SA(1, 1), a1 + hstep, voffA);
;             PG8_WAIT_V(8); PG8_WAIT_L(0); PG8_BAR; PG8_MMA(0, 0, At, B0); PG8_MMA(0, 1, At, B1); PG8_BAR; PG8_SCHED;
;             PG8_LDA(At, 0, 1); PG8_STAGE(PG8_SB(0, 0), b2, voffB); PG8_STAGE(PG8_SB(0, 1), b2 + bhs, voffB); PG8_STAGE(PG8_SA(0, 0), a2, voffA);
;             PG8_WAIT_V(8); PG8_WAIT_L(0); PG8_BAR; PG8_MMA(1, 0, At, B0); PG8_MMA(1, 1, At, B1); PG8_BAR; PG8_SCHED;
;     ...
;         for (int a = 0; a < 2; ++a)
; #pragma unroll
;             for (int b = 0; b < 2; ++b)
; #pragma unroll
;                 for (int m = 0; m < 4; ++m)
; #pragma unroll
;                     for (int n = 0; n < 2; ++n) acc[a][b][m][n] = (f32x4){0.f, 0.f, 0.f, 0.f};
.LBB0_546:
	s_add_u32 s28, s26, 0xfff80080
	s_addc_u32 s29, s27, -1
	s_add_i32 s44, 0, 0x10000
	s_cmp_eq_u32 s39, 28
	s_cselect_b32 s35, s19, s29
	s_cselect_b32 s34, s31, s28
	v_add_u32_e32 v0, s44, v149
	s_cselect_b32 s29, s17, s38
	s_cselect_b32 s28, s33, s37
	s_add_i32 s46, 0, 0x14000
	ds_read_b128 v[150:153], v0
	ds_read_b128 v[154:157], v0 offset:1024
	ds_read_b128 v[158:161], v0 offset:2048
	ds_read_b128 v[186:189], v0 offset:3072
	v_add_u32_e32 v0, s46, v149
	ds_read_b128 v[190:193], v0
	ds_read_b128 v[194:197], v0 offset:1024
	ds_read_b128 v[198:201], v0 offset:2048
	ds_read_b128 v[212:215], v0 offset:3072
	v_lshl_add_u64 v[162:163], s[26:27], 0, v[146:147]
	s_add_i32 m0, s57, 0xc000
	ds_read_b128 v[216:219], v184
	global_load_lds_dwordx4 v[162:163], off
	ds_read_b128 v[220:223], v184 offset:1024
	ds_read_b128 v[224:227], v184 offset:2048
	s_add_i32 m0, s57, 0xe000
	v_lshl_add_u64 v[162:163], s[26:27], 0, v[144:145]
	global_load_lds_dwordx4 v[162:163], off
	ds_read_b128 v[228:231], v184 offset:3072
	ds_read_b128 v[232:235], v184 offset:4096
	ds_read_b128 v[236:239], v184 offset:5120
	ds_read_b128 v[240:243], v184 offset:6144
	ds_read_b128 v[244:247], v184 offset:7168
	s_waitcnt vmcnt(8)
	s_waitcnt lgkmcnt(0)
	s_barrier
	s_setprio 1
	v_mfma_f32_16x16x32_bf16 v[126:129], v[150:153], v[216:219], v[126:129]
	v_mfma_f32_16x16x32_bf16 v[122:125], v[158:161], v[216:219], v[122:125]
	v_mfma_f32_16x16x32_bf16 v[110:113], v[150:153], v[224:227], v[110:113]
	v_mfma_f32_16x16x32_bf16 v[106:109], v[158:161], v[224:227], v[106:109]
	v_mfma_f32_16x16x32_bf16 v[94:97], v[150:153], v[232:235], v[94:97]
	v_mfma_f32_16x16x32_bf16 v[90:93], v[158:161], v[232:235], v[90:93]
	v_mfma_f32_16x16x32_bf16 v[78:81], v[150:153], v[240:243], v[78:81]
	v_mfma_f32_16x16x32_bf16 v[74:77], v[158:161], v[240:243], v[74:77]
	v_mfma_f32_16x16x32_bf16 v[126:129], v[154:157], v[220:223], v[126:129]
	v_mfma_f32_16x16x32_bf16 v[122:125], v[186:189], v[220:223], v[122:125]
	v_mfma_f32_16x16x32_bf16 v[110:113], v[154:157], v[228:231], v[110:113]
	v_mfma_f32_16x16x32_bf16 v[106:109], v[186:189], v[228:231], v[106:109]
	v_mfma_f32_16x16x32_bf16 v[94:97], v[154:157], v[236:239], v[94:97]
	v_mfma_f32_16x16x32_bf16 v[90:93], v[186:189], v[236:239], v[90:93]
	v_mfma_f32_16x16x32_bf16 v[78:81], v[154:157], v[244:247], v[78:81]
	v_mfma_f32_16x16x32_bf16 v[74:77], v[186:189], v[244:247], v[74:77]
	v_mfma_f32_16x16x32_bf16 v[118:121], v[190:193], v[216:219], v[118:121]
	v_mfma_f32_16x16x32_bf16 v[114:117], v[198:201], v[216:219], v[114:117]
	v_mfma_f32_16x16x32_bf16 v[102:105], v[190:193], v[224:227], v[102:105]
	v_mfma_f32_16x16x32_bf16 v[98:101], v[198:201], v[224:227], v[98:101]
	v_mfma_f32_16x16x32_bf16 v[86:89], v[190:193], v[232:235], v[86:89]
	v_mfma_f32_16x16x32_bf16 v[82:85], v[198:201], v[232:235], v[82:85]
	v_mfma_f32_16x16x32_bf16 v[70:73], v[190:193], v[240:243], v[70:73]
	v_mfma_f32_16x16x32_bf16 v[66:69], v[198:201], v[240:243], v[66:69]
	v_mfma_f32_16x16x32_bf16 v[118:121], v[194:197], v[220:223], v[118:121]
	v_mfma_f32_16x16x32_bf16 v[114:117], v[212:215], v[220:223], v[114:117]
	v_mfma_f32_16x16x32_bf16 v[102:105], v[194:197], v[228:231], v[102:105]
	v_mfma_f32_16x16x32_bf16 v[98:101], v[212:215], v[228:231], v[98:101]
	v_mfma_f32_16x16x32_bf16 v[86:89], v[194:197], v[236:239], v[86:89]
	v_mfma_f32_16x16x32_bf16 v[82:85], v[212:215], v[236:239], v[82:85]
	v_mfma_f32_16x16x32_bf16 v[70:73], v[194:197], v[244:247], v[70:73]
	v_mfma_f32_16x16x32_bf16 v[66:69], v[212:215], v[244:247], v[66:69]
	s_setprio 0
	s_barrier
	s_add_i32 s44, s44, s56
	v_lshl_add_u64 v[162:163], s[28:29], 0, v[132:133]
	s_mov_b32 m0, s44
	ds_read_b128 v[216:219], v184 offset:16384
	global_load_lds_dwordx4 v[162:163], off
	ds_read_b128 v[220:223], v184 offset:17408
	ds_read_b128 v[224:227], v184 offset:18432
	s_add_i32 m0, s44, 0x2000
	s_add_u32 s44, s28, 0x8000
	v_lshl_add_u64 v[248:249], s[28:29], 0, v[136:137]
	s_addc_u32 s45, s29, 0
	s_add_i32 s46, s46, s56
	global_load_lds_dwordx4 v[248:249], off
	ds_read_b128 v[228:231], v184 offset:19456
	ds_read_b128 v[232:235], v184 offset:20480
	v_lshl_add_u64 v[172:173], s[44:45], 0, v[132:133]
	s_mov_b32 m0, s46
	v_lshl_add_u64 v[174:175], s[34:35], 0, v[134:135]
	global_load_lds_dwordx4 v[172:173], off
	ds_read_b128 v[236:239], v184 offset:21504
	ds_read_b128 v[240:243], v184 offset:22528
	s_add_i32 m0, s46, 0x2000
	v_lshl_add_u64 v[172:173], s[44:45], 0, v[136:137]
	global_load_lds_dwordx4 v[172:173], off
	ds_read_b128 v[244:247], v184 offset:23552
	s_mov_b32 m0, s57
	v_lshl_add_u64 v[172:173], s[34:35], 0, v[130:131]
	global_load_lds_dwordx4 v[172:173], off
	s_mov_b32 m0, s58
	s_nop 0
	global_load_lds_dwordx4 v[174:175], off
	s_waitcnt vmcnt(8)
	s_waitcnt lgkmcnt(0)
	s_barrier
; #define PG8_STAGE(bufoff, gbase, voff) do { _Pragma("unroll") for (int _i = 0; _i < 2; ++_i) \
;         __builtin_amdgcn_global_load_lds((const unsigned*)((const char*)(gbase) + (voff)[_i]), (LAS unsigned*)(lds + (bufoff) + ldsw + _i * 8192), 16, 0, 0); } while (0)
; #define PG8_LDA(dst, b, h) do { _Pragma("unroll") for (int m = 0; m < 4; ++m) _Pragma("unroll") for (int k = 0; k < 2; ++k) dst[m][k] = *(const LAS bf16x8*)(lds + PG8_SA(b, h) + aoff + m * 2048 + k * 1024); } while (0)
; #define PG8_LDB(dst, b, h) do { _Pragma("unroll") for (int n = 0; n < 2; ++n) _Pragma("unroll") for (int k = 0; k < 2; ++k) dst[n][k] = *(const LAS bf16x8*)(lds + PG8_SB(b, h) + boff + n * 2048 + k * 1024); } while (0)
; #define PG8_MMA(ai, bj, At, Bt) do { __builtin_amdgcn_s_setprio(1); _Pragma("unroll") for (int m = 0; m < 4; ++m) _Pragma("unroll") for (int n = 0; n < 2; ++n) _Pragma("unroll") for (int k = 0; k < 2; ++k) \
;         acc[ai][bj][m][n] = __builtin_amdgcn_mfma_f32_16x16x32_bf16(Bt[n][k], At[m][k], acc[ai][bj][m][n], 0, 0, 0); __builtin_amdgcn_s_setprio(0); } while (0)
; #define PG8_WAIT_V(n) asm volatile("s_waitcnt vmcnt(" #n ")" ::: "memory")
; #define PG8_WAIT_L(n) asm volatile("s_waitcnt lgkmcnt(" #n ")" ::: "memory")
; #define PG8_BAR __builtin_amdgcn_s_barrier()
; #define PG8_SCHED __builtin_amdgcn_sched_barrier(0)
; template <class Epi>
; __device__ __forceinline__ void gemm_phase(LAS unsigned char* lds, const Gemm g, const StaticOrder& S, const Epi& E, const int tid) {
;     ...
;             PG8_WAIT_V(8); PG8_WAIT_L(0); PG8_BAR; PG8_MMA(1, 0, At, B0); PG8_MMA(1, 1, At, B1); PG8_BAR; PG8_SCHED;
;             PG8_LDB(B0, 1, 0); PG8_LDB(B1, 1, 1); PG8_SCHED; PG8_LDA(At, 1, 0); PG8_STAGE(PG8_SA(0, 1), a2 + hstep, voffA);
;             PG8_WAIT_V(8); PG8_WAIT_L(0); PG8_BAR; PG8_MMA(0, 0, At, B0); PG8_MMA(0, 1, At, B1); PG8_BAR; PG8_SCHED;
	s_setprio 1
	v_mfma_f32_16x16x32_bf16 v[62:65], v[150:153], v[216:219], v[62:65]
	v_mfma_f32_16x16x32_bf16 v[58:61], v[158:161], v[216:219], v[58:61]
	v_mfma_f32_16x16x32_bf16 v[46:49], v[150:153], v[224:227], v[46:49]
	v_mfma_f32_16x16x32_bf16 v[42:45], v[158:161], v[224:227], v[42:45]
	v_mfma_f32_16x16x32_bf16 v[30:33], v[150:153], v[232:235], v[30:33]
	v_mfma_f32_16x16x32_bf16 v[26:29], v[158:161], v[232:235], v[26:29]
	v_mfma_f32_16x16x32_bf16 v[14:17], v[150:153], v[240:243], v[14:17]
	v_mfma_f32_16x16x32_bf16 v[10:13], v[158:161], v[240:243], v[10:13]
	v_mfma_f32_16x16x32_bf16 v[62:65], v[154:157], v[220:223], v[62:65]
	v_mfma_f32_16x16x32_bf16 v[58:61], v[186:189], v[220:223], v[58:61]
	v_mfma_f32_16x16x32_bf16 v[46:49], v[154:157], v[228:231], v[46:49]
	v_mfma_f32_16x16x32_bf16 v[42:45], v[186:189], v[228:231], v[42:45]
	v_mfma_f32_16x16x32_bf16 v[30:33], v[154:157], v[236:239], v[30:33]
	v_mfma_f32_16x16x32_bf16 v[26:29], v[186:189], v[236:239], v[26:29]
	v_mfma_f32_16x16x32_bf16 v[14:17], v[154:157], v[244:247], v[14:17]
	v_mfma_f32_16x16x32_bf16 v[10:13], v[186:189], v[244:247], v[10:13]
	v_mfma_f32_16x16x32_bf16 v[54:57], v[190:193], v[216:219], v[54:57]
	v_mfma_f32_16x16x32_bf16 v[50:53], v[198:201], v[216:219], v[50:53]
	v_mfma_f32_16x16x32_bf16 v[38:41], v[190:193], v[224:227], v[38:41]
	v_mfma_f32_16x16x32_bf16 v[34:37], v[198:201], v[224:227], v[34:37]
	v_mfma_f32_16x16x32_bf16 v[22:25], v[190:193], v[232:235], v[22:25]
	v_mfma_f32_16x16x32_bf16 v[18:21], v[198:201], v[232:235], v[18:21]
	v_mfma_f32_16x16x32_bf16 v[6:9], v[190:193], v[240:243], v[6:9]
	v_mfma_f32_16x16x32_bf16 v[2:5], v[198:201], v[240:243], v[2:5]
	v_mfma_f32_16x16x32_bf16 v[54:57], v[194:197], v[220:223], v[54:57]
	v_mfma_f32_16x16x32_bf16 v[50:53], v[212:215], v[220:223], v[50:53]
	v_mfma_f32_16x16x32_bf16 v[38:41], v[194:197], v[228:231], v[38:41]
	v_mfma_f32_16x16x32_bf16 v[34:37], v[212:215], v[228:231], v[34:37]
	v_mfma_f32_16x16x32_bf16 v[22:25], v[194:197], v[236:239], v[22:25]
	v_mfma_f32_16x16x32_bf16 v[18:21], v[212:215], v[236:239], v[18:21]
	v_mfma_f32_16x16x32_bf16 v[6:9], v[194:197], v[244:247], v[6:9]
	v_mfma_f32_16x16x32_bf16 v[2:5], v[212:215], v[244:247], v[2:5]
	s_setprio 0
	s_barrier
	s_add_i32 s44, 0, 0x18000
	v_add_u32_e32 v0, s44, v149
	s_add_i32 s45, 0, 0x1c000
	ds_read_b128 v[150:153], v0
	ds_read_b128 v[154:157], v0 offset:1024
	ds_read_b128 v[158:161], v0 offset:2048
	ds_read_b128 v[186:189], v0 offset:3072
	v_add_u32_e32 v0, s45, v149
	ds_read_b128 v[190:193], v0
	ds_read_b128 v[194:197], v0 offset:1024
	ds_read_b128 v[198:201], v0 offset:2048
	ds_read_b128 v[212:215], v0 offset:3072
	s_add_u32 s34, s34, 0x80000
	s_addc_u32 s35, s35, 0
	s_mov_b32 m0, s59
	v_lshl_add_u64 v[176:177], s[34:35], 0, v[130:131]
	ds_read_b128 v[216:219], v184 offset:32768
	global_load_lds_dwordx4 v[176:177], off
	ds_read_b128 v[220:223], v184 offset:33792
	ds_read_b128 v[224:227], v184 offset:34816
	s_mov_b32 m0, s60
	v_lshl_add_u64 v[176:177], s[34:35], 0, v[134:135]
	global_load_lds_dwordx4 v[176:177], off
	ds_read_b128 v[228:231], v184 offset:35840
	ds_read_b128 v[232:235], v184 offset:36864
	ds_read_b128 v[236:239], v184 offset:37888
	ds_read_b128 v[240:243], v184 offset:38912
	ds_read_b128 v[244:247], v184 offset:39936
	s_waitcnt vmcnt(8)
	s_waitcnt lgkmcnt(0)
	s_barrier
	s_setprio 1
	v_mfma_f32_16x16x32_bf16 v[126:129], v[150:153], v[216:219], v[126:129]
	v_mfma_f32_16x16x32_bf16 v[122:125], v[158:161], v[216:219], v[122:125]
	v_mfma_f32_16x16x32_bf16 v[110:113], v[150:153], v[224:227], v[110:113]
	v_mfma_f32_16x16x32_bf16 v[106:109], v[158:161], v[224:227], v[106:109]
	v_mfma_f32_16x16x32_bf16 v[94:97], v[150:153], v[232:235], v[94:97]
	v_mfma_f32_16x16x32_bf16 v[90:93], v[158:161], v[232:235], v[90:93]
	v_mfma_f32_16x16x32_bf16 v[78:81], v[150:153], v[240:243], v[78:81]
	v_mfma_f32_16x16x32_bf16 v[74:77], v[158:161], v[240:243], v[74:77]
	v_mfma_f32_16x16x32_bf16 v[126:129], v[154:157], v[220:223], v[126:129]
	v_mfma_f32_16x16x32_bf16 v[122:125], v[186:189], v[220:223], v[122:125]
	v_mfma_f32_16x16x32_bf16 v[110:113], v[154:157], v[228:231], v[110:113]
	v_mfma_f32_16x16x32_bf16 v[106:109], v[186:189], v[228:231], v[106:109]
	v_mfma_f32_16x16x32_bf16 v[94:97], v[154:157], v[236:239], v[94:97]
	v_mfma_f32_16x16x32_bf16 v[90:93], v[186:189], v[236:239], v[90:93]
	v_mfma_f32_16x16x32_bf16 v[78:81], v[154:157], v[244:247], v[78:81]
	v_mfma_f32_16x16x32_bf16 v[74:77], v[186:189], v[244:247], v[74:77]
	v_mfma_f32_16x16x32_bf16 v[118:121], v[190:193], v[216:219], v[118:121]
	v_mfma_f32_16x16x32_bf16 v[114:117], v[198:201], v[216:219], v[114:117]
	v_mfma_f32_16x16x32_bf16 v[102:105], v[190:193], v[224:227], v[102:105]
	v_mfma_f32_16x16x32_bf16 v[98:101], v[198:201], v[224:227], v[98:101]
	v_mfma_f32_16x16x32_bf16 v[86:89], v[190:193], v[232:235], v[86:89]
	v_mfma_f32_16x16x32_bf16 v[82:85], v[198:201], v[232:235], v[82:85]
	v_mfma_f32_16x16x32_bf16 v[70:73], v[190:193], v[240:243], v[70:73]
	v_mfma_f32_16x16x32_bf16 v[66:69], v[198:201], v[240:243], v[66:69]
	v_mfma_f32_16x16x32_bf16 v[118:121], v[194:197], v[220:223], v[118:121]
	v_mfma_f32_16x16x32_bf16 v[114:117], v[212:215], v[220:223], v[114:117]
	v_mfma_f32_16x16x32_bf16 v[102:105], v[194:197], v[228:231], v[102:105]
	v_mfma_f32_16x16x32_bf16 v[98:101], v[212:215], v[228:231], v[98:101]
	v_mfma_f32_16x16x32_bf16 v[86:89], v[194:197], v[236:239], v[86:89]
	v_mfma_f32_16x16x32_bf16 v[82:85], v[212:215], v[236:239], v[82:85]
	v_mfma_f32_16x16x32_bf16 v[70:73], v[194:197], v[244:247], v[70:73]
	v_mfma_f32_16x16x32_bf16 v[66:69], v[212:215], v[244:247], v[66:69]
	s_setprio 0
	s_barrier
; #define PG8_STAGE(bufoff, gbase, voff) do { _Pragma("unroll") for (int _i = 0; _i < 2; ++_i) \
;         __builtin_amdgcn_global_load_lds((const unsigned*)((const char*)(gbase) + (voff)[_i]), (LAS unsigned*)(lds + (bufoff) + ldsw + _i * 8192), 16, 0, 0); } while (0)
; #define PG8_LDA(dst, b, h) do { _Pragma("unroll") for (int m = 0; m < 4; ++m) _Pragma("unroll") for (int k = 0; k < 2; ++k) dst[m][k] = *(const LAS bf16x8*)(lds + PG8_SA(b, h) + aoff + m * 2048 + k * 1024); } while (0)
; #define PG8_MMA(ai, bj, At, Bt) do { __builtin_amdgcn_s_setprio(1); _Pragma("unroll") for (int m = 0; m < 4; ++m) _Pragma("unroll") for (int n = 0; n < 2; ++n) _Pragma("unroll") for (int k = 0; k < 2; ++k) \
;         acc[ai][bj][m][n] = __builtin_amdgcn_mfma_f32_16x16x32_bf16(Bt[n][k], At[m][k], acc[ai][bj][m][n], 0, 0, 0); __builtin_amdgcn_s_setprio(0); } while (0)
; #define PG8_WAIT_V(n) asm volatile("s_waitcnt vmcnt(" #n ")" ::: "memory")
; #define PG8_WAIT_L(n) asm volatile("s_waitcnt lgkmcnt(" #n ")" ::: "memory")
; #define PG8_BAR __builtin_amdgcn_s_barrier()
; #define PG8_SCHED __builtin_amdgcn_sched_barrier(0)
; template <class Epi>
; __device__ __forceinline__ void gemm_phase(LAS unsigned char* lds, const Gemm g, const StaticOrder& S, const Epi& E, const int tid) {
;     ...
;             PG8_LDA(At, 1, 1); PG8_STAGE(PG8_SB(1, 0), b3, voffB); PG8_STAGE(PG8_SB(1, 1), b3 + bhs, voffB); PG8_STAGE(PG8_SA(1, 0), a3, voffA);
;             PG8_WAIT_V(8); PG8_WAIT_L(0); PG8_BAR; PG8_MMA(1, 0, At, B0); PG8_MMA(1, 1, At, B1); PG8_BAR; PG8_SCHED;
;     ...
;         if (ALIGN_EPI) { if (wr == 0) PG8_BAR; }
	s_add_i32 s34, s44, s56
	v_lshl_add_u64 v[162:163], v[162:163], 0, s[70:71]
	s_mov_b32 m0, s34
	ds_read_b128 v[216:219], v184 offset:49152
	global_load_lds_dwordx4 v[162:163], off
	ds_read_b128 v[220:223], v184 offset:50176
	ds_read_b128 v[224:227], v184 offset:51200
	s_add_i32 m0, s34, 0x2000
	s_add_u32 s28, s28, 0x8080
	v_lshl_add_u64 v[162:163], v[248:249], 0, s[70:71]
	s_addc_u32 s29, s29, 0
	s_add_i32 s34, s45, s56
	global_load_lds_dwordx4 v[162:163], off
	ds_read_b128 v[228:231], v184 offset:52224
	ds_read_b128 v[232:235], v184 offset:53248
	s_mov_b32 m0, s34
	v_lshl_add_u64 v[162:163], s[28:29], 0, v[132:133]
	global_load_lds_dwordx4 v[162:163], off
	ds_read_b128 v[236:239], v184 offset:54272
	ds_read_b128 v[240:243], v184 offset:55296
	s_add_i32 m0, s34, 0x2000
	v_lshl_add_u64 v[162:163], s[28:29], 0, v[136:137]
	global_load_lds_dwordx4 v[162:163], off
	ds_read_b128 v[244:247], v184 offset:56320
	s_mov_b32 m0, s61
	v_lshl_add_u64 v[162:163], v[172:173], 0, s[70:71]
	global_load_lds_dwordx4 v[162:163], off
	s_mov_b32 m0, s62
	v_lshl_add_u64 v[162:163], v[174:175], 0, s[70:71]
	global_load_lds_dwordx4 v[162:163], off
	s_waitcnt vmcnt(8)
	s_waitcnt lgkmcnt(0)
	s_barrier
	s_setprio 1
	v_mfma_f32_16x16x32_bf16 v[62:65], v[150:153], v[216:219], v[62:65]
	v_mfma_f32_16x16x32_bf16 v[58:61], v[158:161], v[216:219], v[58:61]
	v_mfma_f32_16x16x32_bf16 v[46:49], v[150:153], v[224:227], v[46:49]
	v_mfma_f32_16x16x32_bf16 v[42:45], v[158:161], v[224:227], v[42:45]
	v_mfma_f32_16x16x32_bf16 v[30:33], v[150:153], v[232:235], v[30:33]
	v_mfma_f32_16x16x32_bf16 v[26:29], v[158:161], v[232:235], v[26:29]
	v_mfma_f32_16x16x32_bf16 v[14:17], v[150:153], v[240:243], v[14:17]
	v_mfma_f32_16x16x32_bf16 v[10:13], v[158:161], v[240:243], v[10:13]
	v_mfma_f32_16x16x32_bf16 v[62:65], v[154:157], v[220:223], v[62:65]
	v_mfma_f32_16x16x32_bf16 v[58:61], v[186:189], v[220:223], v[58:61]
	v_mfma_f32_16x16x32_bf16 v[46:49], v[154:157], v[228:231], v[46:49]
	v_mfma_f32_16x16x32_bf16 v[42:45], v[186:189], v[228:231], v[42:45]
	v_mfma_f32_16x16x32_bf16 v[30:33], v[154:157], v[236:239], v[30:33]
	v_mfma_f32_16x16x32_bf16 v[26:29], v[186:189], v[236:239], v[26:29]
	v_mfma_f32_16x16x32_bf16 v[14:17], v[154:157], v[244:247], v[14:17]
	v_mfma_f32_16x16x32_bf16 v[10:13], v[186:189], v[244:247], v[10:13]
	v_mfma_f32_16x16x32_bf16 v[54:57], v[190:193], v[216:219], v[54:57]
	v_mfma_f32_16x16x32_bf16 v[50:53], v[198:201], v[216:219], v[50:53]
	v_mfma_f32_16x16x32_bf16 v[38:41], v[190:193], v[224:227], v[38:41]
	v_mfma_f32_16x16x32_bf16 v[34:37], v[198:201], v[224:227], v[34:37]
	v_mfma_f32_16x16x32_bf16 v[22:25], v[190:193], v[232:235], v[22:25]
	v_mfma_f32_16x16x32_bf16 v[18:21], v[198:201], v[232:235], v[18:21]
	v_mfma_f32_16x16x32_bf16 v[6:9], v[190:193], v[240:243], v[6:9]
	v_mfma_f32_16x16x32_bf16 v[2:5], v[198:201], v[240:243], v[2:5]
	v_mfma_f32_16x16x32_bf16 v[54:57], v[194:197], v[220:223], v[54:57]
	v_mfma_f32_16x16x32_bf16 v[50:53], v[212:215], v[220:223], v[50:53]
	v_mfma_f32_16x16x32_bf16 v[38:41], v[194:197], v[228:231], v[38:41]
	v_mfma_f32_16x16x32_bf16 v[34:37], v[212:215], v[228:231], v[34:37]
	v_mfma_f32_16x16x32_bf16 v[22:25], v[194:197], v[236:239], v[22:25]
	v_mfma_f32_16x16x32_bf16 v[18:21], v[212:215], v[236:239], v[18:21]
	v_mfma_f32_16x16x32_bf16 v[6:9], v[194:197], v[244:247], v[6:9]
	v_mfma_f32_16x16x32_bf16 v[2:5], v[212:215], v[244:247], v[2:5]
	s_setprio 0
	s_barrier
	s_add_i32 s39, s39, 2
	s_add_u32 s37, s37, 0x100
	s_addc_u32 s38, s38, 0
	s_add_u32 s26, s26, 0x100
	s_addc_u32 s27, s27, 0
	s_cmp_gt_u32 s39, 29
	s_cbranch_scc0 .LBB0_546
	s_and_b64 vcc, exec, s[14:15]
	s_cbranch_vccz .LBB0_549
	s_barrier

; #define PG8_STAGE(bufoff, gbase, voff) do { _Pragma("unroll") for (int _i = 0; _i < 2; ++_i) \
;         __builtin_amdgcn_global_load_lds((const unsigned*)((const char*)(gbase) + (voff)[_i]), (LAS unsigned*)(lds + (bufoff) + ldsw + _i * 8192), 16, 0, 0); } while (0)
; #define PG8_LDA(dst, b, h) do { _Pragma("unroll") for (int m = 0; m < 4; ++m) _Pragma("unroll") for (int k = 0; k < 2; ++k) dst[m][k] = *(const LAS bf16x8*)(lds + PG8_SA(b, h) + aoff + m * 2048 + k * 1024); } while (0)
; #define PG8_LDB(dst, b, h) do { _Pragma("unroll") for (int n = 0; n < 2; ++n) _Pragma("unroll") for (int k = 0; k < 2; ++k) dst[n][k] = *(const LAS bf16x8*)(lds + PG8_SB(b, h) + boff + n * 2048 + k * 1024); } while (0)
; #define PG8_MMA(ai, bj, At, Bt) do { __builtin_amdgcn_s_setprio(1); _Pragma("unroll") for (int m = 0; m < 4; ++m) _Pragma("unroll") for (int n = 0; n < 2; ++n) _Pragma("unroll") for (int k = 0; k < 2; ++k) \
;         acc[ai][bj][m][n] = __builtin_amdgcn_mfma_f32_16x16x32_bf16(Bt[n][k], At[m][k], acc[ai][bj][m][n], 0, 0, 0); __builtin_amdgcn_s_setprio(0); } while (0)
; #define PG8_WAIT_V(n) asm volatile("s_waitcnt vmcnt(" #n ")" ::: "memory")
; #define PG8_WAIT_L(n) asm volatile("s_waitcnt lgkmcnt(" #n ")" ::: "memory")
; #define PG8_BAR __builtin_amdgcn_s_barrier()
; #define PG8_SCHED __builtin_amdgcn_sched_barrier(0)
; template <class Epi>
; __device__ __forceinline__ void gemm_phase(LAS unsigned char* lds, const Gemm g, const StaticOrder& S, const Epi& E, const int tid) {
;     ...
;             PG8_LDB(B0, 0, 0); PG8_LDB(B1, 0, 1); PG8_SCHED; PG8_LDA(At, 0, 0); PG8_STAGE(PG8_SA(1, 1), a1 + hstep, voffA);
;             PG8_WAIT_V(8); PG8_WAIT_L(0); PG8_BAR; PG8_MMA(0, 0, At, B0); PG8_MMA(0, 1, At, B1); PG8_BAR; PG8_SCHED;
;             PG8_LDA(At, 0, 1); PG8_STAGE(PG8_SB(0, 0), b2, voffB); PG8_STAGE(PG8_SB(0, 1), b2 + bhs, voffB); PG8_STAGE(PG8_SA(0, 0), a2, voffA);
;             PG8_WAIT_V(8); PG8_WAIT_L(0); PG8_BAR; PG8_MMA(1, 0, At, B0); PG8_MMA(1, 1, At, B1); PG8_BAR; PG8_SCHED;
;     ...
;         for (int a = 0; a < 2; ++a)
; #pragma unroll
;             for (int b = 0; b < 2; ++b)
; #pragma unroll
;                 for (int m = 0; m < 4; ++m)
; #pragma unroll
;                     for (int n = 0; n < 2; ++n) acc[a][b][m][n] = (f32x4){0.f, 0.f, 0.f, 0.f};
.LBB0_844:
	s_add_u32 s28, s26, 0xfff80080
	s_addc_u32 s29, s27, -1
	s_add_i32 s48, 0, 0x10000
	s_cmp_eq_u32 s47, 28
	s_cselect_b32 s31, s15, s29
	s_cselect_b32 s30, s43, s28
	v_add_u32_e32 v145, s48, v142
	s_cselect_b32 s29, s13, s46
	s_cselect_b32 s28, s44, s45
	s_add_i32 s50, 0, 0x14000
	ds_read_b128 v[146:149], v145
	ds_read_b128 v[150:153], v145 offset:1024
	ds_read_b128 v[154:157], v145 offset:2048
	ds_read_b128 v[158:161], v145 offset:3072
	v_add_u32_e32 v145, s50, v142
	ds_read_b128 v[162:165], v145
	ds_read_b128 v[166:169], v145 offset:1024
	ds_read_b128 v[178:181], v145 offset:2048
	ds_read_b128 v[182:185], v145 offset:3072
	v_lshl_add_u64 v[172:173], s[26:27], 0, v[138:139]
	s_add_i32 m0, s23, 0xc000
	ds_read_b128 v[186:189], v144
	global_load_lds_dwordx4 v[172:173], off
	ds_read_b128 v[190:193], v144 offset:1024
	ds_read_b128 v[194:197], v144 offset:2048
	s_add_i32 m0, s23, 0xe000
	v_lshl_add_u64 v[172:173], s[26:27], 0, v[136:137]
	global_load_lds_dwordx4 v[172:173], off
	ds_read_b128 v[198:201], v144 offset:3072
	ds_read_b128 v[212:215], v144 offset:4096
	ds_read_b128 v[216:219], v144 offset:5120
	ds_read_b128 v[220:223], v144 offset:6144
	ds_read_b128 v[224:227], v144 offset:7168
	s_waitcnt vmcnt(8)
	s_waitcnt lgkmcnt(0)
	s_barrier
	s_setprio 1
	v_mfma_f32_16x16x32_bf16 v[126:129], v[146:149], v[186:189], v[126:129]
	v_mfma_f32_16x16x32_bf16 v[122:125], v[154:157], v[186:189], v[122:125]
	v_mfma_f32_16x16x32_bf16 v[118:121], v[146:149], v[194:197], v[118:121]
	v_mfma_f32_16x16x32_bf16 v[110:113], v[154:157], v[194:197], v[110:113]
	v_mfma_f32_16x16x32_bf16 v[102:105], v[146:149], v[212:215], v[102:105]
	v_mfma_f32_16x16x32_bf16 v[94:97], v[154:157], v[212:215], v[94:97]
	v_mfma_f32_16x16x32_bf16 v[86:89], v[146:149], v[220:223], v[86:89]
	v_mfma_f32_16x16x32_bf16 v[78:81], v[154:157], v[220:223], v[78:81]
	v_mfma_f32_16x16x32_bf16 v[126:129], v[150:153], v[190:193], v[126:129]
	v_mfma_f32_16x16x32_bf16 v[122:125], v[158:161], v[190:193], v[122:125]
	v_mfma_f32_16x16x32_bf16 v[118:121], v[150:153], v[198:201], v[118:121]
	v_mfma_f32_16x16x32_bf16 v[110:113], v[158:161], v[198:201], v[110:113]
	v_mfma_f32_16x16x32_bf16 v[102:105], v[150:153], v[216:219], v[102:105]
	v_mfma_f32_16x16x32_bf16 v[94:97], v[158:161], v[216:219], v[94:97]
	v_mfma_f32_16x16x32_bf16 v[86:89], v[150:153], v[224:227], v[86:89]
	v_mfma_f32_16x16x32_bf16 v[78:81], v[158:161], v[224:227], v[78:81]
	v_mfma_f32_16x16x32_bf16 v[114:117], v[162:165], v[186:189], v[114:117]
	v_mfma_f32_16x16x32_bf16 v[106:109], v[178:181], v[186:189], v[106:109]
	v_mfma_f32_16x16x32_bf16 v[98:101], v[162:165], v[194:197], v[98:101]
	v_mfma_f32_16x16x32_bf16 v[90:93], v[178:181], v[194:197], v[90:93]
	v_mfma_f32_16x16x32_bf16 v[82:85], v[162:165], v[212:215], v[82:85]
	v_mfma_f32_16x16x32_bf16 v[74:77], v[178:181], v[212:215], v[74:77]
	v_mfma_f32_16x16x32_bf16 v[70:73], v[162:165], v[220:223], v[70:73]
	v_mfma_f32_16x16x32_bf16 v[66:69], v[178:181], v[220:223], v[66:69]
	v_mfma_f32_16x16x32_bf16 v[114:117], v[166:169], v[190:193], v[114:117]
	v_mfma_f32_16x16x32_bf16 v[106:109], v[182:185], v[190:193], v[106:109]
	v_mfma_f32_16x16x32_bf16 v[98:101], v[166:169], v[198:201], v[98:101]
	v_mfma_f32_16x16x32_bf16 v[90:93], v[182:185], v[198:201], v[90:93]
	v_mfma_f32_16x16x32_bf16 v[82:85], v[166:169], v[216:219], v[82:85]
	v_mfma_f32_16x16x32_bf16 v[74:77], v[182:185], v[216:219], v[74:77]
	v_mfma_f32_16x16x32_bf16 v[70:73], v[166:169], v[224:227], v[70:73]
	v_mfma_f32_16x16x32_bf16 v[66:69], v[182:185], v[224:227], v[66:69]
	s_setprio 0
	s_barrier
	s_add_i32 s48, s48, s37
	v_lshl_add_u64 v[172:173], s[28:29], 0, v[0:1]
	s_mov_b32 m0, s48
	ds_read_b128 v[186:189], v144 offset:16384
	global_load_lds_dwordx4 v[172:173], off
	ds_read_b128 v[190:193], v144 offset:17408
	ds_read_b128 v[194:197], v144 offset:18432
	s_add_i32 m0, s48, 0x2000
	s_add_u32 s48, s28, 0x8000
	v_lshl_add_u64 v[174:175], s[28:29], 0, v[134:135]
	s_addc_u32 s49, s29, 0
	s_add_i32 s50, s50, s37
	global_load_lds_dwordx4 v[174:175], off
	ds_read_b128 v[198:201], v144 offset:19456
	ds_read_b128 v[212:215], v144 offset:20480
	v_lshl_add_u64 v[176:177], s[48:49], 0, v[0:1]
	s_mov_b32 m0, s50
	v_lshl_add_u64 v[228:229], s[30:31], 0, v[132:133]
	global_load_lds_dwordx4 v[176:177], off
	ds_read_b128 v[216:219], v144 offset:21504
	ds_read_b128 v[220:223], v144 offset:22528
	s_add_i32 m0, s50, 0x2000
	v_lshl_add_u64 v[176:177], s[48:49], 0, v[134:135]
	global_load_lds_dwordx4 v[176:177], off
	ds_read_b128 v[224:227], v144 offset:23552
	s_mov_b32 m0, s23
	v_lshl_add_u64 v[176:177], s[30:31], 0, v[130:131]
	global_load_lds_dwordx4 v[176:177], off
	s_mov_b32 m0, s25
	s_nop 0
	global_load_lds_dwordx4 v[228:229], off
	s_waitcnt vmcnt(8)
	s_waitcnt lgkmcnt(0)
	s_barrier
; #define PG8_STAGE(bufoff, gbase, voff) do { _Pragma("unroll") for (int _i = 0; _i < 2; ++_i) \
;         __builtin_amdgcn_global_load_lds((const unsigned*)((const char*)(gbase) + (voff)[_i]), (LAS unsigned*)(lds + (bufoff) + ldsw + _i * 8192), 16, 0, 0); } while (0)
; #define PG8_LDA(dst, b, h) do { _Pragma("unroll") for (int m = 0; m < 4; ++m) _Pragma("unroll") for (int k = 0; k < 2; ++k) dst[m][k] = *(const LAS bf16x8*)(lds + PG8_SA(b, h) + aoff + m * 2048 + k * 1024); } while (0)
; #define PG8_LDB(dst, b, h) do { _Pragma("unroll") for (int n = 0; n < 2; ++n) _Pragma("unroll") for (int k = 0; k < 2; ++k) dst[n][k] = *(const LAS bf16x8*)(lds + PG8_SB(b, h) + boff + n * 2048 + k * 1024); } while (0)
; #define PG8_MMA(ai, bj, At, Bt) do { __builtin_amdgcn_s_setprio(1); _Pragma("unroll") for (int m = 0; m < 4; ++m) _Pragma("unroll") for (int n = 0; n < 2; ++n) _Pragma("unroll") for (int k = 0; k < 2; ++k) \
;         acc[ai][bj][m][n] = __builtin_amdgcn_mfma_f32_16x16x32_bf16(Bt[n][k], At[m][k], acc[ai][bj][m][n], 0, 0, 0); __builtin_amdgcn_s_setprio(0); } while (0)
; #define PG8_WAIT_V(n) asm volatile("s_waitcnt vmcnt(" #n ")" ::: "memory")
; #define PG8_WAIT_L(n) asm volatile("s_waitcnt lgkmcnt(" #n ")" ::: "memory")
; #define PG8_BAR __builtin_amdgcn_s_barrier()
; #define PG8_SCHED __builtin_amdgcn_sched_barrier(0)
; template <class Epi>
; __device__ __forceinline__ void gemm_phase(LAS unsigned char* lds, const Gemm g, const StaticOrder& S, const Epi& E, const int tid) {
;     ...
;             PG8_WAIT_V(8); PG8_WAIT_L(0); PG8_BAR; PG8_MMA(1, 0, At, B0); PG8_MMA(1, 1, At, B1); PG8_BAR; PG8_SCHED;
;             PG8_LDB(B0, 1, 0); PG8_LDB(B1, 1, 1); PG8_SCHED; PG8_LDA(At, 1, 0); PG8_STAGE(PG8_SA(0, 1), a2 + hstep, voffA);
;             PG8_WAIT_V(8); PG8_WAIT_L(0); PG8_BAR; PG8_MMA(0, 0, At, B0); PG8_MMA(0, 1, At, B1); PG8_BAR; PG8_SCHED;
	s_setprio 1
	v_mfma_f32_16x16x32_bf16 v[62:65], v[146:149], v[186:189], v[62:65]
	v_mfma_f32_16x16x32_bf16 v[58:61], v[154:157], v[186:189], v[58:61]
	v_mfma_f32_16x16x32_bf16 v[54:57], v[146:149], v[194:197], v[54:57]
	v_mfma_f32_16x16x32_bf16 v[46:49], v[154:157], v[194:197], v[46:49]
	v_mfma_f32_16x16x32_bf16 v[38:41], v[146:149], v[212:215], v[38:41]
	v_mfma_f32_16x16x32_bf16 v[30:33], v[154:157], v[212:215], v[30:33]
	v_mfma_f32_16x16x32_bf16 v[22:25], v[146:149], v[220:223], v[22:25]
	v_mfma_f32_16x16x32_bf16 v[14:17], v[154:157], v[220:223], v[14:17]
	v_mfma_f32_16x16x32_bf16 v[62:65], v[150:153], v[190:193], v[62:65]
	v_mfma_f32_16x16x32_bf16 v[58:61], v[158:161], v[190:193], v[58:61]
	v_mfma_f32_16x16x32_bf16 v[54:57], v[150:153], v[198:201], v[54:57]
	v_mfma_f32_16x16x32_bf16 v[46:49], v[158:161], v[198:201], v[46:49]
	v_mfma_f32_16x16x32_bf16 v[38:41], v[150:153], v[216:219], v[38:41]
	v_mfma_f32_16x16x32_bf16 v[30:33], v[158:161], v[216:219], v[30:33]
	v_mfma_f32_16x16x32_bf16 v[22:25], v[150:153], v[224:227], v[22:25]
	v_mfma_f32_16x16x32_bf16 v[14:17], v[158:161], v[224:227], v[14:17]
	v_mfma_f32_16x16x32_bf16 v[50:53], v[162:165], v[186:189], v[50:53]
	v_mfma_f32_16x16x32_bf16 v[42:45], v[178:181], v[186:189], v[42:45]
	v_mfma_f32_16x16x32_bf16 v[34:37], v[162:165], v[194:197], v[34:37]
	v_mfma_f32_16x16x32_bf16 v[26:29], v[178:181], v[194:197], v[26:29]
	v_mfma_f32_16x16x32_bf16 v[18:21], v[162:165], v[212:215], v[18:21]
	v_mfma_f32_16x16x32_bf16 v[10:13], v[178:181], v[212:215], v[10:13]
	v_mfma_f32_16x16x32_bf16 v[6:9], v[162:165], v[220:223], v[6:9]
	v_mfma_f32_16x16x32_bf16 v[2:5], v[178:181], v[220:223], v[2:5]
	v_mfma_f32_16x16x32_bf16 v[50:53], v[166:169], v[190:193], v[50:53]
	v_mfma_f32_16x16x32_bf16 v[42:45], v[182:185], v[190:193], v[42:45]
	v_mfma_f32_16x16x32_bf16 v[34:37], v[166:169], v[198:201], v[34:37]
	v_mfma_f32_16x16x32_bf16 v[26:29], v[182:185], v[198:201], v[26:29]
	v_mfma_f32_16x16x32_bf16 v[18:21], v[166:169], v[216:219], v[18:21]
	v_mfma_f32_16x16x32_bf16 v[10:13], v[182:185], v[216:219], v[10:13]
	v_mfma_f32_16x16x32_bf16 v[6:9], v[166:169], v[224:227], v[6:9]
	v_mfma_f32_16x16x32_bf16 v[2:5], v[182:185], v[224:227], v[2:5]
	s_setprio 0
	s_barrier
	s_add_i32 s48, 0, 0x18000
	v_add_u32_e32 v145, s48, v142
	s_add_i32 s49, 0, 0x1c000
	ds_read_b128 v[146:149], v145
	ds_read_b128 v[150:153], v145 offset:1024
	ds_read_b128 v[154:157], v145 offset:2048
	ds_read_b128 v[158:161], v145 offset:3072
	v_add_u32_e32 v145, s49, v142
	ds_read_b128 v[162:165], v145
	ds_read_b128 v[166:169], v145 offset:1024
	ds_read_b128 v[178:181], v145 offset:2048
	ds_read_b128 v[182:185], v145 offset:3072
	s_add_u32 s30, s30, 0x80000
	s_addc_u32 s31, s31, 0
	s_mov_b32 m0, s38
	v_lshl_add_u64 v[230:231], s[30:31], 0, v[130:131]
	ds_read_b128 v[186:189], v144 offset:32768
	global_load_lds_dwordx4 v[230:231], off
	ds_read_b128 v[190:193], v144 offset:33792
	ds_read_b128 v[194:197], v144 offset:34816
	s_mov_b32 m0, s39
	v_lshl_add_u64 v[230:231], s[30:31], 0, v[132:133]
	global_load_lds_dwordx4 v[230:231], off
	ds_read_b128 v[198:201], v144 offset:35840
	ds_read_b128 v[212:215], v144 offset:36864
	ds_read_b128 v[216:219], v144 offset:37888
	ds_read_b128 v[220:223], v144 offset:38912
	ds_read_b128 v[224:227], v144 offset:39936
	s_waitcnt vmcnt(8)
	s_waitcnt lgkmcnt(0)
	s_barrier
	s_setprio 1
	v_mfma_f32_16x16x32_bf16 v[126:129], v[146:149], v[186:189], v[126:129]
	v_mfma_f32_16x16x32_bf16 v[122:125], v[154:157], v[186:189], v[122:125]
	v_mfma_f32_16x16x32_bf16 v[118:121], v[146:149], v[194:197], v[118:121]
	v_mfma_f32_16x16x32_bf16 v[110:113], v[154:157], v[194:197], v[110:113]
	v_mfma_f32_16x16x32_bf16 v[102:105], v[146:149], v[212:215], v[102:105]
	v_mfma_f32_16x16x32_bf16 v[94:97], v[154:157], v[212:215], v[94:97]
	v_mfma_f32_16x16x32_bf16 v[86:89], v[146:149], v[220:223], v[86:89]
	v_mfma_f32_16x16x32_bf16 v[78:81], v[154:157], v[220:223], v[78:81]
	v_mfma_f32_16x16x32_bf16 v[126:129], v[150:153], v[190:193], v[126:129]
	v_mfma_f32_16x16x32_bf16 v[122:125], v[158:161], v[190:193], v[122:125]
	v_mfma_f32_16x16x32_bf16 v[118:121], v[150:153], v[198:201], v[118:121]
	v_mfma_f32_16x16x32_bf16 v[110:113], v[158:161], v[198:201], v[110:113]
	v_mfma_f32_16x16x32_bf16 v[102:105], v[150:153], v[216:219], v[102:105]
	v_mfma_f32_16x16x32_bf16 v[94:97], v[158:161], v[216:219], v[94:97]
	v_mfma_f32_16x16x32_bf16 v[86:89], v[150:153], v[224:227], v[86:89]
	v_mfma_f32_16x16x32_bf16 v[78:81], v[158:161], v[224:227], v[78:81]
	v_mfma_f32_16x16x32_bf16 v[114:117], v[162:165], v[186:189], v[114:117]
	v_mfma_f32_16x16x32_bf16 v[106:109], v[178:181], v[186:189], v[106:109]
	v_mfma_f32_16x16x32_bf16 v[98:101], v[162:165], v[194:197], v[98:101]
	v_mfma_f32_16x16x32_bf16 v[90:93], v[178:181], v[194:197], v[90:93]
	v_mfma_f32_16x16x32_bf16 v[82:85], v[162:165], v[212:215], v[82:85]
	v_mfma_f32_16x16x32_bf16 v[74:77], v[178:181], v[212:215], v[74:77]
	v_mfma_f32_16x16x32_bf16 v[70:73], v[162:165], v[220:223], v[70:73]
	v_mfma_f32_16x16x32_bf16 v[66:69], v[178:181], v[220:223], v[66:69]
	v_mfma_f32_16x16x32_bf16 v[114:117], v[166:169], v[190:193], v[114:117]
	v_mfma_f32_16x16x32_bf16 v[106:109], v[182:185], v[190:193], v[106:109]
	v_mfma_f32_16x16x32_bf16 v[98:101], v[166:169], v[198:201], v[98:101]
	v_mfma_f32_16x16x32_bf16 v[90:93], v[182:185], v[198:201], v[90:93]
	v_mfma_f32_16x16x32_bf16 v[82:85], v[166:169], v[216:219], v[82:85]
	v_mfma_f32_16x16x32_bf16 v[74:77], v[182:185], v[216:219], v[74:77]
	v_mfma_f32_16x16x32_bf16 v[70:73], v[166:169], v[224:227], v[70:73]
	v_mfma_f32_16x16x32_bf16 v[66:69], v[182:185], v[224:227], v[66:69]
	s_setprio 0
	s_barrier
; #define PG8_STAGE(bufoff, gbase, voff) do { _Pragma("unroll") for (int _i = 0; _i < 2; ++_i) \
;         __builtin_amdgcn_global_load_lds((const unsigned*)((const char*)(gbase) + (voff)[_i]), (LAS unsigned*)(lds + (bufoff) + ldsw + _i * 8192), 16, 0, 0); } while (0)
; #define PG8_LDA(dst, b, h) do { _Pragma("unroll") for (int m = 0; m < 4; ++m) _Pragma("unroll") for (int k = 0; k < 2; ++k) dst[m][k] = *(const LAS bf16x8*)(lds + PG8_SA(b, h) + aoff + m * 2048 + k * 1024); } while (0)
; #define PG8_MMA(ai, bj, At, Bt) do { __builtin_amdgcn_s_setprio(1); _Pragma("unroll") for (int m = 0; m < 4; ++m) _Pragma("unroll") for (int n = 0; n < 2; ++n) _Pragma("unroll") for (int k = 0; k < 2; ++k) \
;         acc[ai][bj][m][n] = __builtin_amdgcn_mfma_f32_16x16x32_bf16(Bt[n][k], At[m][k], acc[ai][bj][m][n], 0, 0, 0); __builtin_amdgcn_s_setprio(0); } while (0)
; #define PG8_WAIT_V(n) asm volatile("s_waitcnt vmcnt(" #n ")" ::: "memory")
; #define PG8_WAIT_L(n) asm volatile("s_waitcnt lgkmcnt(" #n ")" ::: "memory")
; #define PG8_BAR __builtin_amdgcn_s_barrier()
; #define PG8_SCHED __builtin_amdgcn_sched_barrier(0)
; template <class Epi>
; __device__ __forceinline__ void gemm_phase(LAS unsigned char* lds, const Gemm g, const StaticOrder& S, const Epi& E, const int tid) {
;     ...
;             PG8_LDA(At, 1, 1); PG8_STAGE(PG8_SB(1, 0), b3, voffB); PG8_STAGE(PG8_SB(1, 1), b3 + bhs, voffB); PG8_STAGE(PG8_SA(1, 0), a3, voffA);
;             PG8_WAIT_V(8); PG8_WAIT_L(0); PG8_BAR; PG8_MMA(1, 0, At, B0); PG8_MMA(1, 1, At, B1); PG8_BAR; PG8_SCHED;
;     ...
;         if (ALIGN_EPI) { if (wr == 0) PG8_BAR; }
	s_add_i32 s30, s48, s37
	v_lshl_add_u64 v[172:173], v[172:173], 0, s[70:71]
	s_mov_b32 m0, s30
	ds_read_b128 v[186:189], v144 offset:49152
	global_load_lds_dwordx4 v[172:173], off
	ds_read_b128 v[190:193], v144 offset:50176
	ds_read_b128 v[194:197], v144 offset:51200
	s_add_i32 m0, s30, 0x2000
	s_add_u32 s28, s28, 0x8080
	v_lshl_add_u64 v[172:173], v[174:175], 0, s[70:71]
	s_addc_u32 s29, s29, 0
	s_add_i32 s30, s49, s37
	global_load_lds_dwordx4 v[172:173], off
	ds_read_b128 v[198:201], v144 offset:52224
	ds_read_b128 v[212:215], v144 offset:53248
	s_mov_b32 m0, s30
	v_lshl_add_u64 v[172:173], s[28:29], 0, v[0:1]
	global_load_lds_dwordx4 v[172:173], off
	ds_read_b128 v[216:219], v144 offset:54272
	ds_read_b128 v[220:223], v144 offset:55296
	s_add_i32 m0, s30, 0x2000
	v_lshl_add_u64 v[172:173], s[28:29], 0, v[134:135]
	global_load_lds_dwordx4 v[172:173], off
	ds_read_b128 v[224:227], v144 offset:56320
	s_mov_b32 m0, s40
	v_lshl_add_u64 v[172:173], v[176:177], 0, s[70:71]
	global_load_lds_dwordx4 v[172:173], off
	s_mov_b32 m0, s41
	v_lshl_add_u64 v[172:173], v[228:229], 0, s[70:71]
	global_load_lds_dwordx4 v[172:173], off
	s_waitcnt vmcnt(8)
	s_waitcnt lgkmcnt(0)
	s_barrier
	s_setprio 1
	v_mfma_f32_16x16x32_bf16 v[62:65], v[146:149], v[186:189], v[62:65]
	v_mfma_f32_16x16x32_bf16 v[58:61], v[154:157], v[186:189], v[58:61]
	v_mfma_f32_16x16x32_bf16 v[54:57], v[146:149], v[194:197], v[54:57]
	v_mfma_f32_16x16x32_bf16 v[46:49], v[154:157], v[194:197], v[46:49]
	v_mfma_f32_16x16x32_bf16 v[38:41], v[146:149], v[212:215], v[38:41]
	v_mfma_f32_16x16x32_bf16 v[30:33], v[154:157], v[212:215], v[30:33]
	v_mfma_f32_16x16x32_bf16 v[22:25], v[146:149], v[220:223], v[22:25]
	v_mfma_f32_16x16x32_bf16 v[14:17], v[154:157], v[220:223], v[14:17]
	v_mfma_f32_16x16x32_bf16 v[62:65], v[150:153], v[190:193], v[62:65]
	v_mfma_f32_16x16x32_bf16 v[58:61], v[158:161], v[190:193], v[58:61]
	v_mfma_f32_16x16x32_bf16 v[54:57], v[150:153], v[198:201], v[54:57]
	v_mfma_f32_16x16x32_bf16 v[46:49], v[158:161], v[198:201], v[46:49]
	v_mfma_f32_16x16x32_bf16 v[38:41], v[150:153], v[216:219], v[38:41]
	v_mfma_f32_16x16x32_bf16 v[30:33], v[158:161], v[216:219], v[30:33]
	v_mfma_f32_16x16x32_bf16 v[22:25], v[150:153], v[224:227], v[22:25]
	v_mfma_f32_16x16x32_bf16 v[14:17], v[158:161], v[224:227], v[14:17]
	v_mfma_f32_16x16x32_bf16 v[50:53], v[162:165], v[186:189], v[50:53]
	v_mfma_f32_16x16x32_bf16 v[42:45], v[178:181], v[186:189], v[42:45]
	v_mfma_f32_16x16x32_bf16 v[34:37], v[162:165], v[194:197], v[34:37]
	v_mfma_f32_16x16x32_bf16 v[26:29], v[178:181], v[194:197], v[26:29]
	v_mfma_f32_16x16x32_bf16 v[18:21], v[162:165], v[212:215], v[18:21]
	v_mfma_f32_16x16x32_bf16 v[10:13], v[178:181], v[212:215], v[10:13]
	v_mfma_f32_16x16x32_bf16 v[6:9], v[162:165], v[220:223], v[6:9]
	v_mfma_f32_16x16x32_bf16 v[2:5], v[178:181], v[220:223], v[2:5]
	v_mfma_f32_16x16x32_bf16 v[50:53], v[166:169], v[190:193], v[50:53]
	v_mfma_f32_16x16x32_bf16 v[42:45], v[182:185], v[190:193], v[42:45]
	v_mfma_f32_16x16x32_bf16 v[34:37], v[166:169], v[198:201], v[34:37]
	v_mfma_f32_16x16x32_bf16 v[26:29], v[182:185], v[198:201], v[26:29]
	v_mfma_f32_16x16x32_bf16 v[18:21], v[166:169], v[216:219], v[18:21]
	v_mfma_f32_16x16x32_bf16 v[10:13], v[182:185], v[216:219], v[10:13]
	v_mfma_f32_16x16x32_bf16 v[6:9], v[166:169], v[224:227], v[6:9]
	v_mfma_f32_16x16x32_bf16 v[2:5], v[182:185], v[224:227], v[2:5]
	s_setprio 0
	s_barrier
	s_add_i32 s47, s47, 2
	s_add_u32 s45, s45, 0x100
	s_addc_u32 s46, s46, 0
	s_add_u32 s26, s26, 0x100
	s_addc_u32 s27, s27, 0
	s_cmp_gt_u32 s47, 29
	s_cbranch_scc0 .LBB0_844
	s_and_b64 vcc, exec, s[10:11]
	s_cbranch_vccz .LBB0_847
	s_barrier

; #define PG8_STAGE(bufoff, gbase, voff) do { _Pragma("unroll") for (int _i = 0; _i < 2; ++_i) \
;         __builtin_amdgcn_global_load_lds((const unsigned*)((const char*)(gbase) + (voff)[_i]), (LAS unsigned*)(lds + (bufoff) + ldsw + _i * 8192), 16, 0, 0); } while (0)
; #define PG8_LDA(dst, b, h) do { _Pragma("unroll") for (int m = 0; m < 4; ++m) _Pragma("unroll") for (int k = 0; k < 2; ++k) dst[m][k] = *(const LAS bf16x8*)(lds + PG8_SA(b, h) + aoff + m * 2048 + k * 1024); } while (0)
; #define PG8_LDB(dst, b, h) do { _Pragma("unroll") for (int n = 0; n < 2; ++n) _Pragma("unroll") for (int k = 0; k < 2; ++k) dst[n][k] = *(const LAS bf16x8*)(lds + PG8_SB(b, h) + boff + n * 2048 + k * 1024); } while (0)
; #define PG8_MMA(ai, bj, At, Bt) do { __builtin_amdgcn_s_setprio(1); _Pragma("unroll") for (int m = 0; m < 4; ++m) _Pragma("unroll") for (int n = 0; n < 2; ++n) _Pragma("unroll") for (int k = 0; k < 2; ++k) \
;         acc[ai][bj][m][n] = __builtin_amdgcn_mfma_f32_16x16x32_bf16(Bt[n][k], At[m][k], acc[ai][bj][m][n], 0, 0, 0); __builtin_amdgcn_s_setprio(0); } while (0)
; #define PG8_WAIT_V(n) asm volatile("s_waitcnt vmcnt(" #n ")" ::: "memory")
; #define PG8_WAIT_L(n) asm volatile("s_waitcnt lgkmcnt(" #n ")" ::: "memory")
; #define PG8_BAR __builtin_amdgcn_s_barrier()
; #define PG8_SCHED __builtin_amdgcn_sched_barrier(0)
; template <class Epi>
; __device__ __forceinline__ void gemm_phase(LAS unsigned char* lds, const Gemm g, const StaticOrder& S, const Epi& E, const int tid) {
;     ...
;             PG8_LDB(B0, 0, 0); PG8_LDB(B1, 0, 1); PG8_SCHED; PG8_LDA(At, 0, 0); PG8_STAGE(PG8_SA(1, 1), a1 + hstep, voffA);
;             PG8_WAIT_V(8); PG8_WAIT_L(0); PG8_BAR; PG8_MMA(0, 0, At, B0); PG8_MMA(0, 1, At, B1); PG8_BAR; PG8_SCHED;
;             PG8_LDA(At, 0, 1); PG8_STAGE(PG8_SB(0, 0), b2, voffB); PG8_STAGE(PG8_SB(0, 1), b2 + bhs, voffB); PG8_STAGE(PG8_SA(0, 0), a2, voffA);
;             PG8_WAIT_V(8); PG8_WAIT_L(0); PG8_BAR; PG8_MMA(1, 0, At, B0); PG8_MMA(1, 1, At, B1); PG8_BAR; PG8_SCHED;
;     ...
;         for (int a = 0; a < 2; ++a)
; #pragma unroll
;             for (int b = 0; b < 2; ++b)
; #pragma unroll
;                 for (int m = 0; m < 4; ++m)
; #pragma unroll
;                     for (int n = 0; n < 2; ++n) acc[a][b][m][n] = (f32x4){0.f, 0.f, 0.f, 0.f};
.LBB0_861:
	s_add_u32 s30, s28, 0xfff80080
	s_addc_u32 s31, s29, -1
	s_add_i32 s51, 0, 0x10000
	s_cmp_eq_u32 s50, 28
	s_cselect_b32 s35, s17, s31
	s_cselect_b32 s34, s46, s30
	v_add_u32_e32 v145, s51, v142
	s_cselect_b32 s31, s15, s49
	s_cselect_b32 s30, s47, s48
	s_add_i32 s54, 0, 0x14000
	ds_read_b128 v[146:149], v145
	ds_read_b128 v[150:153], v145 offset:1024
	ds_read_b128 v[154:157], v145 offset:2048
	ds_read_b128 v[158:161], v145 offset:3072
	v_add_u32_e32 v145, s54, v142
	ds_read_b128 v[162:165], v145
	ds_read_b128 v[166:169], v145 offset:1024
	ds_read_b128 v[178:181], v145 offset:2048
	ds_read_b128 v[182:185], v145 offset:3072
	v_lshl_add_u64 v[172:173], s[28:29], 0, v[138:139]
	s_add_i32 m0, s25, 0xc000
	ds_read_b128 v[186:189], v144
	global_load_lds_dwordx4 v[172:173], off
	ds_read_b128 v[190:193], v144 offset:1024
	ds_read_b128 v[194:197], v144 offset:2048
	s_add_i32 m0, s25, 0xe000
	v_lshl_add_u64 v[172:173], s[28:29], 0, v[136:137]
	global_load_lds_dwordx4 v[172:173], off
	ds_read_b128 v[198:201], v144 offset:3072
	ds_read_b128 v[212:215], v144 offset:4096
	ds_read_b128 v[216:219], v144 offset:5120
	ds_read_b128 v[220:223], v144 offset:6144
	ds_read_b128 v[224:227], v144 offset:7168
	s_waitcnt vmcnt(8)
	s_waitcnt lgkmcnt(0)
	s_barrier
	s_setprio 1
	v_mfma_f32_16x16x32_bf16 v[126:129], v[146:149], v[186:189], v[126:129]
	v_mfma_f32_16x16x32_bf16 v[122:125], v[154:157], v[186:189], v[122:125]
	v_mfma_f32_16x16x32_bf16 v[118:121], v[146:149], v[194:197], v[118:121]
	v_mfma_f32_16x16x32_bf16 v[110:113], v[154:157], v[194:197], v[110:113]
	v_mfma_f32_16x16x32_bf16 v[102:105], v[146:149], v[212:215], v[102:105]
	v_mfma_f32_16x16x32_bf16 v[94:97], v[154:157], v[212:215], v[94:97]
	v_mfma_f32_16x16x32_bf16 v[86:89], v[146:149], v[220:223], v[86:89]
	v_mfma_f32_16x16x32_bf16 v[78:81], v[154:157], v[220:223], v[78:81]
	v_mfma_f32_16x16x32_bf16 v[126:129], v[150:153], v[190:193], v[126:129]
	v_mfma_f32_16x16x32_bf16 v[122:125], v[158:161], v[190:193], v[122:125]
	v_mfma_f32_16x16x32_bf16 v[118:121], v[150:153], v[198:201], v[118:121]
	v_mfma_f32_16x16x32_bf16 v[110:113], v[158:161], v[198:201], v[110:113]
	v_mfma_f32_16x16x32_bf16 v[102:105], v[150:153], v[216:219], v[102:105]
	v_mfma_f32_16x16x32_bf16 v[94:97], v[158:161], v[216:219], v[94:97]
	v_mfma_f32_16x16x32_bf16 v[86:89], v[150:153], v[224:227], v[86:89]
	v_mfma_f32_16x16x32_bf16 v[78:81], v[158:161], v[224:227], v[78:81]
	v_mfma_f32_16x16x32_bf16 v[114:117], v[162:165], v[186:189], v[114:117]
	v_mfma_f32_16x16x32_bf16 v[106:109], v[178:181], v[186:189], v[106:109]
	v_mfma_f32_16x16x32_bf16 v[98:101], v[162:165], v[194:197], v[98:101]
	v_mfma_f32_16x16x32_bf16 v[90:93], v[178:181], v[194:197], v[90:93]
	v_mfma_f32_16x16x32_bf16 v[82:85], v[162:165], v[212:215], v[82:85]
	v_mfma_f32_16x16x32_bf16 v[74:77], v[178:181], v[212:215], v[74:77]
	v_mfma_f32_16x16x32_bf16 v[70:73], v[162:165], v[220:223], v[70:73]
	v_mfma_f32_16x16x32_bf16 v[66:69], v[178:181], v[220:223], v[66:69]
	v_mfma_f32_16x16x32_bf16 v[114:117], v[166:169], v[190:193], v[114:117]
	v_mfma_f32_16x16x32_bf16 v[106:109], v[182:185], v[190:193], v[106:109]
	v_mfma_f32_16x16x32_bf16 v[98:101], v[166:169], v[198:201], v[98:101]
	v_mfma_f32_16x16x32_bf16 v[90:93], v[182:185], v[198:201], v[90:93]
	v_mfma_f32_16x16x32_bf16 v[82:85], v[166:169], v[216:219], v[82:85]
	v_mfma_f32_16x16x32_bf16 v[74:77], v[182:185], v[216:219], v[74:77]
	v_mfma_f32_16x16x32_bf16 v[70:73], v[166:169], v[224:227], v[70:73]
	v_mfma_f32_16x16x32_bf16 v[66:69], v[182:185], v[224:227], v[66:69]
	s_setprio 0
	s_barrier
	s_add_i32 s51, s51, s40
	v_lshl_add_u64 v[172:173], s[30:31], 0, v[0:1]
	s_mov_b32 m0, s51
	ds_read_b128 v[186:189], v144 offset:16384
	global_load_lds_dwordx4 v[172:173], off
	ds_read_b128 v[190:193], v144 offset:17408
	ds_read_b128 v[194:197], v144 offset:18432
	s_add_i32 m0, s51, 0x2000
	s_add_u32 s52, s30, 0x8000
	v_lshl_add_u64 v[174:175], s[30:31], 0, v[134:135]
	s_addc_u32 s53, s31, 0
	s_add_i32 s51, s54, s40
	global_load_lds_dwordx4 v[174:175], off
	ds_read_b128 v[198:201], v144 offset:19456
	ds_read_b128 v[212:215], v144 offset:20480
	v_lshl_add_u64 v[176:177], s[52:53], 0, v[0:1]
	s_mov_b32 m0, s51
	v_lshl_add_u64 v[228:229], s[34:35], 0, v[132:133]
	global_load_lds_dwordx4 v[176:177], off
	ds_read_b128 v[216:219], v144 offset:21504
	ds_read_b128 v[220:223], v144 offset:22528
	s_add_i32 m0, s51, 0x2000
	v_lshl_add_u64 v[176:177], s[52:53], 0, v[134:135]
	global_load_lds_dwordx4 v[176:177], off
	ds_read_b128 v[224:227], v144 offset:23552
	s_mov_b32 m0, s25
	v_lshl_add_u64 v[176:177], s[34:35], 0, v[130:131]
	global_load_lds_dwordx4 v[176:177], off
	s_mov_b32 m0, s27
	s_nop 0
	global_load_lds_dwordx4 v[228:229], off
	s_waitcnt vmcnt(8)
	s_waitcnt lgkmcnt(0)
	s_barrier
; #define PG8_STAGE(bufoff, gbase, voff) do { _Pragma("unroll") for (int _i = 0; _i < 2; ++_i) \
;         __builtin_amdgcn_global_load_lds((const unsigned*)((const char*)(gbase) + (voff)[_i]), (LAS unsigned*)(lds + (bufoff) + ldsw + _i * 8192), 16, 0, 0); } while (0)
; #define PG8_LDA(dst, b, h) do { _Pragma("unroll") for (int m = 0; m < 4; ++m) _Pragma("unroll") for (int k = 0; k < 2; ++k) dst[m][k] = *(const LAS bf16x8*)(lds + PG8_SA(b, h) + aoff + m * 2048 + k * 1024); } while (0)
; #define PG8_LDB(dst, b, h) do { _Pragma("unroll") for (int n = 0; n < 2; ++n) _Pragma("unroll") for (int k = 0; k < 2; ++k) dst[n][k] = *(const LAS bf16x8*)(lds + PG8_SB(b, h) + boff + n * 2048 + k * 1024); } while (0)
; #define PG8_MMA(ai, bj, At, Bt) do { __builtin_amdgcn_s_setprio(1); _Pragma("unroll") for (int m = 0; m < 4; ++m) _Pragma("unroll") for (int n = 0; n < 2; ++n) _Pragma("unroll") for (int k = 0; k < 2; ++k) \
;         acc[ai][bj][m][n] = __builtin_amdgcn_mfma_f32_16x16x32_bf16(Bt[n][k], At[m][k], acc[ai][bj][m][n], 0, 0, 0); __builtin_amdgcn_s_setprio(0); } while (0)
; #define PG8_WAIT_V(n) asm volatile("s_waitcnt vmcnt(" #n ")" ::: "memory")
; #define PG8_WAIT_L(n) asm volatile("s_waitcnt lgkmcnt(" #n ")" ::: "memory")
; #define PG8_BAR __builtin_amdgcn_s_barrier()
; #define PG8_SCHED __builtin_amdgcn_sched_barrier(0)
; template <class Epi>
; __device__ __forceinline__ void gemm_phase(LAS unsigned char* lds, const Gemm g, const StaticOrder& S, const Epi& E, const int tid) {
;     ...
;             PG8_WAIT_V(8); PG8_WAIT_L(0); PG8_BAR; PG8_MMA(1, 0, At, B0); PG8_MMA(1, 1, At, B1); PG8_BAR; PG8_SCHED;
;             PG8_LDB(B0, 1, 0); PG8_LDB(B1, 1, 1); PG8_SCHED; PG8_LDA(At, 1, 0); PG8_STAGE(PG8_SA(0, 1), a2 + hstep, voffA);
;             PG8_WAIT_V(8); PG8_WAIT_L(0); PG8_BAR; PG8_MMA(0, 0, At, B0); PG8_MMA(0, 1, At, B1); PG8_BAR; PG8_SCHED;
	s_setprio 1
	v_mfma_f32_16x16x32_bf16 v[62:65], v[146:149], v[186:189], v[62:65]
	v_mfma_f32_16x16x32_bf16 v[58:61], v[154:157], v[186:189], v[58:61]
	v_mfma_f32_16x16x32_bf16 v[54:57], v[146:149], v[194:197], v[54:57]
	v_mfma_f32_16x16x32_bf16 v[46:49], v[154:157], v[194:197], v[46:49]
	v_mfma_f32_16x16x32_bf16 v[38:41], v[146:149], v[212:215], v[38:41]
	v_mfma_f32_16x16x32_bf16 v[30:33], v[154:157], v[212:215], v[30:33]
	v_mfma_f32_16x16x32_bf16 v[22:25], v[146:149], v[220:223], v[22:25]
	v_mfma_f32_16x16x32_bf16 v[14:17], v[154:157], v[220:223], v[14:17]
	v_mfma_f32_16x16x32_bf16 v[62:65], v[150:153], v[190:193], v[62:65]
	v_mfma_f32_16x16x32_bf16 v[58:61], v[158:161], v[190:193], v[58:61]
	v_mfma_f32_16x16x32_bf16 v[54:57], v[150:153], v[198:201], v[54:57]
	v_mfma_f32_16x16x32_bf16 v[46:49], v[158:161], v[198:201], v[46:49]
	v_mfma_f32_16x16x32_bf16 v[38:41], v[150:153], v[216:219], v[38:41]
	v_mfma_f32_16x16x32_bf16 v[30:33], v[158:161], v[216:219], v[30:33]
	v_mfma_f32_16x16x32_bf16 v[22:25], v[150:153], v[224:227], v[22:25]
	v_mfma_f32_16x16x32_bf16 v[14:17], v[158:161], v[224:227], v[14:17]
	v_mfma_f32_16x16x32_bf16 v[50:53], v[162:165], v[186:189], v[50:53]
	v_mfma_f32_16x16x32_bf16 v[42:45], v[178:181], v[186:189], v[42:45]
	v_mfma_f32_16x16x32_bf16 v[34:37], v[162:165], v[194:197], v[34:37]
	v_mfma_f32_16x16x32_bf16 v[26:29], v[178:181], v[194:197], v[26:29]
	v_mfma_f32_16x16x32_bf16 v[18:21], v[162:165], v[212:215], v[18:21]
	v_mfma_f32_16x16x32_bf16 v[10:13], v[178:181], v[212:215], v[10:13]
	v_mfma_f32_16x16x32_bf16 v[6:9], v[162:165], v[220:223], v[6:9]
	v_mfma_f32_16x16x32_bf16 v[2:5], v[178:181], v[220:223], v[2:5]
	v_mfma_f32_16x16x32_bf16 v[50:53], v[166:169], v[190:193], v[50:53]
	v_mfma_f32_16x16x32_bf16 v[42:45], v[182:185], v[190:193], v[42:45]
	v_mfma_f32_16x16x32_bf16 v[34:37], v[166:169], v[198:201], v[34:37]
	v_mfma_f32_16x16x32_bf16 v[26:29], v[182:185], v[198:201], v[26:29]
	v_mfma_f32_16x16x32_bf16 v[18:21], v[166:169], v[216:219], v[18:21]
	v_mfma_f32_16x16x32_bf16 v[10:13], v[182:185], v[216:219], v[10:13]
	v_mfma_f32_16x16x32_bf16 v[6:9], v[166:169], v[224:227], v[6:9]
	v_mfma_f32_16x16x32_bf16 v[2:5], v[182:185], v[224:227], v[2:5]
	s_setprio 0
	s_barrier
	s_add_i32 s51, 0, 0x18000
	v_add_u32_e32 v145, s51, v142
	s_add_i32 s52, 0, 0x1c000
	ds_read_b128 v[146:149], v145
	ds_read_b128 v[150:153], v145 offset:1024
	ds_read_b128 v[154:157], v145 offset:2048
	ds_read_b128 v[158:161], v145 offset:3072
	v_add_u32_e32 v145, s52, v142
	ds_read_b128 v[162:165], v145
	ds_read_b128 v[166:169], v145 offset:1024
	ds_read_b128 v[178:181], v145 offset:2048
	ds_read_b128 v[182:185], v145 offset:3072
	s_add_u32 s34, s34, 0x80000
	s_addc_u32 s35, s35, 0
	s_mov_b32 m0, s41
	v_lshl_add_u64 v[230:231], s[34:35], 0, v[130:131]
	ds_read_b128 v[186:189], v144 offset:32768
	global_load_lds_dwordx4 v[230:231], off
	ds_read_b128 v[190:193], v144 offset:33792
	ds_read_b128 v[194:197], v144 offset:34816
	s_mov_b32 m0, s42
	v_lshl_add_u64 v[230:231], s[34:35], 0, v[132:133]
	global_load_lds_dwordx4 v[230:231], off
	ds_read_b128 v[198:201], v144 offset:35840
	ds_read_b128 v[212:215], v144 offset:36864
	ds_read_b128 v[216:219], v144 offset:37888
	ds_read_b128 v[220:223], v144 offset:38912
	ds_read_b128 v[224:227], v144 offset:39936
	s_waitcnt vmcnt(8)
	s_waitcnt lgkmcnt(0)
	s_barrier
	s_setprio 1
	v_mfma_f32_16x16x32_bf16 v[126:129], v[146:149], v[186:189], v[126:129]
	v_mfma_f32_16x16x32_bf16 v[122:125], v[154:157], v[186:189], v[122:125]
	v_mfma_f32_16x16x32_bf16 v[118:121], v[146:149], v[194:197], v[118:121]
	v_mfma_f32_16x16x32_bf16 v[110:113], v[154:157], v[194:197], v[110:113]
	v_mfma_f32_16x16x32_bf16 v[102:105], v[146:149], v[212:215], v[102:105]
	v_mfma_f32_16x16x32_bf16 v[94:97], v[154:157], v[212:215], v[94:97]
	v_mfma_f32_16x16x32_bf16 v[86:89], v[146:149], v[220:223], v[86:89]
	v_mfma_f32_16x16x32_bf16 v[78:81], v[154:157], v[220:223], v[78:81]
	v_mfma_f32_16x16x32_bf16 v[126:129], v[150:153], v[190:193], v[126:129]
	v_mfma_f32_16x16x32_bf16 v[122:125], v[158:161], v[190:193], v[122:125]
	v_mfma_f32_16x16x32_bf16 v[118:121], v[150:153], v[198:201], v[118:121]
	v_mfma_f32_16x16x32_bf16 v[110:113], v[158:161], v[198:201], v[110:113]
	v_mfma_f32_16x16x32_bf16 v[102:105], v[150:153], v[216:219], v[102:105]
	v_mfma_f32_16x16x32_bf16 v[94:97], v[158:161], v[216:219], v[94:97]
	v_mfma_f32_16x16x32_bf16 v[86:89], v[150:153], v[224:227], v[86:89]
	v_mfma_f32_16x16x32_bf16 v[78:81], v[158:161], v[224:227], v[78:81]
	v_mfma_f32_16x16x32_bf16 v[114:117], v[162:165], v[186:189], v[114:117]
	v_mfma_f32_16x16x32_bf16 v[106:109], v[178:181], v[186:189], v[106:109]
	v_mfma_f32_16x16x32_bf16 v[98:101], v[162:165], v[194:197], v[98:101]
	v_mfma_f32_16x16x32_bf16 v[90:93], v[178:181], v[194:197], v[90:93]
	v_mfma_f32_16x16x32_bf16 v[82:85], v[162:165], v[212:215], v[82:85]
	v_mfma_f32_16x16x32_bf16 v[74:77], v[178:181], v[212:215], v[74:77]
	v_mfma_f32_16x16x32_bf16 v[70:73], v[162:165], v[220:223], v[70:73]
	v_mfma_f32_16x16x32_bf16 v[66:69], v[178:181], v[220:223], v[66:69]
	v_mfma_f32_16x16x32_bf16 v[114:117], v[166:169], v[190:193], v[114:117]
	v_mfma_f32_16x16x32_bf16 v[106:109], v[182:185], v[190:193], v[106:109]
	v_mfma_f32_16x16x32_bf16 v[98:101], v[166:169], v[198:201], v[98:101]
	v_mfma_f32_16x16x32_bf16 v[90:93], v[182:185], v[198:201], v[90:93]
	v_mfma_f32_16x16x32_bf16 v[82:85], v[166:169], v[216:219], v[82:85]
	v_mfma_f32_16x16x32_bf16 v[74:77], v[182:185], v[216:219], v[74:77]
	v_mfma_f32_16x16x32_bf16 v[70:73], v[166:169], v[224:227], v[70:73]
	v_mfma_f32_16x16x32_bf16 v[66:69], v[182:185], v[224:227], v[66:69]
	s_setprio 0
	s_barrier
; #define PG8_STAGE(bufoff, gbase, voff) do { _Pragma("unroll") for (int _i = 0; _i < 2; ++_i) \
;         __builtin_amdgcn_global_load_lds((const unsigned*)((const char*)(gbase) + (voff)[_i]), (LAS unsigned*)(lds + (bufoff) + ldsw + _i * 8192), 16, 0, 0); } while (0)
; #define PG8_LDA(dst, b, h) do { _Pragma("unroll") for (int m = 0; m < 4; ++m) _Pragma("unroll") for (int k = 0; k < 2; ++k) dst[m][k] = *(const LAS bf16x8*)(lds + PG8_SA(b, h) + aoff + m * 2048 + k * 1024); } while (0)
; #define PG8_MMA(ai, bj, At, Bt) do { __builtin_amdgcn_s_setprio(1); _Pragma("unroll") for (int m = 0; m < 4; ++m) _Pragma("unroll") for (int n = 0; n < 2; ++n) _Pragma("unroll") for (int k = 0; k < 2; ++k) \
;         acc[ai][bj][m][n] = __builtin_amdgcn_mfma_f32_16x16x32_bf16(Bt[n][k], At[m][k], acc[ai][bj][m][n], 0, 0, 0); __builtin_amdgcn_s_setprio(0); } while (0)
; #define PG8_WAIT_V(n) asm volatile("s_waitcnt vmcnt(" #n ")" ::: "memory")
; #define PG8_WAIT_L(n) asm volatile("s_waitcnt lgkmcnt(" #n ")" ::: "memory")
; #define PG8_BAR __builtin_amdgcn_s_barrier()
; #define PG8_SCHED __builtin_amdgcn_sched_barrier(0)
; template <class Epi>
; __device__ __forceinline__ void gemm_phase(LAS unsigned char* lds, const Gemm g, const StaticOrder& S, const Epi& E, const int tid) {
;     ...
;             PG8_LDA(At, 1, 1); PG8_STAGE(PG8_SB(1, 0), b3, voffB); PG8_STAGE(PG8_SB(1, 1), b3 + bhs, voffB); PG8_STAGE(PG8_SA(1, 0), a3, voffA);
;             PG8_WAIT_V(8); PG8_WAIT_L(0); PG8_BAR; PG8_MMA(1, 0, At, B0); PG8_MMA(1, 1, At, B1); PG8_BAR; PG8_SCHED;
;     ...
;         if (ALIGN_EPI) { if (wr == 0) PG8_BAR; }
	s_add_i32 s34, s51, s40
	v_lshl_add_u64 v[172:173], v[172:173], 0, s[70:71]
	s_mov_b32 m0, s34
	ds_read_b128 v[186:189], v144 offset:49152
	global_load_lds_dwordx4 v[172:173], off
	ds_read_b128 v[190:193], v144 offset:50176
	ds_read_b128 v[194:197], v144 offset:51200
	s_add_i32 m0, s34, 0x2000
	s_add_u32 s30, s30, 0x8080
	v_lshl_add_u64 v[172:173], v[174:175], 0, s[70:71]
	s_addc_u32 s31, s31, 0
	s_add_i32 s34, s52, s40
	global_load_lds_dwordx4 v[172:173], off
	ds_read_b128 v[198:201], v144 offset:52224
	ds_read_b128 v[212:215], v144 offset:53248
	s_mov_b32 m0, s34
	v_lshl_add_u64 v[172:173], s[30:31], 0, v[0:1]
	global_load_lds_dwordx4 v[172:173], off
	ds_read_b128 v[216:219], v144 offset:54272
	ds_read_b128 v[220:223], v144 offset:55296
	s_add_i32 m0, s34, 0x2000
	v_lshl_add_u64 v[172:173], s[30:31], 0, v[134:135]
	global_load_lds_dwordx4 v[172:173], off
	ds_read_b128 v[224:227], v144 offset:56320
	s_mov_b32 m0, s43
	v_lshl_add_u64 v[172:173], v[176:177], 0, s[70:71]
	global_load_lds_dwordx4 v[172:173], off
	s_mov_b32 m0, s44
	v_lshl_add_u64 v[172:173], v[228:229], 0, s[70:71]
	global_load_lds_dwordx4 v[172:173], off
	s_waitcnt vmcnt(8)
	s_waitcnt lgkmcnt(0)
	s_barrier
	s_setprio 1
	v_mfma_f32_16x16x32_bf16 v[62:65], v[146:149], v[186:189], v[62:65]
	v_mfma_f32_16x16x32_bf16 v[58:61], v[154:157], v[186:189], v[58:61]
	v_mfma_f32_16x16x32_bf16 v[54:57], v[146:149], v[194:197], v[54:57]
	v_mfma_f32_16x16x32_bf16 v[46:49], v[154:157], v[194:197], v[46:49]
	v_mfma_f32_16x16x32_bf16 v[38:41], v[146:149], v[212:215], v[38:41]
	v_mfma_f32_16x16x32_bf16 v[30:33], v[154:157], v[212:215], v[30:33]
	v_mfma_f32_16x16x32_bf16 v[22:25], v[146:149], v[220:223], v[22:25]
	v_mfma_f32_16x16x32_bf16 v[14:17], v[154:157], v[220:223], v[14:17]
	v_mfma_f32_16x16x32_bf16 v[62:65], v[150:153], v[190:193], v[62:65]
	v_mfma_f32_16x16x32_bf16 v[58:61], v[158:161], v[190:193], v[58:61]
	v_mfma_f32_16x16x32_bf16 v[54:57], v[150:153], v[198:201], v[54:57]
	v_mfma_f32_16x16x32_bf16 v[46:49], v[158:161], v[198:201], v[46:49]
	v_mfma_f32_16x16x32_bf16 v[38:41], v[150:153], v[216:219], v[38:41]
	v_mfma_f32_16x16x32_bf16 v[30:33], v[158:161], v[216:219], v[30:33]
	v_mfma_f32_16x16x32_bf16 v[22:25], v[150:153], v[224:227], v[22:25]
	v_mfma_f32_16x16x32_bf16 v[14:17], v[158:161], v[224:227], v[14:17]
	v_mfma_f32_16x16x32_bf16 v[50:53], v[162:165], v[186:189], v[50:53]
	v_mfma_f32_16x16x32_bf16 v[42:45], v[178:181], v[186:189], v[42:45]
	v_mfma_f32_16x16x32_bf16 v[34:37], v[162:165], v[194:197], v[34:37]
	v_mfma_f32_16x16x32_bf16 v[26:29], v[178:181], v[194:197], v[26:29]
	v_mfma_f32_16x16x32_bf16 v[18:21], v[162:165], v[212:215], v[18:21]
	v_mfma_f32_16x16x32_bf16 v[10:13], v[178:181], v[212:215], v[10:13]
	v_mfma_f32_16x16x32_bf16 v[6:9], v[162:165], v[220:223], v[6:9]
	v_mfma_f32_16x16x32_bf16 v[2:5], v[178:181], v[220:223], v[2:5]
	v_mfma_f32_16x16x32_bf16 v[50:53], v[166:169], v[190:193], v[50:53]
	v_mfma_f32_16x16x32_bf16 v[42:45], v[182:185], v[190:193], v[42:45]
	v_mfma_f32_16x16x32_bf16 v[34:37], v[166:169], v[198:201], v[34:37]
	v_mfma_f32_16x16x32_bf16 v[26:29], v[182:185], v[198:201], v[26:29]
	v_mfma_f32_16x16x32_bf16 v[18:21], v[166:169], v[216:219], v[18:21]
	v_mfma_f32_16x16x32_bf16 v[10:13], v[182:185], v[216:219], v[10:13]
	v_mfma_f32_16x16x32_bf16 v[6:9], v[166:169], v[224:227], v[6:9]
	v_mfma_f32_16x16x32_bf16 v[2:5], v[182:185], v[224:227], v[2:5]
	s_setprio 0
	s_barrier
	s_add_i32 s50, s50, 2
	s_add_u32 s48, s48, 0x100
	s_addc_u32 s49, s49, 0
	s_add_u32 s28, s28, 0x100
	s_addc_u32 s29, s29, 0
	s_cmp_gt_u32 s50, 29
	s_cbranch_scc0 .LBB0_861
	s_and_b64 vcc, exec, s[12:13]
	s_cbranch_vccz .LBB0_864
	s_barrier
